# v61 + HGRN pass C hg_prep: token-group 2/3 z,q loads (32 per sub-chunk) hoisted to the first load cluster into unused VGPRs, vmcnt waits recomputed
# baseline (speedup 1.0000x reference)
.LBB0_372:
	s_andn2_b64 vcc, exec, s[2:3]
	s_cbranch_vccnz .LBB0_339
	s_mul_i32 s3, s4, 9
	s_ashr_i32 s2, s3, 1
	s_add_i32 s3, s3, 9
	s_ashr_i32 s3, s3, 1
	v_ashrrev_i32_e32 v0, 6, v205
	s_sub_i32 s3, s3, s2
	v_cmp_gt_i32_e32 vcc, s3, v0
	s_and_saveexec_b64 s[38:39], vcc
	s_cbranch_execz .LBB0_338
	v_add_u32_e32 v0, s2, v0
	s_mov_b32 s2, 0x38e38e39
	v_mul_hi_i32 v2, v0, s2
	v_lshrrev_b32_e32 v3, 31, v2
	v_ashrrev_i32_e32 v2, 3, v2
	v_add_u32_e32 v2, v2, v3
	v_mul_lo_u32 v3, v2, 36
	v_sub_u32_e32 v96, v0, v3
	v_cmp_gt_i32_e64 s[40:41], 4, v96
	s_and_b64 s[2:3], s[18:19], s[40:41]
	v_mov_b32_e32 v1, v236
	s_xor_b64 s[2:3], s[2:3], -1
	s_and_b64 exec, exec, s[2:3]
	s_cbranch_execz .LBB0_338
	v_lshrrev_b32_e32 v0, 6, v1
	s_movk_i32 s2, 0x4d00
	v_mul_lo_u32 v0, v0, s2
	v_add_u32_e32 v92, 16, v0
	v_lshlrev_b32_e32 v0, 6, v2
	v_and_b32_e32 v94, 63, v1
	v_and_b32_e32 v0, 0xc0, v0
	v_or_b32_e32 v3, v94, v0
	v_readlane_b32 s0, v255, 20
	v_lshlrev_b32_e32 v160, 2, v3
	v_readlane_b32 s1, v255, 21
	s_nop 4
	global_load_dword v3, v160, s[0:1]
	global_load_dword v6, v160, s[0:1] offset:2048
	v_lshl_add_u64 v[4:5], s[0:1], 0, v[160:161]
	v_add_co_u32_e32 v4, vcc, 0x1000, v4
	s_mov_b32 s0, 0xf149f2ca
	s_nop 0
	v_addc_co_u32_e32 v5, vcc, 0, v5, vcc
	global_load_dword v8, v[4:5], off
	s_nop 0
	global_load_dword v4, v[4:5], off offset:2048
	v_lshlrev_b32_e32 v148, 1, v2
	v_ashrrev_i32_e32 v97, 31, v96
	v_mov_b32_e32 v99, v161
	v_mov_b32_e32 v101, v161
	v_readlane_b32 s44, v254, 28
	v_readlane_b32 s45, v254, 29
	v_mov_b32_e32 v16, v94
	s_waitcnt vmcnt(2)
	v_max3_f32 v7, v3, s0, v6
	v_readlane_b32 s0, v255, 1
	v_readlane_b32 s1, v255, 2
	s_waitcnt vmcnt(0)
	v_max3_f32 v5, v7, v8, v4
	v_sub_f32_e32 v6, v6, v5
	v_mul_f32_e32 v6, 0x3fb8aa3b, v6
	v_sub_f32_e32 v3, v3, v5
	v_exp_f32_e32 v6, v6
	v_sub_f32_e32 v7, v8, v5
	v_mul_f32_e32 v3, 0x3fb8aa3b, v3
	v_mul_f32_e32 v7, 0x3fb8aa3b, v7
	v_exp_f32_e32 v3, v3
	v_exp_f32_e32 v7, v7
	v_sub_f32_e32 v4, v4, v5
	v_mul_f32_e32 v4, 0x3fb8aa3b, v4
	v_exp_f32_e32 v4, v4
	v_add_f32_e32 v5, 0, v6
	v_cndmask_b32_e64 v5, v5, 0, s[0:1]
	v_readlane_b32 s0, v255, 3
	v_add_f32_e32 v8, v7, v5
	v_readlane_b32 s1, v255, 4
	v_add_f32_e32 v3, 0, v3
	v_add_f32_e32 v3, v6, v3
	v_cndmask_b32_e64 v5, v8, v5, s[0:1]
	v_readlane_b32 s0, v255, 5
	v_add_f32_e32 v8, v4, v5
	v_readlane_b32 s1, v255, 6
	v_add_f32_e32 v3, v7, v3
	v_add_f32_e32 v3, v4, v3
	v_cndmask_b32_e64 v5, v8, v5, s[0:1]
	v_div_scale_f32 v4, s[2:3], v3, v3, v5
	v_rcp_f32_e32 v6, v4
	v_readlane_b32 s0, v255, 22
	v_readlane_b32 s1, v255, 23
	v_fma_f32 v7, -v4, v6, 1.0
	v_fmac_f32_e32 v6, v7, v6
	v_div_scale_f32 v7, vcc, v5, v3, v5
	v_mul_f32_e32 v8, v7, v6
	v_fma_f32 v9, -v4, v8, v7
	v_fmac_f32_e32 v8, v9, v6
	v_fma_f32 v4, -v4, v8, v7
	v_div_fmas_f32 v4, v4, v6, v8
	v_div_fixup_f32 v149, v4, v3, v5
	v_ashrrev_i32_e32 v6, 2, v2
	v_mad_i64_i32 v[2:3], s[2:3], v148, 36, v[96:97]
	v_lshlrev_b64 v[2:3], 13, v[2:3]
	v_lshlrev_b32_e32 v4, 7, v1
	v_lshl_add_u64 v[2:3], s[0:1], 0, v[2:3]
	v_and_b32_e32 v98, 0xf80, v4
	v_lshrrev_b32_e32 v1, 2, v1
	v_lshl_add_u64 v[2:3], v[2:3], 0, v[98:99]
	v_and_b32_e32 v100, 8, v1
	v_lshl_add_u64 v[2:3], v[2:3], 0, v[100:101]
	global_load_dwordx2 v[42:43], v[2:3], off
	global_load_dwordx2 v[36:37], v[2:3], off offset:16
	global_load_dwordx2 v[34:35], v[2:3], off offset:32
	global_load_dwordx2 v[4:5], v[2:3], off offset:48
	s_movk_i32 s0, 0x1000
	v_mov_b32_e32 v1, 0xffffff00
	v_lshl_add_u32 v1, v6, 11, v1
	s_mov_b64 s[2:3], s[44:45]
	v_sub_f32_e32 v80, 1.0, v149
	s_waitcnt vmcnt(1)
	v_lshlrev_b32_e32 v40, 16, v35
	s_waitcnt vmcnt(0)
	v_lshlrev_b32_e32 v44, 16, v4
	v_and_b32_e32 v45, 0xffff0000, v4
	v_add_co_u32_e32 v4, vcc, s0, v2
	v_lshlrev_b32_e32 v46, 16, v5
	v_and_b32_e32 v47, 0xffff0000, v5
	v_addc_co_u32_e32 v5, vcc, 0, v3, vcc
	global_load_dwordx2 v[52:53], v[4:5], off
	global_load_dwordx2 v[50:51], v[4:5], off offset:16
	global_load_dwordx2 v[48:49], v[4:5], off offset:32
	global_load_dwordx2 v[38:39], v[4:5], off offset:48
	global_load_dwordx2 v[60:61], v[2:3], off offset:64
	global_load_dwordx2 v[58:59], v[2:3], off offset:80
	global_load_dwordx2 v[56:57], v[2:3], off offset:96
	global_load_dwordx2 v[54:55], v[2:3], off offset:112
	global_load_dwordx2 v[26:27], v[4:5], off offset:64
	global_load_dwordx2 v[28:29], v[4:5], off offset:80
	global_load_dwordx2 v[30:31], v[4:5], off offset:96
	global_load_dwordx2 v[32:33], v[4:5], off offset:112
	v_mov_b32_e32 v2, 0x4000
	v_lshl_add_u32 v2, v6, 8, v2
	v_cndmask_b32_e64 v1, v1, v2, s[40:41]
	v_lshl_add_u32 v93, v96, 6, v1
	v_and_b32_e32 v41, 0xffff0000, v35
	v_ashrrev_i32_e32 v89, 31, v93
	v_and_b32_e32 v35, 31, v16
	v_ashrrev_i32_e32 v81, 5, v16
	v_mov_b64_e32 v[2:3], s[2:3]
	s_movk_i32 s0, 0x1200
	v_mad_i64_i32 v[2:3], s[4:5], v93, s0, v[2:3]
	v_lshlrev_b32_e32 v90, 1, v0
	v_mov_b32_e32 v91, v161
	v_ashrrev_i32_e32 v17, 31, v16
	v_lshl_add_u64 v[0:1], v[2:3], 0, v[90:91]
	v_lshl_add_u64 v[18:19], v[16:17], 1, v[0:1]
	s_mov_b64 s[0:1], 0xb200000
	v_lshl_add_u64 v[0:1], v[18:19], 0, s[0:1]
	global_load_ushort v15, v[0:1], off offset:3072
	global_load_ushort v66, v[0:1], off offset:2048
	s_mov_b32 s7, 0xb202000
	v_add_co_u32_e32 v2, vcc, s7, v18
	s_mov_b32 s11, 0xb205000
	s_nop 0
	v_addc_co_u32_e32 v3, vcc, 0, v19, vcc
	v_add_co_u32_e32 v4, vcc, s11, v18
	s_mov_b32 s12, 0xb207000
	s_nop 0
	v_addc_co_u32_e32 v5, vcc, 0, v19, vcc
	v_add_co_u32_e32 v6, vcc, s12, v18
	s_mov_b32 s13, 0xb209000
	s_nop 0
	v_addc_co_u32_e32 v7, vcc, 0, v19, vcc
	v_add_co_u32_e32 v8, vcc, s13, v18
	s_mov_b32 s14, 0xb20b000
	s_nop 0
	v_addc_co_u32_e32 v9, vcc, 0, v19, vcc
	v_add_co_u32_e32 v10, vcc, s14, v18
	s_mov_b32 s15, 0xb20e000
	s_nop 0
	v_addc_co_u32_e32 v11, vcc, 0, v19, vcc
	v_add_co_u32_e32 v62, vcc, s15, v18
	s_mov_b32 s18, 0xb210000
	s_nop 0
	v_addc_co_u32_e32 v63, vcc, 0, v19, vcc
	v_add_co_u32_e32 v64, vcc, s18, v18
	s_mov_b32 s19, 0xb212000
	s_nop 0
	v_addc_co_u32_e32 v65, vcc, 0, v19, vcc
	v_add_co_u32_e32 v76, vcc, s19, v18
	s_mov_b32 s21, 0xb214000
	s_nop 0
	v_addc_co_u32_e32 v77, vcc, 0, v19, vcc
	v_add_co_u32_e32 v102, vcc, s21, v18
	s_mov_b32 s30, 0xb217000
	s_nop 0
	v_addc_co_u32_e32 v103, vcc, 0, v19, vcc
	global_load_ushort v88, v[4:5], off offset:1024
	global_load_ushort v95, v[4:5], off
	global_load_ushort v104, v[2:3], off offset:3072
	global_load_ushort v14, v[4:5], off offset:512
	global_load_ushort v13, v[2:3], off offset:3584
	global_load_ushort v12, v[0:1], off offset:2560
	v_add_co_u32_e32 v78, vcc, s30, v18
	s_mov_b32 s9, 0xc1f00000
	s_nop 0
	v_addc_co_u32_e32 v79, vcc, 0, v19, vcc
	s_mov_b32 s31, 0xb219000
	v_add_co_u32_e32 v82, vcc, s31, v18
	s_mov_b32 s34, 0xb21b000
	s_nop 0
	v_addc_co_u32_e32 v83, vcc, 0, v19, vcc
	v_add_co_u32_e32 v20, vcc, s34, v18
	s_mov_b32 s35, 0xb21d000
	s_nop 0
	v_addc_co_u32_e32 v21, vcc, 0, v19, vcc
	v_add_co_u32_e32 v68, vcc, s35, v18
	s_mov_b32 s36, 0xb220000
	s_nop 0
	v_addc_co_u32_e32 v69, vcc, 0, v19, vcc
	v_add_co_u32_e32 v22, vcc, s36, v18
	s_mov_b32 s37, 0xb222000
	s_nop 0
	v_addc_co_u32_e32 v23, vcc, 0, v19, vcc
	v_add_co_u32_e32 v24, vcc, s37, v18
	s_mov_b32 s40, 0xb201000
	s_nop 0
	v_addc_co_u32_e32 v25, vcc, 0, v19, vcc
	s_waitcnt vmcnt(7)
	v_lshlrev_b32_e32 v0, 16, v15
	v_max_f32_e32 v0, v0, v0
	v_med3_f32 v0, v0, s9, v244
	v_mul_f32_e32 v0, 0xbfb8aa3b, v0
	v_exp_f32_e32 v86, v0
	v_add_co_u32_e32 v0, vcc, s40, v18
	s_mov_b32 s41, 0xb203000
	v_add_f32_e32 v2, 1.0, v86
	v_rcp_f32_e32 v118, v2
	v_addc_co_u32_e32 v1, vcc, 0, v19, vcc
	s_waitcnt vmcnt(6)
	v_lshlrev_b32_e32 v4, 16, v66
	v_fma_f32 v5, v80, v118, v149
	v_max_f32_e32 v15, 0xda24260, v5
	v_add_co_u32_e32 v2, vcc, s41, v18
	v_mul_f32_e32 v4, v15, v4
	s_nop 0
	v_addc_co_u32_e32 v3, vcc, 0, v19, vcc
	v_bfe_u32 v5, v4, 16, 1
	s_movk_i32 s10, 0x7fff
	s_mov_b32 s46, 0xb204000
	v_add3_u32 v105, v4, v5, s10
	v_add_co_u32_e32 v4, vcc, s46, v18
	s_mov_b32 s28, 0xb206000
	s_nop 0
	v_addc_co_u32_e32 v5, vcc, 0, v19, vcc
	global_load_ushort v106, v[4:5], off offset:-4096
	global_load_ushort v107, v[4:5], off offset:512
	global_load_ushort v87, v[0:1], off offset:3584
	global_load_ushort v110, v[0:1], off offset:2560
	global_load_ushort v111, v[2:3], off offset:3584
	v_add_co_u32_e32 v2, vcc, s28, v18
	s_mov_b32 s29, 0xb208000
	s_nop 0
	v_addc_co_u32_e32 v3, vcc, 0, v19, vcc
	global_load_ushort v156, v[6:7], off offset:1536
	global_load_ushort v157, v[8:9], off offset:2560
	global_load_ushort v158, v[10:11], off offset:3584
	global_load_ushort v116, v[6:7], off offset:2048
	global_load_ushort v117, v[8:9], off offset:3072
	global_load_ushort v121, v[10:11], off offset:3072
	global_load_ushort v120, v[8:9], off offset:2048
	global_load_ushort v126, v[6:7], off offset:1024
	v_add_co_u32_e32 v6, vcc, s29, v18
	s_mov_b32 s42, 0xb20a000
	s_nop 0
	v_addc_co_u32_e32 v7, vcc, 0, v19, vcc
	v_add_co_u32_e32 v8, vcc, s42, v18
	s_mov_b32 s6, 0xb20c000
	s_nop 0
	v_addc_co_u32_e32 v9, vcc, 0, v19, vcc
	v_add_co_u32_e32 v10, vcc, s6, v18
	s_mov_b32 s49, 0xb20d000
	s_nop 0
	v_addc_co_u32_e32 v11, vcc, 0, v19, vcc
	v_add_co_u32_e32 v66, vcc, s49, v18
	s_mov_b32 s4, 0xb20f000
	s_nop 0
	v_addc_co_u32_e32 v67, vcc, 0, v19, vcc
	v_add_co_u32_e32 v74, vcc, s4, v18
	s_mov_b32 s4, 0xb211000
	s_nop 0
	v_addc_co_u32_e32 v75, vcc, 0, v19, vcc
	v_add_co_u32_e32 v84, vcc, s4, v18
	s_mov_b32 s4, 0xb223000
	s_nop 0
	v_addc_co_u32_e32 v85, vcc, 0, v19, vcc
	global_load_ushort v159, v[62:63], off offset:512
	global_load_ushort v162, v[64:65], off offset:1536
	global_load_ushort v163, v[76:77], off offset:2560
	global_load_ushort v164, v[102:103], off offset:3584
	global_load_ushort v127, v[62:63], off offset:1024
	global_load_ushort v137, v[64:65], off offset:2048
	global_load_ushort v141, v[64:65], off offset:1024
	global_load_ushort v131, v[62:63], off
	v_add_co_u32_e32 v62, vcc, s4, v18
	s_mov_b32 s4, 0xb221000
	s_nop 0
	v_addc_co_u32_e32 v63, vcc, 0, v19, vcc
	v_add_co_u32_e32 v64, vcc, s4, v18
	s_mov_b32 s4, 0xb21f000
	s_nop 0
	v_addc_co_u32_e32 v65, vcc, 0, v19, vcc
	v_add_co_u32_e32 v70, vcc, s4, v18
	s_mov_b32 s97, 0xb21c000
	s_nop 0
	v_addc_co_u32_e32 v71, vcc, 0, v19, vcc
	v_add_co_u32_e32 v72, vcc, s97, v18
	s_mov_b32 s4, 0xb21a000
	s_nop 0
	v_addc_co_u32_e32 v73, vcc, 0, v19, vcc
	v_add_co_u32_e32 v108, vcc, s4, v18
	s_mov_b32 s48, 0xb218000
	s_nop 0
	v_addc_co_u32_e32 v109, vcc, 0, v19, vcc
	v_add_co_u32_e32 v112, vcc, s48, v18
	s_mov_b32 s47, 0xb216000
	s_nop 0
	v_addc_co_u32_e32 v113, vcc, 0, v19, vcc
	v_add_co_u32_e32 v114, vcc, s47, v18
	s_mov_b32 s43, 0xb213000
	s_nop 0
	v_addc_co_u32_e32 v115, vcc, 0, v19, vcc
	v_add_co_u32_e32 v124, vcc, s43, v18
	global_load_ushort v165, v[78:79], off offset:512
	global_load_ushort v166, v[82:83], off offset:1536
	global_load_ushort v167, v[20:21], off offset:2560
	global_load_ushort v168, v[68:69], off offset:3584
	global_load_ushort v169, v[22:23], off offset:512
	global_load_ushort v170, v[24:25], off offset:1536
	global_load_ushort v171, v[22:23], off offset:-4096
	global_load_ushort v172, v[78:79], off offset:-4096
	v_addc_co_u32_e32 v125, vcc, 0, v19, vcc
	global_load_ushort v128, v[66:67], off offset:-4096
	global_load_ushort v129, v[66:67], off offset:512
	global_load_ushort v173, v[112:113], off offset:1024
	s_nop 0
	global_load_ushort v66, v[66:67], off
	s_nop 0
	global_load_ushort v67, v[4:5], off
	s_nop 0
	global_load_ushort v4, v[124:125], off offset:3072
	global_load_ushort v5, v[2:3], off offset:1536
	global_load_ushort v130, v[2:3], off offset:512
	global_load_ushort v136, v[6:7], off offset:1536
	global_load_ushort v174, v[2:3], off offset:1024
	global_load_ushort v175, v[0:1], off offset:3072
	s_waitcnt vmcnt(37)
	v_lshlrev_b32_e32 v0, 16, v87
	v_max_f32_e32 v0, v0, v0
	v_med3_f32 v0, v0, s9, v244
	v_mul_f32_e32 v0, 0xbfb8aa3b, v0
	v_exp_f32_e32 v87, v0
	global_load_ushort v0, v[74:75], off offset:1536
	global_load_ushort v1, v[84:85], off offset:2560
	global_load_ushort v2, v[84:85], off offset:1536
	global_load_ushort v3, v[62:63], off offset:2048
	global_load_ushort v176, v[64:65], off offset:1024
	global_load_ushort v177, v[72:73], off offset:3072
	global_load_ushort v178, v[108:109], off offset:2048
	global_load_ushort v179, v[84:85], off offset:2048
	global_load_ushort v138, v[6:7], off offset:2560
	global_load_ushort v139, v[8:9], off offset:3584
	global_load_ushort v140, v[8:9], off offset:2560
	s_nop 0
	global_load_ushort v10, v[10:11], off offset:3584
	s_nop 0
	global_load_ushort v11, v[74:75], off offset:512
	global_load_ushort v180, v[74:75], off offset:1024
	s_nop 0
	global_load_ushort v8, v[8:9], off offset:3072
	s_nop 0
	global_load_ushort v181, v[6:7], off offset:2048
	s_mov_b32 s101, 0
	s_mov_b32 s100, 0xb213000
	v_lshl_add_u64 v[196:197], v[18:19], 0, s[100:101]
	global_load_ushort v200, v[196:197], off offset:-2048
	global_load_ushort v201, v[196:197], off offset:-1024
	global_load_ushort v202, v[196:197], off offset:2560
	global_load_ushort v203, v[196:197], off offset:3584
	s_mov_b32 s100, 0xb215400
	v_lshl_add_u64 v[198:199], v[18:19], 0, s[100:101]
	global_load_ushort v206, v[198:199], off offset:-2048
	global_load_ushort v207, v[198:199], off offset:-1024
	global_load_ushort v208, v[198:199], off offset:2560
	global_load_ushort v209, v[198:199], off offset:3584
	s_mov_b32 s100, 0xb217800
	v_lshl_add_u64 v[196:197], v[18:19], 0, s[100:101]
	global_load_ushort v210, v[196:197], off offset:-2048
	global_load_ushort v211, v[196:197], off offset:-1024
	global_load_ushort v212, v[196:197], off offset:2560
	global_load_ushort v213, v[196:197], off offset:3584
	s_mov_b32 s100, 0xb219c00
	v_lshl_add_u64 v[198:199], v[18:19], 0, s[100:101]
	global_load_ushort v214, v[198:199], off offset:-2048
	global_load_ushort v215, v[198:199], off offset:-1024
	global_load_ushort v216, v[198:199], off offset:2560
	global_load_ushort v217, v[198:199], off offset:3584
	s_mov_b32 s100, 0xb21c000
	v_lshl_add_u64 v[196:197], v[18:19], 0, s[100:101]
	global_load_ushort v218, v[196:197], off offset:-2048
	global_load_ushort v219, v[196:197], off offset:-1024
	global_load_ushort v220, v[196:197], off offset:2560
	global_load_ushort v221, v[196:197], off offset:3584
	s_mov_b32 s100, 0xb21e400
	v_lshl_add_u64 v[198:199], v[18:19], 0, s[100:101]
	global_load_ushort v222, v[198:199], off offset:-2048
	global_load_ushort v223, v[198:199], off offset:-1024
	global_load_ushort v224, v[198:199], off offset:2560
	global_load_ushort v225, v[198:199], off offset:3584
	s_mov_b32 s100, 0xb220800
	v_lshl_add_u64 v[196:197], v[18:19], 0, s[100:101]
	global_load_ushort v226, v[196:197], off offset:-2048
	global_load_ushort v227, v[196:197], off offset:-1024
	global_load_ushort v228, v[196:197], off offset:2560
	global_load_ushort v229, v[196:197], off offset:3584
	s_mov_b32 s100, 0xb222c00
	v_lshl_add_u64 v[198:199], v[18:19], 0, s[100:101]
	global_load_ushort v230, v[198:199], off offset:-2048
	global_load_ushort v231, v[198:199], off offset:-1024
	global_load_ushort v232, v[198:199], off offset:2560
	global_load_ushort v233, v[198:199], off offset:3584
	v_lshlrev_b32_e32 v7, 16, v106
	v_max_f32_e32 v7, v7, v7
	v_add_f32_e32 v84, 1.0, v87
	v_med3_f32 v7, v7, s9, v244
	v_rcp_f32_e32 v119, v84
	v_mul_f32_e32 v7, 0xbfb8aa3b, v7
	v_exp_f32_e32 v84, v7
	s_waitcnt vmcnt(63)
	v_lshlrev_b32_e32 v7, 16, v110
	v_fma_f32 v6, v80, v119, v149
	v_mul_f32_e32 v6, v15, v6
	v_add_f32_e32 v9, 1.0, v84
	v_max_f32_e32 v6, 0xda24260, v6
	v_rcp_f32_e32 v132, v9
	v_mul_f32_e32 v7, v6, v7
	v_bfe_u32 v9, v7, 16, 1
	v_lshl_add_u32 v17, v16, 1, v92
	v_add3_u32 v7, v7, v9, s10
	ds_write_b16_d16_hi v17, v7 offset:144
	v_fma_f32 v7, v80, v132, v149
	v_rcp_f32_e32 v123, v6
	v_mul_f32_e32 v6, v6, v7
	v_lshlrev_b32_e32 v7, 16, v107
	v_max_f32_e32 v7, v7, v7
	v_med3_f32 v7, v7, s9, v244
	v_mul_f32_e32 v7, 0xbfb8aa3b, v7
	v_exp_f32_e32 v85, v7
	v_max_f32_e32 v6, 0xda24260, v6
	v_lshlrev_b32_e32 v7, 16, v104
	v_mul_f32_e32 v7, v6, v7
	v_add_f32_e32 v9, 1.0, v85
	v_rcp_f32_e32 v133, v9
	v_bfe_u32 v9, v7, 16, 1
	v_add3_u32 v7, v7, v9, s10
	ds_write_b16_d16_hi v17, v7 offset:288
	v_fma_f32 v7, v80, v133, v149
	v_rcp_f32_e32 v134, v6
	v_mul_f32_e32 v6, v6, v7
	v_lshlrev_b32_e32 v7, 16, v88
	v_max_f32_e32 v7, v7, v7
	v_med3_f32 v7, v7, s9, v244
	v_mul_f32_e32 v7, 0xbfb8aa3b, v7
	v_exp_f32_e32 v74, v7
	v_max_f32_e32 v6, 0xda24260, v6
	s_waitcnt vmcnt(63)
	v_lshlrev_b32_e32 v7, 16, v111
	v_mul_f32_e32 v7, v6, v7
	v_add_f32_e32 v9, 1.0, v74
	v_rcp_f32_e32 v144, v9
	v_bfe_u32 v9, v7, 16, 1
	v_add3_u32 v7, v7, v9, s10
	ds_write_b16_d16_hi v17, v7 offset:432
	v_fma_f32 v7, v80, v144, v149
	v_rcp_f32_e32 v135, v6
	v_mul_f32_e32 v6, v6, v7
	v_max_f32_e32 v6, 0xda24260, v6
	v_rcp_f32_e32 v146, v6
	ds_write_b16_d16_hi v17, v105
	v_rcp_f32_e32 v122, v15
	v_pk_mul_f32 v[84:85], v[84:85], v[132:133]
	v_pk_mul_f32 v[86:87], v[86:87], v[118:119]
	v_pk_mul_f32 v[84:85], v[80:81], v[84:85] op_sel_hi:[0,1]
	v_pk_mul_f32 v[86:87], v[80:81], v[86:87] op_sel_hi:[0,1]
	s_movk_i32 s4, 0x50
	v_pk_mul_f32 v[84:85], v[84:85], v[134:135]
	v_pk_mul_f32 v[86:87], v[86:87], v[122:123]
	v_and_b32_sdwa v132, v85, v239 dst_sel:DWORD dst_unused:UNUSED_PAD src0_sel:WORD_1 src1_sel:DWORD
	s_waitcnt vmcnt(55)
	v_lshl_or_b32 v9, v66, 16, v158
	s_waitcnt vmcnt(54)
	v_lshl_or_b32 v13, v67, 16, v13
	v_mad_u64_u32 v[66:67], s[4:5], v16, s4, v[92:93]
	s_waitcnt vmcnt(52)
	v_lshlrev_b32_e32 v5, 16, v5
	v_max_f32_e32 v5, v5, v5
	v_med3_f32 v5, v5, s9, v244
	v_mul_f32_e32 v5, 0xbfb8aa3b, v5
	v_exp_f32_e32 v75, v5
	v_lshlrev_b32_e32 v5, 16, v95
	v_mul_f32_e32 v5, v6, v5
	s_waitcnt vmcnt(47)
	v_lshlrev_b32_e32 v0, 16, v0
	v_add_f32_e32 v7, 1.0, v75
	v_rcp_f32_e32 v145, v7
	v_bfe_u32 v7, v5, 16, 1
	v_add3_u32 v5, v5, v7, s10
	ds_write_b16_d16_hi v17, v5 offset:576
	v_fma_f32 v5, v80, v145, v149
	v_mul_f32_e32 v5, v6, v5
	v_lshlrev_b32_e32 v6, 16, v116
	v_max_f32_e32 v6, v6, v6
	v_med3_f32 v6, v6, s9, v244
	v_mul_f32_e32 v6, 0xbfb8aa3b, v6
	v_exp_f32_e32 v150, v6
	v_max_f32_e32 v5, 0xda24260, v5
	v_lshlrev_b32_e32 v6, 16, v130
	v_mul_f32_e32 v6, v5, v6
	v_add_f32_e32 v7, 1.0, v150
	v_rcp_f32_e32 v152, v7
	v_bfe_u32 v7, v6, 16, 1
	v_add3_u32 v6, v6, v7, s10
	ds_write_b16_d16_hi v17, v6 offset:720
	v_fma_f32 v6, v80, v152, v149
	v_rcp_f32_e32 v147, v5
	v_mul_f32_e32 v5, v5, v6
	s_waitcnt vmcnt(39)
	v_lshlrev_b32_e32 v6, 16, v138
	v_max_f32_e32 v6, v6, v6
	v_med3_f32 v6, v6, s9, v244
	v_mul_f32_e32 v6, 0xbfb8aa3b, v6
	v_exp_f32_e32 v151, v6
	v_max_f32_e32 v5, 0xda24260, v5
	v_lshlrev_b32_e32 v6, 16, v126
	v_mul_f32_e32 v6, v5, v6
	v_add_f32_e32 v7, 1.0, v151
	v_rcp_f32_e32 v153, v7
	v_bfe_u32 v7, v6, 16, 1
	v_add3_u32 v6, v6, v7, s10
	ds_write_b16_d16_hi v17, v6 offset:864
	v_fma_f32 v6, v80, v153, v149
	v_rcp_f32_e32 v154, v5
	v_mul_f32_e32 v5, v5, v6
	v_lshlrev_b32_e32 v6, 16, v117
	v_max_f32_e32 v6, v6, v6
	v_med3_f32 v6, v6, s9, v244
	v_mul_f32_e32 v6, 0xbfb8aa3b, v6
	v_exp_f32_e32 v104, v6
	v_max_f32_e32 v5, 0xda24260, v5
	v_lshlrev_b32_e32 v6, 16, v136
	v_mul_f32_e32 v6, v5, v6
	v_add_f32_e32 v7, 1.0, v104
	v_rcp_f32_e32 v106, v7
	v_bfe_u32 v7, v6, 16, 1
	v_add3_u32 v6, v6, v7, s10
	ds_write_b16_d16_hi v17, v6 offset:1008
	v_fma_f32 v6, v80, v106, v149
	v_rcp_f32_e32 v155, v5
	v_mul_f32_e32 v5, v5, v6
	s_waitcnt vmcnt(38)
	v_lshlrev_b32_e32 v6, 16, v139
	v_max_f32_e32 v6, v6, v6
	v_med3_f32 v6, v6, s9, v244
	v_mul_f32_e32 v6, 0xbfb8aa3b, v6
	v_exp_f32_e32 v105, v6
	v_max_f32_e32 v5, 0xda24260, v5
	v_lshlrev_b32_e32 v6, 16, v120
	v_mul_f32_e32 v6, v5, v6
	v_add_f32_e32 v7, 1.0, v105
	v_rcp_f32_e32 v107, v7
	v_bfe_u32 v7, v6, 16, 1
	v_add3_u32 v88, v6, v7, s10
	v_rcp_f32_e32 v110, v5
	v_fma_f32 v6, v80, v107, v149
	v_mul_f32_e32 v5, v5, v6
	v_lshlrev_b32_e32 v6, 16, v128
	v_max_f32_e32 v6, v6, v6
	v_med3_f32 v6, v6, s9, v244
	v_mul_f32_e32 v6, 0xbfb8aa3b, v6
	v_exp_f32_e32 v116, v6
	v_max_f32_e32 v5, 0xda24260, v5
	s_waitcnt vmcnt(37)
	v_lshlrev_b32_e32 v6, 16, v140
	v_mul_f32_e32 v6, v5, v6
	v_add_f32_e32 v7, 1.0, v116
	v_rcp_f32_e32 v120, v7
	v_bfe_u32 v7, v6, 16, 1
	v_add3_u32 v95, v6, v7, s10
	v_rcp_f32_e32 v111, v5
	v_fma_f32 v6, v80, v120, v149
	v_mul_f32_e32 v5, v5, v6
	v_lshlrev_b32_e32 v6, 16, v129
	v_max_f32_e32 v6, v6, v6
	v_med3_f32 v6, v6, s9, v244
	v_mul_f32_e32 v6, 0xbfb8aa3b, v6
	v_exp_f32_e32 v117, v6
	v_lshlrev_b32_e32 v6, 16, v121
	v_max_f32_e32 v5, 0xda24260, v5
	v_mul_f32_e32 v6, v5, v6
	v_add_f32_e32 v7, 1.0, v117
	v_rcp_f32_e32 v121, v7
	v_bfe_u32 v7, v6, 16, 1
	v_add3_u32 v182, v6, v7, s10
	v_rcp_f32_e32 v126, v5
	v_fma_f32 v6, v80, v121, v149
	v_mul_f32_e32 v5, v5, v6
	v_lshlrev_b32_e32 v6, 16, v127
	v_max_f32_e32 v6, v6, v6
	v_med3_f32 v6, v6, s9, v244
	v_mul_f32_e32 v6, 0xbfb8aa3b, v6
	v_exp_f32_e32 v128, v6
	v_max_f32_e32 v0, v0, v0
	v_med3_f32 v0, v0, s9, v244
	v_mul_f32_e32 v0, 0xbfb8aa3b, v0
	v_add_f32_e32 v7, 1.0, v128
	v_rcp_f32_e32 v130, v7
	v_max_f32_e32 v5, 0xda24260, v5
	s_waitcnt vmcnt(36)
	v_lshlrev_b32_e32 v6, 16, v10
	v_exp_f32_e32 v129, v0
	v_mul_f32_e32 v6, v5, v6
	v_bfe_u32 v7, v6, 16, 1
	v_add3_u32 v183, v6, v7, s10
	v_fma_f32 v6, v80, v130, v149
	v_rcp_f32_e32 v127, v5
	v_mul_f32_e32 v5, v5, v6
	v_add_f32_e32 v6, 1.0, v129
	v_max_f32_e32 v0, 0xda24260, v5
	v_lshlrev_b32_e32 v5, 16, v131
	v_rcp_f32_e32 v131, v6
	v_mul_f32_e32 v5, v0, v5
	v_bfe_u32 v6, v5, 16, 1
	v_add3_u32 v184, v5, v6, s10
	v_fma_f32 v5, v80, v131, v149
	v_rcp_f32_e32 v136, v0
	v_mul_f32_e32 v0, v0, v5
	v_lshlrev_b32_e32 v5, 16, v137
	v_max_f32_e32 v5, v5, v5
	v_med3_f32 v5, v5, s9, v244
	v_mul_f32_e32 v5, 0xbfb8aa3b, v5
	v_exp_f32_e32 v138, v5
	v_lshlrev_b32_e32 v1, 16, v1
	v_max_f32_e32 v1, v1, v1
	v_med3_f32 v1, v1, s9, v244
	v_add_f32_e32 v6, 1.0, v138
	v_rcp_f32_e32 v140, v6
	v_mul_f32_e32 v1, 0xbfb8aa3b, v1
	v_max_f32_e32 v0, 0xda24260, v0
	s_waitcnt vmcnt(35)
	v_lshlrev_b32_e32 v5, 16, v11
	v_exp_f32_e32 v139, v1
	v_mul_f32_e32 v5, v0, v5
	v_bfe_u32 v6, v5, 16, 1
	v_add3_u32 v185, v5, v6, s10
	v_fma_f32 v5, v80, v140, v149
	v_rcp_f32_e32 v137, v0
	v_mul_f32_e32 v0, v0, v5
	v_add_f32_e32 v5, 1.0, v139
	v_lshlrev_b32_e32 v1, 16, v141
	v_rcp_f32_e32 v141, v5
	v_max_f32_e32 v0, 0xda24260, v0
	v_mul_f32_e32 v1, v0, v1
	v_bfe_u32 v5, v1, 16, 1
	v_add3_u32 v186, v1, v5, s10
	v_fma_f32 v1, v80, v141, v149
	v_pk_mul_f32 v[150:151], v[150:151], v[152:153]
	v_pk_mul_f32 v[74:75], v[74:75], v[144:145]
	v_rcp_f32_e32 v142, v0
	v_mul_f32_e32 v0, v0, v1
	v_pk_mul_f32 v[150:151], v[80:81], v[150:151] op_sel_hi:[0,1]
	v_pk_mul_f32 v[74:75], v[80:81], v[74:75] op_sel_hi:[0,1]
	v_max_f32_e32 v187, 0xda24260, v0
	v_lshlrev_b32_e32 v0, 16, v2
	v_pk_mul_f32 v[150:151], v[150:151], v[154:155]
	v_pk_mul_f32 v[74:75], v[74:75], v[146:147]
	v_mul_f32_e32 v0, v187, v0
	v_and_b32_sdwa v152, v150, v239 dst_sel:DWORD dst_unused:UNUSED_PAD src0_sel:WORD_1 src1_sel:DWORD
	v_and_b32_sdwa v144, v75, v239 dst_sel:DWORD dst_unused:UNUSED_PAD src0_sel:WORD_1 src1_sel:DWORD
	v_and_b32_sdwa v145, v74, v239 dst_sel:DWORD dst_unused:UNUSED_PAD src0_sel:WORD_1 src1_sel:DWORD
	v_and_b32_sdwa v133, v84, v239 dst_sel:DWORD dst_unused:UNUSED_PAD src0_sel:WORD_1 src1_sel:DWORD
	v_and_b32_sdwa v118, v87, v239 dst_sel:DWORD dst_unused:UNUSED_PAD src0_sel:WORD_1 src1_sel:DWORD
	v_and_b32_sdwa v119, v86, v239 dst_sel:DWORD dst_unused:UNUSED_PAD src0_sel:WORD_1 src1_sel:DWORD
	v_bfe_u32 v1, v0, 16, 1
	v_and_b32_sdwa v67, v151, v239 dst_sel:DWORD dst_unused:UNUSED_PAD src0_sel:WORD_1 src1_sel:DWORD
	v_add3_u32 v150, v150, v152, s10
	v_add3_u32 v75, v75, v144, s10
	v_add3_u32 v74, v74, v145, s10
	v_add3_u32 v85, v85, v132, s10
	v_add3_u32 v84, v84, v133, s10
	v_add3_u32 v87, v87, v118, s10
	v_add3_u32 v86, v86, v119, s10
	v_rcp_f32_e32 v143, v187
	v_add3_u32 v188, v0, v1, s10
	v_lshl_or_b32 v3, v3, 16, v170
	v_lshl_or_b32 v2, v176, 16, v169
	v_lshl_or_b32 v1, v171, 16, v168
	v_lshl_or_b32 v0, v177, 16, v167
	v_lshl_or_b32 v7, v178, 16, v166
	v_lshl_or_b32 v6, v173, 16, v165
	v_lshl_or_b32 v5, v172, 16, v164
	v_lshl_or_b32 v4, v4, 16, v163
	v_lshl_or_b32 v11, v179, 16, v162
	s_waitcnt vmcnt(34)
	v_lshl_or_b32 v10, v180, 16, v159
	s_waitcnt vmcnt(33)
	v_lshl_or_b32 v8, v8, 16, v157
	s_waitcnt vmcnt(32)
	v_lshl_or_b32 v15, v181, 16, v156
	v_lshl_or_b32 v14, v174, 16, v14
	v_lshl_or_b32 v12, v175, 16, v12
	s_movk_i32 s16, 0x50
	v_add3_u32 v67, v151, v67, s10
	ds_write_b16_d16_hi v17, v150 offset:5472
	ds_write_b16_d16_hi v17, v67 offset:5616
	ds_write_b16_d16_hi v17, v74 offset:5184
	ds_write_b16_d16_hi v17, v75 offset:5328
	v_and_b32_e32 v75, 0xffff0000, v75
	v_and_b32_e32 v74, 0xffff0000, v74
	ds_write_b16_d16_hi v17, v84 offset:4896
	ds_write_b16_d16_hi v17, v85 offset:5040
	v_and_b32_e32 v85, 0xffff0000, v85
	v_and_b32_e32 v84, 0xffff0000, v84
	ds_write_b16_d16_hi v17, v86 offset:4608
	ds_write_b16_d16_hi v17, v87 offset:4752
	v_and_b32_e32 v87, 0xffff0000, v87
	v_and_b32_e32 v86, 0xffff0000, v86
	s_nop 0
	s_nop 0
	s_nop 0
	s_nop 0
	s_mov_b32 s5, 0xb215000
	v_add_co_u32_e32 v76, vcc, s5, v18
	v_pk_mul_f32 v[138:139], v[138:139], v[140:141]
	s_nop 0
	v_addc_co_u32_e32 v77, vcc, 0, v19, vcc
	s_nop 0
	s_nop 0
	s_nop 0
	s_nop 0
	ds_write_b16_d16_hi v17, v88 offset:1152
	ds_write_b16_d16_hi v17, v95 offset:1296
	ds_write_b16_d16_hi v17, v182 offset:1440
	ds_write_b16_d16_hi v17, v183 offset:1584
	ds_write_b16_d16_hi v17, v184 offset:1728
	ds_write_b16_d16_hi v17, v185 offset:1872
	ds_write_b16_d16_hi v17, v186 offset:2016
	ds_write_b16_d16_hi v17, v188 offset:2160
	v_pk_mul_f32 v[128:129], v[128:129], v[130:131]
	v_pk_mul_f32 v[116:117], v[116:117], v[120:121]
	v_pk_mul_f32 v[104:105], v[104:105], v[106:107]
	v_pk_mul_f32 v[138:139], v[80:81], v[138:139] op_sel_hi:[0,1]
	v_pk_mul_f32 v[128:129], v[80:81], v[128:129] op_sel_hi:[0,1]
	v_pk_mul_f32 v[116:117], v[80:81], v[116:117] op_sel_hi:[0,1]
	v_pk_mul_f32 v[104:105], v[80:81], v[104:105] op_sel_hi:[0,1]
	v_pk_mul_f32 v[138:139], v[138:139], v[142:143]
	v_pk_mul_f32 v[128:129], v[128:129], v[136:137]
	v_pk_mul_f32 v[116:117], v[116:117], v[126:127]
	v_pk_mul_f32 v[104:105], v[104:105], v[110:111]
	v_and_b32_sdwa v140, v138, v239 dst_sel:DWORD dst_unused:UNUSED_PAD src0_sel:WORD_1 src1_sel:DWORD
	v_and_b32_sdwa v130, v129, v239 dst_sel:DWORD dst_unused:UNUSED_PAD src0_sel:WORD_1 src1_sel:DWORD
	v_and_b32_sdwa v131, v128, v239 dst_sel:DWORD dst_unused:UNUSED_PAD src0_sel:WORD_1 src1_sel:DWORD
	v_and_b32_sdwa v120, v117, v239 dst_sel:DWORD dst_unused:UNUSED_PAD src0_sel:WORD_1 src1_sel:DWORD
	v_and_b32_sdwa v121, v116, v239 dst_sel:DWORD dst_unused:UNUSED_PAD src0_sel:WORD_1 src1_sel:DWORD
	v_and_b32_sdwa v106, v105, v239 dst_sel:DWORD dst_unused:UNUSED_PAD src0_sel:WORD_1 src1_sel:DWORD
	v_and_b32_sdwa v107, v104, v239 dst_sel:DWORD dst_unused:UNUSED_PAD src0_sel:WORD_1 src1_sel:DWORD
	v_add3_u32 v142, v138, v140, s10
	v_add3_u32 v129, v129, v130, s10
	v_add3_u32 v128, v128, v131, s10
	v_add3_u32 v117, v117, v120, s10
	v_add3_u32 v116, v116, v121, s10
	v_add3_u32 v105, v105, v106, s10
	v_add3_u32 v104, v104, v107, s10
	s_waitcnt vmcnt(30)
	v_lshlrev_b32_e32 v108, 16, v201
	s_waitcnt vmcnt(27)
	v_lshlrev_b32_e32 v113, 16, v206
	s_waitcnt vmcnt(18)
	v_lshlrev_b32_e32 v118, 16, v210
	v_max_f32_e32 v78, v108, v108
	s_waitcnt vmcnt(18)
	v_lshlrev_b32_e32 v112, 16, v200
	s_waitcnt vmcnt(18)
	v_lshlrev_b32_e32 v79, 16, v203
	v_med3_f32 v78, v78, s9, v244
	v_lshlrev_b32_e32 v82, 16, v211
	v_max_f32_e32 v79, v79, v79
	v_mul_f32_e32 v78, 0xbfb8aa3b, v78
	s_waitcnt vmcnt(18)
	v_lshlrev_b32_e32 v122, 16, v202
	v_lshlrev_b32_e32 v77, 16, v207
	v_lshlrev_b32_e32 v124, 16, v208
	v_max_f32_e32 v76, v82, v82
	s_waitcnt vmcnt(18)
	v_lshlrev_b32_e32 v82, 16, v213
	v_med3_f32 v79, v79, s9, v244
	v_exp_f32_e32 v102, v78
	v_max_f32_e32 v77, v77, v77
	v_max_f32_e32 v82, v82, v82
	v_mul_f32_e32 v79, 0xbfb8aa3b, v79
	v_lshlrev_b32_e32 v83, 16, v209
	v_med3_f32 v76, v76, s9, v244
	v_med3_f32 v77, v77, s9, v244
	v_med3_f32 v82, v82, s9, v244
	v_exp_f32_e32 v103, v79
	v_max_f32_e32 v83, v83, v83
	v_mul_f32_e32 v76, 0xbfb8aa3b, v76
	v_mul_f32_e32 v77, 0xbfb8aa3b, v77
	v_mul_f32_e32 v82, 0xbfb8aa3b, v82
	v_med3_f32 v83, v83, s9, v244
	v_exp_f32_e32 v76, v76
	v_exp_f32_e32 v78, v77
	v_exp_f32_e32 v77, v82
	v_add_f32_e32 v82, 1.0, v102
	v_mul_f32_e32 v79, 0xbfb8aa3b, v83
	v_rcp_f32_e32 v114, v82
	v_exp_f32_e32 v79, v79
	v_add_f32_e32 v83, 1.0, v103
	v_rcp_f32_e32 v115, v83
	v_add_f32_e32 v108, 1.0, v76
	v_add_f32_e32 v83, 1.0, v78
	v_rcp_f32_e32 v82, v108
	v_rcp_f32_e32 v108, v83
	v_fma_f32 v83, v80, v114, v149
	v_add_f32_e32 v109, 1.0, v79
	v_mul_f32_e32 v83, v187, v83
	v_rcp_f32_e32 v109, v109
	v_fma_f32 v125, v80, v115, v149
	v_max_f32_e32 v83, 0xda24260, v83
	v_rcp_f32_e32 v134, v83
	v_mul_f32_e32 v112, v83, v112
	v_mul_f32_e32 v83, v83, v125
	v_fma_f32 v132, v80, v108, v149
	v_bfe_u32 v125, v112, 16, 1
	v_max_f32_e32 v83, 0xda24260, v83
	v_add3_u32 v146, v112, v125, s10
	v_rcp_f32_e32 v135, v83
	v_mul_f32_e32 v112, v83, v122
	v_mul_f32_e32 v83, v83, v132
	v_fma_f32 v133, v80, v109, v149
	v_bfe_u32 v122, v112, 16, 1
	v_max_f32_e32 v83, 0xda24260, v83
	v_add3_u32 v147, v112, v122, s10
	v_rcp_f32_e32 v132, v83
	v_mul_f32_e32 v112, v83, v113
	v_mul_f32_e32 v83, v83, v133
	v_fma_f32 v145, v80, v82, v149
	v_bfe_u32 v113, v112, 16, 1
	v_max_f32_e32 v83, 0xda24260, v83
	v_add3_u32 v151, v112, v113, s10
	v_rcp_f32_e32 v133, v83
	v_mul_f32_e32 v112, v83, v124
	v_mul_f32_e32 v83, v83, v145
	v_max_f32_e32 v124, 0xda24260, v83
	v_add_f32_e32 v83, 1.0, v77
	v_rcp_f32_e32 v83, v83
	v_bfe_u32 v113, v112, 16, 1
	v_add3_u32 v152, v112, v113, s10
	v_mul_f32_e32 v112, v124, v118
	v_bfe_u32 v113, v112, 16, 1
	v_add3_u32 v153, v112, v113, s10
	v_fma_f32 v112, v80, v83, v149
	v_mul_f32_e32 v113, v124, v112
	v_lshlrev_b32_e32 v112, 16, v215
	v_max_f32_e32 v112, v112, v112
	v_med3_f32 v112, v112, s9, v244
	v_mul_f32_e32 v112, 0xbfb8aa3b, v112
	v_exp_f32_e32 v112, v112
	v_max_f32_e32 v113, 0xda24260, v113
	s_waitcnt vmcnt(17)
	v_lshlrev_b32_e32 v88, 16, v212
	s_waitcnt vmcnt(16)
	v_lshlrev_b32_e32 v95, 16, v217
	v_add_f32_e32 v118, 1.0, v112
	v_rcp_f32_e32 v118, v118
	v_mul_f32_e32 v88, v113, v88
	v_max_f32_e32 v95, v95, v95
	v_rcp_f32_e32 v122, v124
	v_bfe_u32 v124, v88, 16, 1
	v_med3_f32 v95, v95, s9, v244
	v_add3_u32 v88, v88, v124, s10
	v_fma_f32 v124, v80, v118, v149
	v_mul_f32_e32 v95, 0xbfb8aa3b, v95
	v_rcp_f32_e32 v123, v113
	v_mul_f32_e32 v124, v113, v124
	v_exp_f32_e32 v113, v95
	v_lshlrev_b32_e32 v125, 16, v214
	v_max_f32_e32 v95, 0xda24260, v124
	v_mul_f32_e32 v125, v95, v125
	v_add_f32_e32 v119, 1.0, v113
	v_rcp_f32_e32 v119, v119
	v_bfe_u32 v145, v125, 16, 1
	v_add3_u32 v154, v125, v145, s10
	v_rcp_f32_e32 v124, v95
	v_fma_f32 v125, v80, v119, v149
	v_mul_f32_e32 v95, v95, v125
	v_max_f32_e32 v95, 0xda24260, v95
	v_lshlrev_b32_e32 v144, 16, v216
	v_mul_f32_e32 v144, v95, v144
	v_bfe_u32 v145, v144, 16, 1
	v_add3_u32 v155, v144, v145, s10
	v_and_b32_e32 v145, 0xffff0000, v67
	v_and_b32_sdwa v67, v139, v239 dst_sel:DWORD dst_unused:UNUSED_PAD src0_sel:WORD_1 src1_sel:DWORD
	v_rcp_f32_e32 v125, v95
	v_and_b32_e32 v144, 0xffff0000, v150
	v_add3_u32 v67, v139, v67, s10
	ds_write_b16_d16_hi v17, v142 offset:6624
	ds_write_b16_d16_hi v17, v67 offset:6768
	ds_write_b16_d16_hi v17, v128 offset:6336
	ds_write_b16_d16_hi v17, v129 offset:6480
	v_and_b32_e32 v129, 0xffff0000, v129
	v_and_b32_e32 v128, 0xffff0000, v128
	ds_write_b16_d16_hi v17, v116 offset:6048
	ds_write_b16_d16_hi v17, v117 offset:6192
	v_and_b32_e32 v117, 0xffff0000, v117
	v_and_b32_e32 v116, 0xffff0000, v116
	ds_write_b16_d16_hi v17, v104 offset:5760
	ds_write_b16_d16_hi v17, v105 offset:5904
	v_and_b32_e32 v105, 0xffff0000, v105
	v_and_b32_e32 v104, 0xffff0000, v104
	s_nop 0
	s_nop 0
	s_nop 0
	s_nop 0
	s_nop 0
	s_mov_b32 s4, 0xb21e000
	v_add_co_u32_e32 v18, vcc, s4, v18
	s_waitcnt vmcnt(11)
	v_lshlrev_b32_e32 v68, 16, v222
	v_addc_co_u32_e32 v19, vcc, 0, v19, vcc
	s_nop 0
	s_nop 0
	s_nop 0
	ds_write_b16_d16_hi v17, v146 offset:2304
	ds_write_b16_d16_hi v17, v147 offset:2448
	ds_write_b16_d16_hi v17, v151 offset:2592
	ds_write_b16_d16_hi v17, v152 offset:2736
	ds_write_b16_d16_hi v17, v153 offset:2880
	ds_write_b16_d16_hi v17, v88 offset:3024
	ds_write_b16_d16_hi v17, v154 offset:3168
	ds_write_b16_d16_hi v17, v155 offset:3312
	s_nop 0
	v_lshlrev_b32_e32 v63, 16, v219
	s_waitcnt vmcnt(2)
	v_lshlrev_b32_e32 v65, 16, v218
	s_waitcnt vmcnt(2)
	v_lshlrev_b32_e32 v20, 16, v221
	v_lshlrev_b32_e32 v21, 16, v227
	v_lshlrev_b32_e32 v69, 16, v226
	v_max_f32_e32 v22, v63, v63
	v_med3_f32 v22, v22, s9, v244
	v_max_f32_e32 v20, v20, v20
	v_mul_f32_e32 v22, 0xbfb8aa3b, v22
	v_med3_f32 v20, v20, s9, v244
	v_mul_f32_e32 v20, 0xbfb8aa3b, v20
	s_waitcnt vmcnt(2)
	v_lshlrev_b32_e32 v71, 16, v224
	s_waitcnt vmcnt(2)
	v_lshlrev_b32_e32 v63, 16, v220
	v_lshlrev_b32_e32 v19, 16, v223
	s_waitcnt vmcnt(2)
	v_lshlrev_b32_e32 v23, 16, v225
	v_exp_f32_e32 v24, v22
	v_max_f32_e32 v18, v21, v21
	s_waitcnt vmcnt(2)
	v_lshlrev_b32_e32 v21, 16, v229
	v_max_f32_e32 v19, v19, v19
	v_max_f32_e32 v23, v23, v23
	v_max_f32_e32 v21, v21, v21
	v_med3_f32 v19, v19, s9, v244
	v_med3_f32 v23, v23, s9, v244
	v_exp_f32_e32 v25, v20
	v_med3_f32 v21, v21, s9, v244
	v_mul_f32_e32 v19, 0xbfb8aa3b, v19
	v_mul_f32_e32 v22, 0xbfb8aa3b, v23
	v_med3_f32 v18, v18, s9, v244
	v_mul_f32_e32 v23, 0xbfb8aa3b, v21
	v_exp_f32_e32 v20, v19
	v_exp_f32_e32 v21, v22
	v_add_f32_e32 v22, 1.0, v24
	v_mul_f32_e32 v18, 0xbfb8aa3b, v18
	v_rcp_f32_e32 v106, v22
	v_exp_f32_e32 v18, v18
	v_exp_f32_e32 v19, v23
	v_add_f32_e32 v23, 1.0, v25
	v_rcp_f32_e32 v107, v23
	v_add_f32_e32 v23, 1.0, v20
	v_rcp_f32_e32 v110, v23
	v_fma_f32 v23, v80, v106, v149
	v_add_f32_e32 v72, 1.0, v18
	v_add_f32_e32 v73, 1.0, v21
	v_mul_f32_e32 v23, v95, v23
	v_rcp_f32_e32 v22, v72
	v_rcp_f32_e32 v111, v73
	v_fma_f32 v72, v80, v107, v149
	v_max_f32_e32 v23, 0xda24260, v23
	v_rcp_f32_e32 v120, v23
	v_mul_f32_e32 v65, v23, v65
	v_mul_f32_e32 v23, v23, v72
	v_fma_f32 v88, v80, v110, v149
	v_max_f32_e32 v23, 0xda24260, v23
	v_bfe_u32 v72, v65, 16, 1
	v_rcp_f32_e32 v121, v23
	v_mul_f32_e32 v63, v23, v63
	v_mul_f32_e32 v23, v23, v88
	v_fma_f32 v95, v80, v111, v149
	v_add3_u32 v143, v65, v72, s10
	v_bfe_u32 v65, v63, 16, 1
	v_max_f32_e32 v23, 0xda24260, v23
	v_add3_u32 v146, v63, v65, s10
	v_rcp_f32_e32 v126, v23
	v_mul_f32_e32 v63, v23, v68
	v_mul_f32_e32 v23, v23, v95
	v_fma_f32 v73, v80, v22, v149
	v_bfe_u32 v65, v63, 16, 1
	v_max_f32_e32 v23, 0xda24260, v23
	v_add3_u32 v95, v63, v65, s10
	v_rcp_f32_e32 v127, v23
	v_mul_f32_e32 v63, v23, v71
	v_mul_f32_e32 v23, v23, v73
	v_bfe_u32 v65, v63, 16, 1
	v_max_f32_e32 v68, 0xda24260, v23
	v_add3_u32 v147, v63, v65, s10
	v_mul_f32_e32 v63, v68, v69
	v_bfe_u32 v65, v63, 16, 1
	v_add3_u32 v150, v63, v65, s10
	v_lshlrev_b32_e32 v65, 16, v231
	v_max_f32_e32 v65, v65, v65
	v_med3_f32 v65, v65, s9, v244
	v_add_f32_e32 v23, 1.0, v19
	v_mul_f32_e32 v65, 0xbfb8aa3b, v65
	v_rcp_f32_e32 v23, v23
	v_exp_f32_e32 v136, v65
	s_waitcnt vmcnt(0)
	v_lshlrev_b32_e32 v62, 16, v233
	v_max_f32_e32 v62, v62, v62
	v_fma_f32 v63, v80, v23, v149
	v_add_f32_e32 v65, 1.0, v136
	v_med3_f32 v62, v62, s9, v244
	v_mul_f32_e32 v63, v68, v63
	v_rcp_f32_e32 v138, v65
	v_mul_f32_e32 v62, 0xbfb8aa3b, v62
	v_max_f32_e32 v63, 0xda24260, v63
	v_lshlrev_b32_e32 v64, 16, v228
	v_exp_f32_e32 v137, v62
	v_mul_f32_e32 v64, v63, v64
	v_bfe_u32 v65, v64, 16, 1
	v_add3_u32 v151, v64, v65, s10
	v_fma_f32 v64, v80, v138, v149
	v_rcp_f32_e32 v131, v63
	v_mul_f32_e32 v63, v63, v64
	v_add_f32_e32 v64, 1.0, v137
	v_max_f32_e32 v62, 0xda24260, v63
	v_lshlrev_b32_e32 v63, 16, v230
	v_rcp_f32_e32 v139, v64
	v_mul_f32_e32 v63, v62, v63
	v_bfe_u32 v64, v63, 16, 1
	v_add3_u32 v152, v63, v64, s10
	v_fma_f32 v63, v80, v139, v149
	v_rcp_f32_e32 v140, v62
	v_mul_f32_e32 v62, v62, v63
	v_max_f32_e32 v88, 0xda24260, v62
	v_lshlrev_b32_e32 v62, 16, v232
	v_mul_f32_e32 v62, v88, v62
	v_bfe_u32 v63, v62, 16, 1
	v_add3_u32 v153, v62, v63, s10
	v_pk_mul_f32 v[62:63], v[88:89], v[86:87] op_sel_hi:[0,1]
	v_pk_mul_f32 v[64:65], v[88:89], v[84:85] op_sel_hi:[0,1]
	v_rcp_f32_e32 v130, v68
	v_cvt_pk_bf16_f32 v62, v62, v63
	v_cvt_pk_bf16_f32 v63, v64, v65
	v_pk_mul_f32 v[64:65], v[88:89], v[74:75] op_sel_hi:[0,1]
	v_pk_mul_f32 v[68:69], v[88:89], v[144:145] op_sel_hi:[0,1]
	v_cvt_pk_bf16_f32 v64, v64, v65
	v_cvt_pk_bf16_f32 v65, v68, v69
	v_pk_mul_f32 v[68:69], v[88:89], v[104:105] op_sel_hi:[0,1]
	v_pk_mul_f32 v[70:71], v[88:89], v[116:117] op_sel_hi:[0,1]
	v_and_b32_e32 v73, 0xffff0000, v67
	v_and_b32_e32 v72, 0xffff0000, v142
	v_cvt_pk_bf16_f32 v68, v68, v69
	v_cvt_pk_bf16_f32 v69, v70, v71
	v_pk_mul_f32 v[70:71], v[88:89], v[128:129] op_sel_hi:[0,1]
	v_pk_mul_f32 v[72:73], v[88:89], v[72:73] op_sel_hi:[0,1]
	v_cvt_pk_bf16_f32 v70, v70, v71
	v_cvt_pk_bf16_f32 v71, v72, v73
	v_pk_mul_f32 v[72:73], v[102:103], v[114:115]
	v_rcp_f32_e32 v141, v88
	v_pk_mul_f32 v[72:73], v[80:81], v[72:73] op_sel_hi:[0,1]
	v_pk_mul_f32 v[72:73], v[72:73], v[134:135]
	s_nop 0
	v_and_b32_sdwa v67, v73, v239 dst_sel:DWORD dst_unused:UNUSED_PAD src0_sel:WORD_1 src1_sel:DWORD
	v_and_b32_sdwa v74, v72, v239 dst_sel:DWORD dst_unused:UNUSED_PAD src0_sel:WORD_1 src1_sel:DWORD
	v_add3_u32 v67, v73, v67, s10
	v_add3_u32 v72, v72, v74, s10
	v_pk_mul_f32 v[74:75], v[78:79], v[108:109]
	ds_write_b16_d16_hi v17, v72 offset:6912
	ds_write_b16_d16_hi v17, v67 offset:7056
	v_and_b32_e32 v73, 0xffff0000, v67
	v_and_b32_e32 v72, 0xffff0000, v72
	v_pk_mul_f32 v[74:75], v[80:81], v[74:75] op_sel_hi:[0,1]
	v_pk_mul_f32 v[72:73], v[88:89], v[72:73] op_sel_hi:[0,1]
	v_pk_mul_f32 v[74:75], v[74:75], v[132:133]
	v_cvt_pk_bf16_f32 v72, v72, v73
	v_and_b32_sdwa v67, v75, v239 dst_sel:DWORD dst_unused:UNUSED_PAD src0_sel:WORD_1 src1_sel:DWORD
	v_and_b32_sdwa v73, v74, v239 dst_sel:DWORD dst_unused:UNUSED_PAD src0_sel:WORD_1 src1_sel:DWORD
	v_add3_u32 v67, v75, v67, s10
	v_add3_u32 v73, v74, v73, s10
	v_and_b32_e32 v75, 0xffff0000, v67
	v_and_b32_e32 v74, 0xffff0000, v73
	v_pk_mul_f32 v[74:75], v[88:89], v[74:75] op_sel_hi:[0,1]
	ds_write_b16_d16_hi v17, v73 offset:7200
	ds_write_b16_d16_hi v17, v67 offset:7344
	v_cvt_pk_bf16_f32 v73, v74, v75
	v_pk_mul_f32 v[74:75], v[76:77], v[82:83]
	s_nop 0
	v_pk_mul_f32 v[74:75], v[80:81], v[74:75] op_sel_hi:[0,1]
	v_pk_mul_f32 v[74:75], v[74:75], v[122:123]
	s_nop 0
	v_and_b32_sdwa v67, v75, v239 dst_sel:DWORD dst_unused:UNUSED_PAD src0_sel:WORD_1 src1_sel:DWORD
	v_and_b32_sdwa v76, v74, v239 dst_sel:DWORD dst_unused:UNUSED_PAD src0_sel:WORD_1 src1_sel:DWORD
	v_add3_u32 v67, v75, v67, s10
	v_add3_u32 v74, v74, v76, s10
	v_pk_mul_f32 v[76:77], v[112:113], v[118:119]
	ds_write_b16_d16_hi v17, v74 offset:7488
	ds_write_b16_d16_hi v17, v67 offset:7632
	v_and_b32_e32 v75, 0xffff0000, v67
	v_and_b32_e32 v74, 0xffff0000, v74
	v_pk_mul_f32 v[76:77], v[80:81], v[76:77] op_sel_hi:[0,1]
	v_pk_mul_f32 v[74:75], v[88:89], v[74:75] op_sel_hi:[0,1]
	v_pk_mul_f32 v[76:77], v[76:77], v[124:125]
	v_cvt_pk_bf16_f32 v74, v74, v75
	v_and_b32_sdwa v75, v76, v239 dst_sel:DWORD dst_unused:UNUSED_PAD src0_sel:WORD_1 src1_sel:DWORD
	v_and_b32_sdwa v67, v77, v239 dst_sel:DWORD dst_unused:UNUSED_PAD src0_sel:WORD_1 src1_sel:DWORD
	v_add3_u32 v75, v76, v75, s10
	v_add3_u32 v67, v77, v67, s10
	ds_write_b16_d16_hi v17, v75 offset:7776
	ds_write_b16_d16_hi v17, v67 offset:7920
	v_pk_mul_f32 v[24:25], v[24:25], v[106:107]
	v_and_b32_e32 v77, 0xffff0000, v67
	v_and_b32_e32 v76, 0xffff0000, v75
	v_pk_mul_f32 v[24:25], v[80:81], v[24:25] op_sel_hi:[0,1]
	v_pk_mul_f32 v[76:77], v[88:89], v[76:77] op_sel_hi:[0,1]
	v_pk_mul_f32 v[24:25], v[24:25], v[120:121]
	v_cvt_pk_bf16_f32 v75, v76, v77
	v_and_b32_sdwa v67, v25, v239 dst_sel:DWORD dst_unused:UNUSED_PAD src0_sel:WORD_1 src1_sel:DWORD
	v_and_b32_sdwa v76, v24, v239 dst_sel:DWORD dst_unused:UNUSED_PAD src0_sel:WORD_1 src1_sel:DWORD
	v_add3_u32 v25, v25, v67, s10
	v_add3_u32 v24, v24, v76, s10
	v_pk_mul_f32 v[20:21], v[20:21], v[110:111]
	ds_write_b16_d16_hi v17, v143 offset:3456
	ds_write_b16_d16_hi v17, v146 offset:3600
	ds_write_b16_d16_hi v17, v95 offset:3744
	ds_write_b16_d16_hi v17, v147 offset:3888
	ds_write_b16_d16_hi v17, v150 offset:4032
	ds_write_b16_d16_hi v17, v151 offset:4176
	ds_write_b16_d16_hi v17, v152 offset:4320
	ds_write_b16_d16_hi v17, v153 offset:4464
	ds_write_b16_d16_hi v17, v24 offset:8064
	ds_write_b16_d16_hi v17, v25 offset:8208
	v_and_b32_e32 v25, 0xffff0000, v25
	v_and_b32_e32 v24, 0xffff0000, v24
	v_pk_mul_f32 v[20:21], v[80:81], v[20:21] op_sel_hi:[0,1]
	v_pk_mul_f32 v[24:25], v[88:89], v[24:25] op_sel_hi:[0,1]
	v_pk_mul_f32 v[20:21], v[20:21], v[126:127]
	v_cvt_pk_bf16_f32 v76, v24, v25
	v_and_b32_sdwa v24, v21, v239 dst_sel:DWORD dst_unused:UNUSED_PAD src0_sel:WORD_1 src1_sel:DWORD
	v_and_b32_sdwa v25, v20, v239 dst_sel:DWORD dst_unused:UNUSED_PAD src0_sel:WORD_1 src1_sel:DWORD
	v_add3_u32 v21, v21, v24, s10
	v_add3_u32 v20, v20, v25, s10
	v_pk_mul_f32 v[18:19], v[18:19], v[22:23]
	ds_write_b16_d16_hi v17, v20 offset:8352
	ds_write_b16_d16_hi v17, v21 offset:8496
	v_and_b32_e32 v21, 0xffff0000, v21
	v_and_b32_e32 v20, 0xffff0000, v20
	v_pk_mul_f32 v[18:19], v[80:81], v[18:19] op_sel_hi:[0,1]
	v_pk_mul_f32 v[20:21], v[88:89], v[20:21] op_sel_hi:[0,1]
	v_pk_mul_f32 v[18:19], v[18:19], v[130:131]
	v_cvt_pk_bf16_f32 v77, v20, v21
	v_and_b32_sdwa v20, v19, v239 dst_sel:DWORD dst_unused:UNUSED_PAD src0_sel:WORD_1 src1_sel:DWORD
	v_and_b32_sdwa v21, v18, v239 dst_sel:DWORD dst_unused:UNUSED_PAD src0_sel:WORD_1 src1_sel:DWORD
	v_add3_u32 v19, v19, v20, s10
	v_add3_u32 v18, v18, v21, s10
	ds_write_b16_d16_hi v17, v18 offset:8640
	ds_write_b16_d16_hi v17, v19 offset:8784
	v_and_b32_e32 v19, 0xffff0000, v19
	v_and_b32_e32 v18, 0xffff0000, v18
	v_pk_mul_f32 v[18:19], v[88:89], v[18:19] op_sel_hi:[0,1]
	v_cvt_pk_bf16_f32 v78, v18, v19
	v_pk_mul_f32 v[18:19], v[136:137], v[138:139]
	s_nop 0
	v_pk_mul_f32 v[18:19], v[80:81], v[18:19] op_sel_hi:[0,1]
	v_pk_mul_f32 v[18:19], v[18:19], v[140:141]
	s_nop 0
	v_and_b32_sdwa v21, v18, v239 dst_sel:DWORD dst_unused:UNUSED_PAD src0_sel:WORD_1 src1_sel:DWORD
	v_and_b32_sdwa v20, v19, v239 dst_sel:DWORD dst_unused:UNUSED_PAD src0_sel:WORD_1 src1_sel:DWORD
	v_add3_u32 v18, v18, v21, s10
	v_add3_u32 v19, v19, v20, s10
	ds_write_b16_d16_hi v17, v18 offset:8928
	ds_write_b16_d16_hi v17, v19 offset:9072
	v_and_b32_e32 v19, 0xffff0000, v19
	v_and_b32_e32 v18, 0xffff0000, v18
	v_pk_mul_f32 v[18:19], v[88:89], v[18:19] op_sel_hi:[0,1]
	v_cvt_pk_bf16_f32 v79, v18, v19
	v_lshl_add_u32 v16, v16, 2, v92
	ds_write_b128 v66, v[62:65] offset:9216
	ds_write_b128 v66, v[68:71] offset:9232
	ds_write_b128 v66, v[72:75] offset:9248
	ds_write_b128 v66, v[76:79] offset:9264
	ds_write_b32 v16, v88 offset:19456
	ds_write_b128 v66, v[12:15] offset:14336
	ds_write_b128 v66, v[8:11] offset:14352
	ds_write_b128 v66, v[4:7] offset:14368
	ds_write_b128 v66, v[0:3] offset:14384
	s_waitcnt lgkmcnt(0)
	s_movk_i32 s17, 0x90
	v_mad_u32_u24 v72, v35, s17, v92
	v_lshlrev_b32_e32 v73, 4, v81
	v_add_u32_e32 v66, v72, v73
	ds_read_b128 v[0:3], v66 offset:4608
	ds_read_b128 v[4:7], v66
	ds_read_b128 v[18:21], v66 offset:32
	ds_read_b128 v[22:25], v66 offset:4640
	ds_read_b128 v[62:65], v66 offset:4672
	s_waitcnt lgkmcnt(3)
	v_mfma_f32_32x32x16_bf16 v[2:17], v[0:3], v[4:7], 0
	v_lshlrev_b32_e32 v70, 2, v81
	v_cmp_le_i32_e32 vcc, v70, v35
	v_or_b32_e32 v74, 2, v70
	v_or_b32_e32 v75, 3, v70
	v_or_b32_e32 v88, v93, v35
	v_add_u32_e32 v76, 8, v70
	v_lshlrev_b64 v[0:1], 11, v[88:89]
	s_waitcnt lgkmcnt(1)
	v_mfma_f32_32x32x16_bf16 v[2:17], v[22:25], v[18:21], v[2:17]
	ds_read_b128 v[18:21], v66 offset:64
	ds_read_b128 v[22:25], v66 offset:4704
	ds_read_b128 v[66:69], v66 offset:96
	v_lshl_add_u64 v[0:1], s[2:3], 0, v[0:1]
	v_ashrrev_i32_e32 v71, 31, v70
	v_lshl_add_u64 v[0:1], v[0:1], 0, v[90:91]
	v_lshl_add_u64 v[84:85], v[70:71], 1, v[0:1]
	v_add_u32_e32 v0, 16, v70
	s_waitcnt lgkmcnt(2)
	v_mfma_f32_32x32x16_bf16 v[2:17], v[62:65], v[18:21], v[2:17]
	v_add_u32_e32 v18, 9, v70
	v_add_u32_e32 v19, 10, v70
	v_add_u32_e32 v20, 11, v70
	v_lshlrev_b32_e32 v138, 16, v42
	v_and_b32_e32 v139, 0xffff0000, v42
	v_lshlrev_b32_e32 v42, 16, v43
	v_and_b32_e32 v43, 0xffff0000, v43
	s_waitcnt lgkmcnt(0)
	v_mfma_f32_32x32x16_bf16 v[2:17], v[22:25], v[66:69], v[2:17]
	v_lshlrev_b32_e32 v140, 16, v36
	v_and_b32_e32 v141, 0xffff0000, v36
	v_lshlrev_b32_e32 v142, 16, v37
	v_and_b32_e32 v143, 0xffff0000, v37
	v_cvt_pk_bf16_f32 v130, v138, v139
	v_cvt_pk_bf16_f32 v131, v42, v43
	v_cvt_pk_bf16_f32 v132, v140, v141
	s_nop 4
	v_cndmask_b32_e32 v21, 0, v2, vcc
	v_cmp_lt_i32_e32 vcc, v70, v35
	v_cvt_pk_bf16_f32 v133, v142, v143
	v_add_u32_e32 v95, v92, v73
	v_cndmask_b32_e32 v22, 0, v3, vcc
	v_cmp_le_i32_e32 vcc, v74, v35
	v_lshlrev_b32_e32 v74, 3, v81
	v_add_u32_e32 v88, v72, v74
	v_cndmask_b32_e32 v4, 0, v4, vcc
	v_cmp_le_i32_e32 vcc, v75, v35
	v_mad_u32_u24 v144, v35, s16, v95
	v_cvt_pk_bf16_f32 v36, v44, v45
	v_cndmask_b32_e32 v5, 0, v5, vcc
	v_cmp_le_i32_e32 vcc, v76, v35
	v_cvt_pk_bf16_f32 v37, v46, v47
	v_lshlrev_b32_e32 v78, 16, v60
	v_cndmask_b32_e32 v6, 0, v6, vcc
	v_cmp_le_i32_e32 vcc, v18, v35
	v_cvt_pk_bf16_f32 v18, v21, v22
	v_and_b32_e32 v79, 0xffff0000, v60
	v_cndmask_b32_e32 v7, 0, v7, vcc
	v_cmp_le_i32_e32 vcc, v19, v35
	v_cvt_pk_bf16_f32 v19, v4, v5
	v_lshlrev_b32_e32 v82, 16, v61
	v_cndmask_b32_e32 v8, 0, v8, vcc
	v_cmp_le_i32_e32 vcc, v20, v35
	v_cvt_pk_bf16_f32 v20, v6, v7
	v_and_b32_e32 v83, 0xffff0000, v61
	v_cndmask_b32_e32 v9, 0, v9, vcc
	v_cmp_le_i32_e32 vcc, v0, v35
	v_add_u32_e32 v0, 17, v70
	v_cvt_pk_bf16_f32 v21, v8, v9
	v_cndmask_b32_e32 v23, 0, v10, vcc
	v_cmp_le_i32_e32 vcc, v0, v35
	v_add_u32_e32 v0, 18, v70
	v_add_u32_e32 v10, 26, v70
	v_cndmask_b32_e32 v24, 0, v11, vcc
	v_cmp_le_i32_e32 vcc, v0, v35
	v_add_u32_e32 v0, 19, v70
	v_cvt_pk_bf16_f32 v22, v23, v24
	v_cndmask_b32_e32 v25, 0, v12, vcc
	v_cmp_le_i32_e32 vcc, v0, v35
	v_add_u32_e32 v0, 24, v70
	v_lshlrev_b32_e32 v60, 16, v58
	v_cndmask_b32_e32 v68, 0, v13, vcc
	v_cmp_le_i32_e32 vcc, v0, v35
	v_add_u32_e32 v0, 25, v70
	v_add_u32_e32 v70, 27, v70
	v_cndmask_b32_e32 v69, 0, v14, vcc
	v_cmp_le_i32_e32 vcc, v0, v35
	v_mul_u32_u24_e32 v0, 0x50, v35
	v_add3_u32 v81, v92, v74, v0
	v_add_u32_e32 v11, 0x3800, v81
	ds_read2_b64 v[0:3], v11 offset1:2
	ds_read2_b64 v[64:67], v11 offset0:4 offset1:6
	v_cndmask_b32_e32 v71, 0, v15, vcc
	v_cmp_le_i32_e32 vcc, v10, v35
	s_waitcnt lgkmcnt(1)
	v_mfma_f32_32x32x16_bf16 v[0:15], v[0:3], v[18:21], 0
	v_cndmask_b32_e32 v16, 0, v16, vcc
	v_cmp_le_i32_e32 vcc, v70, v35
	v_cvt_pk_bf16_f32 v23, v25, v68
	v_cvt_pk_bf16_f32 v24, v69, v71
	v_cndmask_b32_e32 v17, 0, v17, vcc
	v_cvt_pk_bf16_f32 v25, v16, v17
	ds_read2_b64 v[106:109], v88 offset1:2
	ds_read2_b64 v[110:113], v88 offset0:4 offset1:6
	ds_read2_b64 v[114:117], v88 offset0:8 offset1:10
	ds_read2_b64 v[118:121], v88 offset0:12 offset1:14
	s_waitcnt lgkmcnt(4)
	v_mfma_f32_32x32x16_bf16 v[0:15], v[64:67], v[22:25], v[0:15]
	v_cvt_pk_bf16_f32 v35, v40, v41
	v_and_b32_e32 v61, 0xffff0000, v58
	v_lshlrev_b32_e32 v58, 16, v59
	v_and_b32_e32 v59, 0xffff0000, v59
	v_cvt_pk_bf16_f32 v122, v78, v79
	v_cvt_pk_bf16_f32 v123, v82, v83
	v_cvt_pk_bf16_f32 v124, v60, v61
	s_waitcnt lgkmcnt(3)
	v_mfma_f32_32x32x16_bf16 v[0:15], v[130:133], v[106:109], v[0:15]
	v_lshlrev_b32_e32 v106, 16, v34
	v_and_b32_e32 v107, 0xffff0000, v34
	v_cvt_pk_bf16_f32 v34, v106, v107
	v_cvt_pk_bf16_f32 v125, v58, v59
	v_lshlrev_b32_e32 v86, 16, v56
	v_and_b32_e32 v87, 0xffff0000, v56
	v_lshlrev_b32_e32 v56, 16, v57
	s_waitcnt lgkmcnt(2)
	v_mfma_f32_32x32x16_bf16 v[0:15], v[34:37], v[110:113], v[0:15]
	v_and_b32_e32 v57, 0xffff0000, v57
	v_lshlrev_b32_e32 v102, 16, v54
	v_and_b32_e32 v103, 0xffff0000, v54
	v_lshlrev_b32_e32 v104, 16, v55
	v_and_b32_e32 v105, 0xffff0000, v55
	v_cvt_pk_bf16_f32 v126, v86, v87
	v_cvt_pk_bf16_f32 v127, v56, v57
	s_waitcnt lgkmcnt(1)
	v_mfma_f32_32x32x16_bf16 v[0:15], v[122:125], v[114:117], v[0:15]
	v_cvt_pk_bf16_f32 v128, v102, v103
	v_cvt_pk_bf16_f32 v129, v104, v105
	s_mov_b64 s[2:3], 0x16f00600
	v_lshl_add_u64 v[62:63], v[84:85], 0, s[2:3]
	s_mov_b32 s2, 0x16f00000
	v_lshlrev_b32_e32 v16, 16, v26
	v_and_b32_e32 v17, 0xffff0000, v26
	s_waitcnt lgkmcnt(0)
	v_mfma_f32_32x32x16_bf16 v[0:15], v[126:129], v[118:121], v[0:15]
	v_lshlrev_b32_e32 v64, 16, v27
	v_and_b32_e32 v65, 0xffff0000, v27
	v_lshlrev_b32_e32 v66, 16, v28
	v_and_b32_e32 v67, 0xffff0000, v28
	v_lshlrev_b32_e32 v68, 16, v29
	v_and_b32_e32 v69, 0xffff0000, v29
	v_lshlrev_b32_e32 v70, 16, v30
	s_nop 4
	v_cvt_pk_bf16_f32 v0, v0, v1
	v_cvt_pk_bf16_f32 v1, v2, v3
	v_add_co_u32_e32 v2, vcc, s2, v84
	v_and_b32_e32 v71, 0xffff0000, v30
	s_nop 0
	v_addc_co_u32_e32 v3, vcc, 0, v85, vcc
	global_store_dwordx2 v[2:3], v[0:1], off offset:1536
	v_cvt_pk_bf16_f32 v0, v4, v5
	v_cvt_pk_bf16_f32 v1, v6, v7
	global_store_dwordx2 v[62:63], v[0:1], off offset:16
	v_cvt_pk_bf16_f32 v0, v8, v9
	v_cvt_pk_bf16_f32 v1, v10, v11
	v_lshlrev_b32_e32 v72, 16, v31
	v_and_b32_e32 v73, 0xffff0000, v31
	v_lshlrev_b32_e32 v74, 16, v32
	v_and_b32_e32 v75, 0xffff0000, v32
	v_lshlrev_b32_e32 v76, 16, v33
	v_and_b32_e32 v77, 0xffff0000, v33
	v_lshlrev_b32_e32 v54, 16, v52
	v_and_b32_e32 v55, 0xffff0000, v52
	v_lshlrev_b32_e32 v52, 16, v53
	v_and_b32_e32 v53, 0xffff0000, v53
	v_lshlrev_b32_e32 v130, 16, v50
	v_and_b32_e32 v131, 0xffff0000, v50
	v_lshlrev_b32_e32 v50, 16, v51
	v_and_b32_e32 v51, 0xffff0000, v51
	v_lshlrev_b32_e32 v132, 16, v48
	v_and_b32_e32 v133, 0xffff0000, v48
	v_lshlrev_b32_e32 v48, 16, v49
	v_and_b32_e32 v49, 0xffff0000, v49
	v_lshlrev_b32_e32 v114, 16, v38
	v_and_b32_e32 v115, 0xffff0000, v38
	v_lshlrev_b32_e32 v116, 16, v39
	v_and_b32_e32 v117, 0xffff0000, v39
	global_store_dwordx2 v[62:63], v[0:1], off offset:32
	v_cvt_pk_bf16_f32 v0, v12, v13
	v_cvt_pk_bf16_f32 v1, v14, v15
	v_cvt_pk_bf16_f32 v26, v16, v17
	v_cvt_pk_bf16_f32 v27, v64, v65
	v_cvt_pk_bf16_f32 v28, v66, v67
	v_cvt_pk_bf16_f32 v29, v68, v69
	v_cvt_pk_bf16_f32 v30, v70, v71
	v_cvt_pk_bf16_f32 v31, v72, v73
	v_cvt_pk_bf16_f32 v32, v74, v75
	v_cvt_pk_bf16_f32 v33, v76, v77
	v_cvt_pk_bf16_f32 v134, v54, v55
	v_cvt_pk_bf16_f32 v135, v52, v53
	v_cvt_pk_bf16_f32 v136, v130, v131
	v_cvt_pk_bf16_f32 v137, v50, v51
	v_cvt_pk_bf16_f32 v34, v132, v133
	v_cvt_pk_bf16_f32 v35, v48, v49
	v_cvt_pk_bf16_f32 v36, v114, v115
	v_cvt_pk_bf16_f32 v37, v116, v117
	global_store_dwordx2 v[62:63], v[0:1], off offset:48
	v_add_u32_e32 v38, 0x4000, v81
	ds_read2_b64 v[0:3], v38 offset0:64 offset1:66
	s_waitcnt lgkmcnt(0)
	v_mfma_f32_32x32x16_bf16 v[0:15], v[0:3], v[18:21], 0
	ds_read2_b64 v[18:21], v38 offset0:68 offset1:70
	s_waitcnt lgkmcnt(0)
	v_mfma_f32_32x32x16_bf16 v[0:15], v[18:21], v[22:25], v[0:15]
	ds_read2_b64 v[18:21], v88 offset1:2
	s_waitcnt lgkmcnt(0)
	v_mfma_f32_32x32x16_bf16 v[0:15], v[134:137], v[18:21], v[0:15]
	ds_read2_b64 v[18:21], v88 offset0:4 offset1:6
	s_waitcnt lgkmcnt(0)
	v_mfma_f32_32x32x16_bf16 v[0:15], v[34:37], v[18:21], v[0:15]
	ds_read2_b64 v[18:21], v88 offset0:8 offset1:10
	s_waitcnt lgkmcnt(0)
	v_mfma_f32_32x32x16_bf16 v[0:15], v[26:29], v[18:21], v[0:15]
	ds_read2_b64 v[18:21], v88 offset0:12 offset1:14
	s_waitcnt lgkmcnt(0)
	v_mfma_f32_32x32x16_bf16 v[0:15], v[30:33], v[18:21], v[0:15]
	s_nop 11
	v_cvt_pk_bf16_f32 v0, v0, v1
	v_cvt_pk_bf16_f32 v1, v2, v3
	v_cvt_pk_bf16_f32 v2, v4, v5
	v_cvt_pk_bf16_f32 v3, v6, v7
	v_cvt_pk_bf16_f32 v4, v8, v9
	v_cvt_pk_bf16_f32 v5, v10, v11
	v_cvt_pk_bf16_f32 v6, v12, v13
	v_cvt_pk_bf16_f32 v7, v14, v15
	global_store_dwordx2 v[62:63], v[0:1], off offset:64
	global_store_dwordx2 v[62:63], v[2:3], off offset:80
	global_store_dwordx2 v[62:63], v[4:5], off offset:96
	global_store_dwordx2 v[62:63], v[6:7], off offset:112
	ds_read_b128 v[0:3], v95 offset:19456
	ds_read_b128 v[4:7], v95 offset:19488
	ds_read_b128 v[8:11], v95 offset:19520
	ds_read_b128 v[12:15], v95 offset:19552
	ds_read_b128 v[18:21], v144 offset:9216
	s_waitcnt lgkmcnt(4)
	v_pk_mul_f32 v[34:35], v[2:3], v[42:43]
	ds_read_b128 v[22:25], v144 offset:14336
	s_waitcnt lgkmcnt(3)
	v_pk_mul_f32 v[42:43], v[10:11], v[40:41]
	v_pk_mul_f32 v[40:41], v[8:9], v[106:107]
	ds_read_b128 v[26:29], v144 offset:9248
	ds_read_b128 v[106:109], v144 offset:14368
	ds_read_b128 v[110:113], v144 offset:16896
	v_pk_mul_f32 v[32:33], v[0:1], v[138:139]
	v_pk_mul_f32 v[38:39], v[6:7], v[142:143]
	v_pk_mul_f32 v[36:37], v[4:5], v[140:141]
	s_waitcnt lgkmcnt(5)
	v_pk_mul_f32 v[46:47], v[14:15], v[46:47]
	v_pk_mul_f32 v[44:45], v[12:13], v[44:45]
	v_pk_mul_f32 v[0:1], v[0:1], v[54:55]
	v_pk_mul_f32 v[2:3], v[2:3], v[52:53]
	v_pk_mul_f32 v[4:5], v[4:5], v[130:131]
	v_pk_mul_f32 v[6:7], v[6:7], v[50:51]
	v_pk_mul_f32 v[8:9], v[8:9], v[132:133]
	v_pk_mul_f32 v[10:11], v[10:11], v[48:49]
	v_pk_mul_f32 v[12:13], v[12:13], v[114:115]
	v_pk_mul_f32 v[14:15], v[14:15], v[116:117]
	s_waitcnt lgkmcnt(3)
	v_mfma_f32_32x32x16_bf16 v[32:47], v[18:21], v[22:25], v[32:47]
	ds_read_b128 v[114:117], v144 offset:16928
	s_waitcnt lgkmcnt(1)
	v_mfma_f32_32x32x16_bf16 v[0:15], v[18:21], v[110:113], v[0:15]
	v_mfma_f32_32x32x16_bf16 v[32:47], v[26:29], v[106:109], v[32:47]
	s_waitcnt lgkmcnt(0)
	v_mfma_f32_32x32x16_bf16 v[0:15], v[26:29], v[114:117], v[0:15]
	ds_read_b128 v[18:21], v95 offset:19584
	ds_read_b128 v[26:29], v95 offset:19616
	ds_read_b128 v[118:121], v95 offset:19648
	ds_read_b128 v[122:125], v95 offset:19680
	ds_read_b128 v[126:129], v144 offset:11776
	s_waitcnt lgkmcnt(4)
	v_pk_mul_f32 v[50:51], v[20:21], v[82:83]
	v_pk_mul_f32 v[48:49], v[18:19], v[78:79]
	s_waitcnt lgkmcnt(3)
	v_pk_mul_f32 v[54:55], v[28:29], v[58:59]
	v_pk_mul_f32 v[52:53], v[26:27], v[60:61]
	s_waitcnt lgkmcnt(2)
	v_pk_mul_f32 v[58:59], v[120:121], v[56:57]
	v_pk_mul_f32 v[56:57], v[118:119], v[86:87]
	s_waitcnt lgkmcnt(1)
	v_pk_mul_f32 v[62:63], v[124:125], v[104:105]
	v_pk_mul_f32 v[60:61], v[122:123], v[102:103]
	ds_read_b128 v[82:85], v144 offset:11808
	v_pk_mul_f32 v[16:17], v[18:19], v[16:17]
	s_waitcnt lgkmcnt(1)
	v_mfma_f32_32x32x16_bf16 v[48:63], v[126:129], v[22:25], v[48:63]
	v_mul_f32_e64 v18, v20, v64
	v_mul_f32_e64 v19, v21, v65
	v_mul_f32_e64 v20, v26, v66
	v_mul_f32_e64 v21, v27, v67
	v_mul_f32_e64 v22, v28, v68
	v_mul_f32_e64 v23, v29, v69
	v_pk_mul_f32 v[24:25], v[118:119], v[70:71]
	v_pk_mul_f32 v[26:27], v[120:121], v[72:73]
	v_pk_mul_f32 v[28:29], v[122:123], v[74:75]
	v_pk_mul_f32 v[30:31], v[124:125], v[76:77]
	s_waitcnt lgkmcnt(0)
	s_waitcnt lgkmcnt(0)
	v_mfma_f32_32x32x16_bf16 v[48:63], v[82:85], v[106:109], v[48:63]
	v_mfma_f32_32x32x16_bf16 v[16:31], v[126:129], v[110:113], v[16:31]
	v_mfma_f32_32x32x16_bf16 v[16:31], v[82:85], v[114:117], v[16:31]
	v_mov_b32_e32 v82, v94
	s_mov_b64 s[16:17], s[44:45]
	v_or_b32_e32 v95, 32, v93
	v_and_b32_e32 v124, 31, v82
	v_ashrrev_i32_e32 v125, 5, v82
	v_mov_b64_e32 v[64:65], s[16:17]
	s_movk_i32 s2, 0x1200
	v_mad_i64_i32 v[64:65], s[2:3], v95, s2, v[64:65]
	v_ashrrev_i32_e32 v83, 31, v82
	v_lshl_add_u64 v[64:65], v[64:65], 0, v[90:91]
	v_lshl_add_u64 v[64:65], v[82:83], 1, v[64:65]
	v_lshl_add_u64 v[114:115], v[64:65], 0, s[0:1]
	global_load_ushort v88, v[114:115], off offset:2560
	global_load_ushort v81, v[114:115], off offset:3072
	v_add_co_u32_e32 v112, vcc, s7, v64
	s_mov_b32 s0, 0xb20f000
	s_nop 0
	v_addc_co_u32_e32 v113, vcc, 0, v65, vcc
	global_load_ushort v126, v[112:113], off offset:3584
	v_add_co_u32_e32 v110, vcc, s11, v64
	v_lshl_add_u32 v83, v82, 1, v92
	s_nop 0
	v_addc_co_u32_e32 v111, vcc, 0, v65, vcc
	v_add_co_u32_e32 v108, vcc, s12, v64
	s_waitcnt vmcnt(1)
	v_lshlrev_b32_e32 v81, 16, v81
	v_max_f32_e32 v81, v81, v81
	v_med3_f32 v81, v81, s9, v244
	v_mul_f32_e32 v81, 0xbfb8aa3b, v81
	v_exp_f32_e32 v81, v81
	v_addc_co_u32_e32 v109, vcc, 0, v65, vcc
	v_add_co_u32_e32 v106, vcc, s13, v64
	v_add_f32_e32 v116, 1.0, v81
	v_rcp_f32_e32 v116, v116
	v_addc_co_u32_e32 v107, vcc, 0, v65, vcc
	v_add_co_u32_e32 v104, vcc, s14, v64
	v_fma_f32 v117, v80, v116, v149
	v_max_f32_e32 v183, 0xda24260, v117
	v_mul_f32_e32 v81, v81, v116
	v_rcp_f32_e32 v116, v183
	v_mul_f32_e32 v81, v80, v81
	v_addc_co_u32_e32 v105, vcc, 0, v65, vcc
	v_mul_f32_e32 v81, v81, v116
	v_bfe_u32 v116, v81, 16, 1
	v_add3_u32 v133, v81, v116, s10
	global_load_ushort v81, v[114:115], off offset:2048
	global_load_ushort v127, v[110:111], off offset:512
	global_load_ushort v128, v[108:109], off offset:1536
	global_load_ushort v129, v[106:107], off offset:2560
	global_load_ushort v130, v[104:105], off offset:3584
	v_add_co_u32_e32 v102, vcc, s15, v64
	s_waitcnt vmcnt(4)
	v_lshlrev_b32_e32 v81, 16, v81
	v_addc_co_u32_e32 v103, vcc, 0, v65, vcc
	v_add_co_u32_e32 v86, vcc, s18, v64
	global_load_ushort v131, v[102:103], off offset:512
	s_nop 0
	v_addc_co_u32_e32 v87, vcc, 0, v65, vcc
	v_add_co_u32_e32 v74, vcc, s19, v64
	global_load_ushort v132, v[86:87], off offset:1536
	s_nop 0
	v_addc_co_u32_e32 v75, vcc, 0, v65, vcc
	v_add_co_u32_e32 v78, vcc, s21, v64
	global_load_ushort v134, v[74:75], off offset:2560
	s_nop 0
	v_addc_co_u32_e32 v79, vcc, 0, v65, vcc
	v_add_co_u32_e32 v76, vcc, s30, v64
	global_load_ushort v135, v[78:79], off offset:3584
	s_nop 0
	v_addc_co_u32_e32 v77, vcc, 0, v65, vcc
	v_add_co_u32_e32 v84, vcc, s31, v64
	v_mul_f32_e32 v81, v183, v81
	s_nop 0
	v_addc_co_u32_e32 v85, vcc, 0, v65, vcc
	v_add_co_u32_e32 v66, vcc, s34, v64
	global_load_ushort v137, v[84:85], off offset:1536
	global_load_ushort v136, v[76:77], off offset:512
	v_addc_co_u32_e32 v67, vcc, 0, v65, vcc
	v_add_co_u32_e32 v72, vcc, s35, v64
	global_load_ushort v138, v[66:67], off offset:2560
	s_nop 0
	v_addc_co_u32_e32 v73, vcc, 0, v65, vcc
	v_add_co_u32_e32 v68, vcc, s36, v64
	global_load_ushort v139, v[72:73], off offset:3584
	s_nop 0
	v_addc_co_u32_e32 v69, vcc, 0, v65, vcc
	v_add_co_u32_e32 v70, vcc, s37, v64
	global_load_ushort v140, v[68:69], off offset:512
	s_nop 0
	v_addc_co_u32_e32 v71, vcc, 0, v65, vcc
	v_add_co_u32_e32 v116, vcc, s40, v64
	global_load_ushort v141, v[70:71], off offset:1536
	s_nop 0
	v_addc_co_u32_e32 v117, vcc, 0, v65, vcc
	global_load_ushort v187, v[116:117], off offset:3584
	global_load_ushort v182, v[116:117], off offset:2560
	v_bfe_u32 v114, v81, 16, 1
	v_add3_u32 v188, v81, v114, s10
	v_add_co_u32_e32 v114, vcc, s41, v64
	s_nop 1
	v_addc_co_u32_e32 v115, vcc, 0, v65, vcc
	v_add_co_u32_e32 v118, vcc, s46, v64
	s_nop 1
	v_addc_co_u32_e32 v119, vcc, 0, v65, vcc
	global_load_ushort v180, v[118:119], off offset:-4096
	global_load_ushort v176, v[112:113], off offset:3072
	global_load_ushort v175, v[118:119], off offset:512
	global_load_ushort v170, v[114:115], off offset:3584
	global_load_ushort v181, v[110:111], off offset:1024
	global_load_ushort v178, v[110:111], off
	v_add_co_u32_e32 v120, vcc, s28, v64
	s_nop 1
	v_addc_co_u32_e32 v121, vcc, 0, v65, vcc
	v_add_co_u32_e32 v122, vcc, s29, v64
	global_load_ushort v186, v[120:121], off offset:1536
	global_load_ushort v185, v[120:121], off offset:512
	global_load_ushort v184, v[108:109], off offset:2048
	global_load_ushort v179, v[108:109], off offset:1024
	v_addc_co_u32_e32 v123, vcc, 0, v65, vcc
	v_add_co_u32_e32 v190, vcc, s42, v64
	global_load_ushort v177, v[122:123], off offset:2560
	global_load_ushort v173, v[122:123], off offset:1536
	global_load_ushort v174, v[106:107], off offset:3072
	global_load_ushort v172, v[106:107], off offset:2048
	v_addc_co_u32_e32 v191, vcc, 0, v65, vcc
	v_add_co_u32_e32 v106, vcc, s6, v64
	global_load_ushort v171, v[190:191], off offset:3584
	global_load_ushort v169, v[190:191], off offset:2560
	v_addc_co_u32_e32 v107, vcc, 0, v65, vcc
	v_add_co_u32_e32 v154, vcc, s49, v64
	s_waitcnt vmcnt(4)
	v_lshlrev_b32_e32 v173, 16, v173
	v_addc_co_u32_e32 v155, vcc, 0, v65, vcc
	v_add_co_u32_e32 v192, vcc, s0, v64
	s_mov_b32 s0, 0xb211000
	s_nop 0
	v_addc_co_u32_e32 v193, vcc, 0, v65, vcc
	v_add_co_u32_e32 v194, vcc, s0, v64
	s_mov_b32 s0, 0xb21a000
	s_nop 0
	v_addc_co_u32_e32 v195, vcc, 0, v65, vcc
	v_add_co_u32_e32 v108, vcc, s43, v64
	global_load_ushort v166, v[154:155], off offset:-4096
	global_load_ushort v164, v[104:105], off offset:3072
	global_load_ushort v167, v[154:155], off offset:512
	global_load_ushort v158, v[106:107], off offset:3584
	global_load_ushort v168, v[102:103], off offset:1024
	global_load_ushort v163, v[102:103], off
	v_addc_co_u32_e32 v109, vcc, 0, v65, vcc
	v_add_co_u32_e32 v110, vcc, s47, v64
	global_load_ushort v165, v[192:193], off offset:1536
	global_load_ushort v157, v[192:193], off offset:512
	global_load_ushort v162, v[86:87], off offset:2048
	global_load_ushort v156, v[86:87], off offset:1024
	v_addc_co_u32_e32 v111, vcc, 0, v65, vcc
	v_add_co_u32_e32 v112, vcc, s48, v64
	global_load_ushort v159, v[194:195], off offset:2560
	global_load_ushort v81, v[194:195], off offset:1536
	v_addc_co_u32_e32 v113, vcc, 0, v65, vcc
	v_add_co_u32_e32 v114, vcc, s0, v64
	s_mov_b32 s0, 0xb223000
	s_nop 0
	v_addc_co_u32_e32 v115, vcc, 0, v65, vcc
	v_add_co_u32_e32 v86, vcc, s0, v64
	s_mov_b32 s0, 0xb221000
	s_nop 0
	v_addc_co_u32_e32 v87, vcc, 0, v65, vcc
	v_add_co_u32_e32 v102, vcc, s0, v64
	s_mov_b32 s0, 0xb21f000
	s_nop 0
	v_addc_co_u32_e32 v103, vcc, 0, v65, vcc
	v_add_co_u32_e32 v104, vcc, s0, v64
	global_load_ushort v142, v[86:87], off offset:2048
	global_load_ushort v143, v[102:103], off offset:1024
	global_load_ushort v145, v[68:69], off offset:-4096
	v_addc_co_u32_e32 v105, vcc, 0, v65, vcc
	v_add_co_u32_e32 v106, vcc, s97, v64
	s_nop 1
	v_addc_co_u32_e32 v107, vcc, 0, v65, vcc
	global_load_ushort v146, v[106:107], off offset:3072
	global_load_ushort v147, v[114:115], off offset:2048
	global_load_ushort v150, v[112:113], off offset:1024
	global_load_ushort v151, v[76:77], off offset:-4096
	global_load_ushort v152, v[108:109], off offset:3072
	global_load_ushort v153, v[194:195], off offset:2048
	global_load_ushort v144, v[192:193], off offset:1024
	s_nop 0
	global_load_ushort v154, v[154:155], off
	s_nop 0
	global_load_ushort v155, v[190:191], off offset:3072
	s_nop 0
	global_load_ushort v122, v[122:123], off offset:2048
	s_nop 0
	global_load_ushort v120, v[120:121], off offset:1024
	s_nop 0
	global_load_ushort v118, v[118:119], off
	s_nop 0
	global_load_ushort v121, v[116:117], off offset:3072
	s_mov_b32 s101, 0
	s_mov_b32 s100, 0xb213000
	v_lshl_add_u64 v[196:197], v[64:65], 0, s[100:101]
	global_load_ushort v200, v[196:197], off offset:-2048
	global_load_ushort v201, v[196:197], off offset:-1024
	global_load_ushort v202, v[196:197], off offset:2560
	global_load_ushort v203, v[196:197], off offset:3584
	s_mov_b32 s100, 0xb215400
	v_lshl_add_u64 v[198:199], v[64:65], 0, s[100:101]
	global_load_ushort v206, v[198:199], off offset:-2048
	global_load_ushort v207, v[198:199], off offset:-1024
	global_load_ushort v208, v[198:199], off offset:2560
	global_load_ushort v209, v[198:199], off offset:3584
	s_mov_b32 s100, 0xb217800
	v_lshl_add_u64 v[196:197], v[64:65], 0, s[100:101]
	global_load_ushort v210, v[196:197], off offset:-2048
	global_load_ushort v211, v[196:197], off offset:-1024
	global_load_ushort v212, v[196:197], off offset:2560
	global_load_ushort v213, v[196:197], off offset:3584
	s_mov_b32 s100, 0xb219c00
	v_lshl_add_u64 v[198:199], v[64:65], 0, s[100:101]
	global_load_ushort v214, v[198:199], off offset:-2048
	global_load_ushort v215, v[198:199], off offset:-1024
	global_load_ushort v216, v[198:199], off offset:2560
	global_load_ushort v217, v[198:199], off offset:3584
	s_mov_b32 s100, 0xb21c000
	v_lshl_add_u64 v[196:197], v[64:65], 0, s[100:101]
	global_load_ushort v218, v[196:197], off offset:-2048
	global_load_ushort v219, v[196:197], off offset:-1024
	global_load_ushort v220, v[196:197], off offset:2560
	global_load_ushort v221, v[196:197], off offset:3584
	s_mov_b32 s100, 0xb21e400
	v_lshl_add_u64 v[198:199], v[64:65], 0, s[100:101]
	global_load_ushort v222, v[198:199], off offset:-2048
	global_load_ushort v223, v[198:199], off offset:-1024
	global_load_ushort v224, v[198:199], off offset:2560
	global_load_ushort v225, v[198:199], off offset:3584
	s_mov_b32 s100, 0xb220800
	v_lshl_add_u64 v[196:197], v[64:65], 0, s[100:101]
	global_load_ushort v226, v[196:197], off offset:-2048
	global_load_ushort v227, v[196:197], off offset:-1024
	global_load_ushort v228, v[196:197], off offset:2560
	global_load_ushort v229, v[196:197], off offset:3584
	s_mov_b32 s100, 0xb222c00
	v_lshl_add_u64 v[198:199], v[64:65], 0, s[100:101]
	global_load_ushort v230, v[198:199], off offset:-2048
	global_load_ushort v231, v[198:199], off offset:-1024
	global_load_ushort v232, v[198:199], off offset:2560
	global_load_ushort v233, v[198:199], off offset:3584
	v_lshlrev_b32_e32 v116, 16, v187
	v_max_f32_e32 v116, v116, v116
	v_med3_f32 v116, v116, s9, v244
	v_mul_f32_e32 v116, 0xbfb8aa3b, v116
	v_exp_f32_e32 v116, v116
	ds_write_b16_d16_hi v83, v188
	ds_write_b16_d16_hi v83, v133 offset:4608
	v_add_f32_e32 v117, 1.0, v116
	v_rcp_f32_e32 v117, v117
	s_nop 0
	v_fma_f32 v119, v80, v117, v149
	v_mul_f32_e32 v116, v116, v117
	v_mul_f32_e32 v117, v183, v119
	v_max_f32_e32 v117, 0xda24260, v117
	v_rcp_f32_e32 v119, v117
	v_mul_f32_e32 v116, v80, v116
	v_mul_f32_e32 v116, v116, v119
	v_bfe_u32 v119, v116, 16, 1
	v_add3_u32 v119, v116, v119, s10
	v_lshlrev_b32_e32 v116, 16, v182
	v_mul_f32_e32 v116, v117, v116
	v_bfe_u32 v123, v116, 16, 1
	v_add3_u32 v116, v116, v123, s10
	ds_write_b16_d16_hi v83, v116 offset:144
	ds_write_b16_d16_hi v83, v119 offset:4752
	v_lshlrev_b32_e32 v116, 16, v180
	v_max_f32_e32 v116, v116, v116
	v_med3_f32 v116, v116, s9, v244
	v_mul_f32_e32 v116, 0xbfb8aa3b, v116
	v_exp_f32_e32 v116, v116
	s_nop 0
	v_add_f32_e32 v123, 1.0, v116
	v_rcp_f32_e32 v123, v123
	s_nop 0
	v_fma_f32 v180, v80, v123, v149
	v_mul_f32_e32 v117, v117, v180
	v_max_f32_e32 v117, 0xda24260, v117
	v_mul_f32_e32 v116, v116, v123
	v_rcp_f32_e32 v123, v117
	v_mul_f32_e32 v116, v80, v116
	v_mul_f32_e32 v116, v116, v123
	v_bfe_u32 v123, v116, 16, 1
	v_add3_u32 v116, v116, v123, s10
	v_lshlrev_b32_e32 v123, 16, v176
	v_mul_f32_e32 v123, v117, v123
	v_bfe_u32 v176, v123, 16, 1
	v_add3_u32 v123, v123, v176, s10
	ds_write_b16_d16_hi v83, v123 offset:288
	ds_write_b16_d16_hi v83, v116 offset:4896
	v_lshlrev_b32_e32 v123, 16, v175
	v_max_f32_e32 v123, v123, v123
	v_med3_f32 v123, v123, s9, v244
	v_mul_f32_e32 v123, 0xbfb8aa3b, v123
	v_exp_f32_e32 v123, v123
	s_nop 0
	v_add_f32_e32 v175, 1.0, v123
	v_rcp_f32_e32 v175, v175
	s_nop 0
	v_fma_f32 v176, v80, v175, v149
	v_mul_f32_e32 v117, v117, v176
	v_mul_f32_e32 v123, v123, v175
	v_max_f32_e32 v175, 0xda24260, v117
	v_rcp_f32_e32 v117, v175
	v_mul_f32_e32 v123, v80, v123
	v_mul_f32_e32 v117, v123, v117
	v_bfe_u32 v123, v117, 16, 1
	v_add3_u32 v117, v117, v123, s10
	v_lshlrev_b32_e32 v123, 16, v170
	v_mul_f32_e32 v123, v175, v123
	v_bfe_u32 v170, v123, 16, 1
	v_add3_u32 v123, v123, v170, s10
	ds_write_b16_d16_hi v83, v123 offset:432
	ds_write_b16_d16_hi v83, v117 offset:5040
	v_lshlrev_b32_e32 v123, 16, v181
	v_max_f32_e32 v123, v123, v123
	v_med3_f32 v123, v123, s9, v244
	v_mul_f32_e32 v123, 0xbfb8aa3b, v123
	v_exp_f32_e32 v123, v123
	s_nop 0
	v_add_f32_e32 v170, 1.0, v123
	v_rcp_f32_e32 v170, v170
	s_nop 0
	v_fma_f32 v176, v80, v170, v149
	v_mul_f32_e32 v123, v123, v170
	v_mul_f32_e32 v170, v175, v176
	v_max_f32_e32 v170, 0xda24260, v170
	v_rcp_f32_e32 v175, v170
	v_mul_f32_e32 v123, v80, v123
	v_mul_f32_e32 v123, v123, v175
	v_bfe_u32 v175, v123, 16, 1
	v_add3_u32 v123, v123, v175, s10
	v_lshlrev_b32_e32 v175, 16, v178
	v_mul_f32_e32 v175, v170, v175
	v_bfe_u32 v176, v175, 16, 1
	v_add3_u32 v175, v175, v176, s10
	ds_write_b16_d16_hi v83, v175 offset:576
	ds_write_b16_d16_hi v83, v123 offset:5184
	v_lshlrev_b32_e32 v175, 16, v186
	v_max_f32_e32 v175, v175, v175
	v_med3_f32 v175, v175, s9, v244
	v_mul_f32_e32 v175, 0xbfb8aa3b, v175
	v_exp_f32_e32 v175, v175
	s_nop 0
	v_add_f32_e32 v176, 1.0, v175
	v_rcp_f32_e32 v176, v176
	s_nop 0
	v_fma_f32 v178, v80, v176, v149
	v_mul_f32_e32 v170, v170, v178
	v_max_f32_e32 v170, 0xda24260, v170
	v_mul_f32_e32 v175, v175, v176
	v_rcp_f32_e32 v176, v170
	v_mul_f32_e32 v175, v80, v175
	v_mul_f32_e32 v175, v175, v176
	v_bfe_u32 v176, v175, 16, 1
	v_add3_u32 v175, v175, v176, s10
	v_lshlrev_b32_e32 v176, 16, v185
	v_mul_f32_e32 v176, v170, v176
	v_bfe_u32 v178, v176, 16, 1
	v_add3_u32 v176, v176, v178, s10
	ds_write_b16_d16_hi v83, v176 offset:720
	ds_write_b16_d16_hi v83, v175 offset:5328
	v_lshlrev_b32_e32 v176, 16, v184
	v_max_f32_e32 v176, v176, v176
	v_med3_f32 v176, v176, s9, v244
	v_mul_f32_e32 v176, 0xbfb8aa3b, v176
	v_exp_f32_e32 v176, v176
	s_nop 0
	v_add_f32_e32 v178, 1.0, v176
	v_rcp_f32_e32 v178, v178
	s_nop 0
	v_fma_f32 v180, v80, v178, v149
	v_mul_f32_e32 v170, v170, v180
	v_mul_f32_e32 v176, v176, v178
	v_max_f32_e32 v178, 0xda24260, v170
	v_rcp_f32_e32 v170, v178
	v_mul_f32_e32 v176, v80, v176
	v_mul_f32_e32 v170, v176, v170
	v_bfe_u32 v176, v170, 16, 1
	v_add3_u32 v170, v170, v176, s10
	v_lshlrev_b32_e32 v176, 16, v179
	v_mul_f32_e32 v176, v178, v176
	v_bfe_u32 v179, v176, 16, 1
	v_add3_u32 v176, v176, v179, s10
	ds_write_b16_d16_hi v83, v176 offset:864
	ds_write_b16_d16_hi v83, v170 offset:5472
	v_lshlrev_b32_e32 v176, 16, v177
	v_max_f32_e32 v176, v176, v176
	v_med3_f32 v176, v176, s9, v244
	v_mul_f32_e32 v176, 0xbfb8aa3b, v176
	v_exp_f32_e32 v176, v176
	s_nop 0
	v_add_f32_e32 v177, 1.0, v176
	v_rcp_f32_e32 v177, v177
	s_nop 0
	v_fma_f32 v179, v80, v177, v149
	v_mul_f32_e32 v176, v176, v177
	v_mul_f32_e32 v177, v178, v179
	v_max_f32_e32 v177, 0xda24260, v177
	v_rcp_f32_e32 v178, v177
	v_mul_f32_e32 v176, v80, v176
	v_mul_f32_e32 v173, v177, v173
	v_mul_f32_e32 v176, v176, v178
	v_bfe_u32 v178, v176, 16, 1
	v_add3_u32 v176, v176, v178, s10
	v_bfe_u32 v178, v173, 16, 1
	v_add3_u32 v173, v173, v178, s10
	ds_write_b16_d16_hi v83, v173 offset:1008
	ds_write_b16_d16_hi v83, v176 offset:5616
	s_waitcnt vmcnt(63)
	v_lshlrev_b32_e32 v173, 16, v174
	v_max_f32_e32 v173, v173, v173
	v_med3_f32 v173, v173, s9, v244
	v_mul_f32_e32 v173, 0xbfb8aa3b, v173
	v_exp_f32_e32 v173, v173
	s_waitcnt vmcnt(61)
	v_lshlrev_b32_e32 v171, 16, v171
	v_max_f32_e32 v171, v171, v171
	v_med3_f32 v171, v171, s9, v244
	v_add_f32_e32 v174, 1.0, v173
	v_rcp_f32_e32 v174, v174
	v_mul_f32_e32 v171, 0xbfb8aa3b, v171
	v_exp_f32_e32 v178, v171
	v_lshlrev_b32_e32 v172, 16, v172
	v_fma_f32 v171, v80, v174, v149
	v_mul_f32_e32 v171, v177, v171
	v_max_f32_e32 v177, 0xda24260, v171
	v_rcp_f32_e32 v171, v177
	v_mul_f32_e32 v173, v173, v174
	v_mul_f32_e32 v173, v80, v173
	v_mul_f32_e32 v172, v177, v172
	v_mul_f32_e32 v171, v173, v171
	v_bfe_u32 v173, v171, 16, 1
	v_add3_u32 v171, v171, v173, s10
	v_add_f32_e32 v173, 1.0, v178
	v_rcp_f32_e32 v173, v173
	v_bfe_u32 v174, v172, 16, 1
	v_add3_u32 v172, v172, v174, s10
	ds_write_b16_d16_hi v83, v172 offset:1152
	v_fma_f32 v172, v80, v173, v149
	v_mul_f32_e32 v172, v177, v172
	v_max_f32_e32 v174, 0xda24260, v172
	v_rcp_f32_e32 v172, v174
	v_mul_f32_e32 v173, v178, v173
	v_mul_f32_e32 v173, v80, v173
	s_waitcnt vmcnt(60)
	v_lshlrev_b32_e32 v169, 16, v169
	v_mul_f32_e32 v172, v173, v172
	v_bfe_u32 v173, v172, 16, 1
	v_mul_f32_e32 v169, v174, v169
	ds_write_b16_d16_hi v83, v171 offset:5760
	v_add3_u32 v172, v172, v173, s10
	v_bfe_u32 v173, v169, 16, 1
	v_add3_u32 v169, v169, v173, s10
	s_nop 0
	s_nop 0
	s_nop 0
	s_nop 0
	s_nop 0
	s_waitcnt vmcnt(59)
	v_lshlrev_b32_e32 v74, 16, v166
	v_max_f32_e32 v74, v74, v74
	v_med3_f32 v74, v74, s9, v244
	v_mul_f32_e32 v74, 0xbfb8aa3b, v74
	v_exp_f32_e32 v84, v74
	v_add_co_u32_e32 v74, vcc, s5, v64
	s_waitcnt vmcnt(56)
	v_lshlrev_b32_e32 v158, 16, v158
	v_addc_co_u32_e32 v75, vcc, 0, v65, vcc
	v_add_f32_e32 v166, 1.0, v84
	s_nop 0
	s_nop 0
	s_nop 0
	s_nop 0
	s_nop 0
	s_nop 0
	v_rcp_f32_e32 v166, v166
	s_waitcnt vmcnt(53)
	v_lshlrev_b32_e32 v165, 16, v165
	v_max_f32_e32 v165, v165, v165
	v_med3_f32 v165, v165, s9, v244
	v_fma_f32 v113, v80, v166, v149
	v_mul_f32_e32 v113, v174, v113
	v_mul_f32_e32 v84, v84, v166
	v_lshlrev_b32_e32 v166, 16, v167
	v_max_f32_e32 v113, 0xda24260, v113
	v_max_f32_e32 v166, v166, v166
	v_rcp_f32_e32 v115, v113
	v_med3_f32 v166, v166, s9, v244
	v_mul_f32_e32 v166, 0xbfb8aa3b, v166
	v_exp_f32_e32 v166, v166
	v_mul_f32_e32 v84, v80, v84
	v_mul_f32_e32 v84, v84, v115
	v_bfe_u32 v115, v84, 16, 1
	v_add3_u32 v84, v84, v115, s10
	v_lshlrev_b32_e32 v115, 16, v164
	v_add_f32_e32 v164, 1.0, v166
	v_rcp_f32_e32 v164, v164
	v_mul_f32_e32 v115, v113, v115
	v_bfe_u32 v167, v115, 16, 1
	v_add3_u32 v115, v115, v167, s10
	ds_write_b16_d16_hi v83, v115 offset:1440
	v_fma_f32 v115, v80, v164, v149
	v_mul_f32_e32 v113, v113, v115
	v_mul_f32_e32 v164, v166, v164
	v_lshlrev_b32_e32 v166, 16, v168
	v_max_f32_e32 v113, 0xda24260, v113
	v_max_f32_e32 v166, v166, v166
	v_rcp_f32_e32 v115, v113
	v_med3_f32 v166, v166, s9, v244
	v_mul_f32_e32 v166, 0xbfb8aa3b, v166
	v_exp_f32_e32 v166, v166
	v_mul_f32_e32 v164, v80, v164
	v_mul_f32_e32 v115, v164, v115
	v_bfe_u32 v164, v115, 16, 1
	v_add3_u32 v115, v115, v164, s10
	v_add_f32_e32 v164, 1.0, v166
	v_rcp_f32_e32 v164, v164
	v_mul_f32_e32 v158, v113, v158
	v_bfe_u32 v167, v158, 16, 1
	v_add3_u32 v158, v158, v167, s10
	ds_write_b16_d16_hi v83, v158 offset:1584
	v_fma_f32 v158, v80, v164, v149
	v_mul_f32_e32 v113, v113, v158
	v_max_f32_e32 v113, 0xda24260, v113
	v_rcp_f32_e32 v158, v113
	v_mul_f32_e32 v165, 0xbfb8aa3b, v165
	v_mul_f32_e32 v164, v166, v164
	v_exp_f32_e32 v165, v165
	v_mul_f32_e32 v164, v80, v164
	v_mul_f32_e32 v158, v164, v158
	v_bfe_u32 v164, v158, 16, 1
	v_add3_u32 v158, v158, v164, s10
	v_add_f32_e32 v164, 1.0, v165
	v_lshlrev_b32_e32 v163, 16, v163
	v_rcp_f32_e32 v164, v164
	v_mul_f32_e32 v163, v113, v163
	v_bfe_u32 v166, v163, 16, 1
	v_add3_u32 v163, v163, v166, s10
	ds_write_b16_d16_hi v83, v163 offset:1728
	v_fma_f32 v163, v80, v164, v149
	v_mul_f32_e32 v113, v113, v163
	s_waitcnt vmcnt(51)
	v_lshlrev_b32_e32 v162, 16, v162
	v_max_f32_e32 v113, 0xda24260, v113
	v_max_f32_e32 v162, v162, v162
	v_rcp_f32_e32 v163, v113
	v_med3_f32 v162, v162, s9, v244
	v_mul_f32_e32 v162, 0xbfb8aa3b, v162
	v_mul_f32_e32 v164, v165, v164
	v_exp_f32_e32 v162, v162
	v_mul_f32_e32 v164, v80, v164
	v_mul_f32_e32 v163, v164, v163
	v_bfe_u32 v164, v163, 16, 1
	v_add3_u32 v163, v163, v164, s10
	v_add_f32_e32 v164, 1.0, v162
	v_lshlrev_b32_e32 v157, 16, v157
	v_rcp_f32_e32 v164, v164
	v_mul_f32_e32 v157, v113, v157
	v_bfe_u32 v165, v157, 16, 1
	v_add3_u32 v157, v157, v165, s10
	ds_write_b16_d16_hi v83, v157 offset:1872
	v_fma_f32 v157, v80, v164, v149
	v_mul_f32_e32 v113, v113, v157
	s_waitcnt vmcnt(49)
	v_lshlrev_b32_e32 v159, 16, v159
	v_max_f32_e32 v113, 0xda24260, v113
	v_max_f32_e32 v159, v159, v159
	v_rcp_f32_e32 v157, v113
	v_med3_f32 v159, v159, s9, v244
	v_mul_f32_e32 v159, 0xbfb8aa3b, v159
	v_mul_f32_e32 v162, v162, v164
	v_exp_f32_e32 v159, v159
	v_mul_f32_e32 v162, v80, v162
	v_mul_f32_e32 v157, v162, v157
	v_bfe_u32 v162, v157, 16, 1
	v_add3_u32 v157, v157, v162, s10
	v_add_f32_e32 v162, 1.0, v159
	v_lshlrev_b32_e32 v156, 16, v156
	v_rcp_f32_e32 v162, v162
	v_mul_f32_e32 v156, v113, v156
	v_bfe_u32 v164, v156, 16, 1
	v_add3_u32 v156, v156, v164, s10
	ds_write_b16_d16_hi v83, v156 offset:2016
	v_fma_f32 v156, v80, v162, v149
	v_mul_f32_e32 v113, v113, v156
	v_max_f32_e32 v113, 0xda24260, v113
	v_rcp_f32_e32 v156, v113
	v_mul_f32_e32 v159, v159, v162
	v_mul_f32_e32 v159, v80, v159
	s_waitcnt vmcnt(48)
	v_lshlrev_b32_e32 v81, 16, v81
	v_mul_f32_e32 v156, v159, v156
	v_bfe_u32 v159, v156, 16, 1
	v_mul_f32_e32 v81, v113, v81
	v_add3_u32 v159, v156, v159, s10
	v_bfe_u32 v156, v81, 16, 1
	v_add3_u32 v81, v81, v156, s10
	ds_write_b16_d16_hi v83, v169 offset:1296
	ds_write_b16_d16_hi v83, v172 offset:5904
	ds_write_b16_d16_hi v83, v84 offset:6048
	ds_write_b16_d16_hi v83, v115 offset:6192
	ds_write_b16_d16_hi v83, v158 offset:6336
	ds_write_b16_d16_hi v83, v163 offset:6480
	ds_write_b16_d16_hi v83, v157 offset:6624
	ds_write_b16_d16_hi v83, v81 offset:2160
	ds_write_b16_d16_hi v83, v159 offset:6768
	s_waitcnt vmcnt(30)
	v_lshlrev_b32_e32 v81, 16, v201
	v_max_f32_e32 v81, v81, v81
	v_med3_f32 v81, v81, s9, v244
	v_mul_f32_e32 v81, 0xbfb8aa3b, v81
	v_exp_f32_e32 v81, v81
	s_waitcnt vmcnt(18)
	v_lshlrev_b32_e32 v108, 16, v203
	v_max_f32_e32 v108, v108, v108
	v_med3_f32 v108, v108, s9, v244
	v_add_f32_e32 v156, 1.0, v81
	v_rcp_f32_e32 v156, v156
	v_mul_f32_e32 v108, 0xbfb8aa3b, v108
	v_exp_f32_e32 v108, v108
	v_lshlrev_b32_e32 v77, 16, v200
	v_fma_f32 v162, v80, v156, v149
	v_mul_f32_e32 v113, v113, v162
	v_max_f32_e32 v113, 0xda24260, v113
	v_rcp_f32_e32 v162, v113
	v_mul_f32_e32 v81, v81, v156
	v_mul_f32_e32 v81, v80, v81
	v_mul_f32_e32 v77, v113, v77
	v_mul_f32_e32 v81, v81, v162
	v_bfe_u32 v156, v81, 16, 1
	v_add3_u32 v156, v81, v156, s10
	v_add_f32_e32 v81, 1.0, v108
	v_rcp_f32_e32 v81, v81
	v_bfe_u32 v162, v77, 16, 1
	v_add3_u32 v77, v77, v162, s10
	ds_write_b16_d16_hi v83, v77 offset:2304
	v_fma_f32 v77, v80, v81, v149
	ds_write_b16_d16_hi v83, v156 offset:6912
	v_mul_f32_e32 v77, v113, v77
	s_waitcnt vmcnt(18)
	v_lshlrev_b32_e32 v66, 16, v207
	v_max_f32_e32 v77, 0xda24260, v77
	v_max_f32_e32 v66, v66, v66
	v_rcp_f32_e32 v113, v77
	v_med3_f32 v66, v66, s9, v244
	v_mul_f32_e32 v66, 0xbfb8aa3b, v66
	v_mul_f32_e32 v81, v108, v81
	v_exp_f32_e32 v66, v66
	v_mul_f32_e32 v81, v80, v81
	v_mul_f32_e32 v81, v81, v113
	v_bfe_u32 v108, v81, 16, 1
	v_add_co_u32_e32 v64, vcc, s4, v64
	v_add3_u32 v108, v81, v108, s10
	v_lshlrev_b32_e32 v81, 16, v202
	v_addc_co_u32_e32 v65, vcc, 0, v65, vcc
	v_add_f32_e32 v67, 1.0, v66
	s_nop 0
	s_nop 0
	s_nop 0
	s_nop 0
	s_nop 0
	v_rcp_f32_e32 v67, v67
	v_mul_f32_e32 v81, v77, v81
	v_bfe_u32 v113, v81, 16, 1
	v_add3_u32 v81, v81, v113, s10
	v_fma_f32 v64, v80, v67, v149
	v_mul_f32_e32 v64, v77, v64
	v_mul_f32_e32 v66, v66, v67
	s_waitcnt vmcnt(18)
	v_lshlrev_b32_e32 v67, 16, v209
	v_max_f32_e32 v64, 0xda24260, v64
	v_max_f32_e32 v67, v67, v67
	v_rcp_f32_e32 v65, v64
	v_med3_f32 v67, v67, s9, v244
	v_mul_f32_e32 v67, 0xbfb8aa3b, v67
	v_exp_f32_e32 v67, v67
	v_mul_f32_e32 v66, v80, v66
	v_mul_f32_e32 v65, v66, v65
	v_bfe_u32 v66, v65, 16, 1
	v_add3_u32 v181, v65, v66, s10
	v_add_f32_e32 v66, 1.0, v67
	v_lshlrev_b32_e32 v65, 16, v206
	v_rcp_f32_e32 v66, v66
	v_mul_f32_e32 v65, v64, v65
	v_bfe_u32 v68, v65, 16, 1
	v_add3_u32 v65, v65, v68, s10
	ds_write_b16_d16_hi v83, v65 offset:2592
	v_fma_f32 v65, v80, v66, v149
	v_mul_f32_e32 v66, v67, v66
	v_lshlrev_b32_e32 v67, 16, v211
	v_mul_f32_e32 v64, v64, v65
	v_max_f32_e32 v67, v67, v67
	v_max_f32_e32 v64, 0xda24260, v64
	v_med3_f32 v67, v67, s9, v244
	v_rcp_f32_e32 v65, v64
	v_mul_f32_e32 v67, 0xbfb8aa3b, v67
	v_exp_f32_e32 v67, v67
	v_mul_f32_e32 v66, v80, v66
	v_mul_f32_e32 v65, v66, v65
	v_bfe_u32 v66, v65, 16, 1
	v_add_f32_e32 v68, 1.0, v67
	v_add3_u32 v65, v65, v66, s10
	s_waitcnt vmcnt(18)
	v_lshlrev_b32_e32 v66, 16, v208
	v_rcp_f32_e32 v68, v68
	v_mul_f32_e32 v66, v64, v66
	v_bfe_u32 v69, v66, 16, 1
	v_add3_u32 v66, v66, v69, s10
	ds_write_b16_d16_hi v83, v66 offset:2736
	v_fma_f32 v66, v80, v68, v149
	v_mul_f32_e32 v64, v64, v66
	v_mul_f32_e32 v67, v67, v68
	s_waitcnt vmcnt(18)
	v_lshlrev_b32_e32 v68, 16, v213
	v_max_f32_e32 v64, 0xda24260, v64
	v_max_f32_e32 v68, v68, v68
	v_rcp_f32_e32 v66, v64
	v_med3_f32 v68, v68, s9, v244
	v_mul_f32_e32 v68, 0xbfb8aa3b, v68
	v_exp_f32_e32 v68, v68
	v_mul_f32_e32 v67, v80, v67
	v_mul_f32_e32 v66, v67, v66
	v_bfe_u32 v67, v66, 16, 1
	v_add3_u32 v182, v66, v67, s10
	v_add_f32_e32 v67, 1.0, v68
	v_lshlrev_b32_e32 v66, 16, v210
	v_rcp_f32_e32 v67, v67
	v_mul_f32_e32 v66, v64, v66
	v_bfe_u32 v69, v66, 16, 1
	v_add3_u32 v66, v66, v69, s10
	ds_write_b16_d16_hi v83, v66 offset:2880
	v_fma_f32 v66, v80, v67, v149
	v_mul_f32_e32 v67, v68, v67
	v_lshlrev_b32_e32 v68, 16, v215
	v_mul_f32_e32 v64, v64, v66
	v_max_f32_e32 v68, v68, v68
	v_max_f32_e32 v64, 0xda24260, v64
	v_med3_f32 v68, v68, s9, v244
	v_rcp_f32_e32 v66, v64
	v_mul_f32_e32 v68, 0xbfb8aa3b, v68
	v_exp_f32_e32 v68, v68
	v_mul_f32_e32 v67, v80, v67
	v_mul_f32_e32 v66, v67, v66
	v_bfe_u32 v67, v66, 16, 1
	v_add_f32_e32 v69, 1.0, v68
	v_add3_u32 v66, v66, v67, s10
	s_waitcnt vmcnt(16)
	v_lshlrev_b32_e32 v67, 16, v212
	v_rcp_f32_e32 v69, v69
	v_mul_f32_e32 v67, v64, v67
	v_bfe_u32 v70, v67, 16, 1
	v_add3_u32 v67, v67, v70, s10
	ds_write_b16_d16_hi v83, v67 offset:3024
	v_fma_f32 v67, v80, v69, v149
	v_mul_f32_e32 v64, v64, v67
	v_mul_f32_e32 v68, v68, v69
	v_lshlrev_b32_e32 v69, 16, v217
	v_max_f32_e32 v64, 0xda24260, v64
	v_max_f32_e32 v69, v69, v69
	v_rcp_f32_e32 v67, v64
	v_med3_f32 v69, v69, s9, v244
	v_mul_f32_e32 v69, 0xbfb8aa3b, v69
	v_exp_f32_e32 v69, v69
	v_mul_f32_e32 v68, v80, v68
	v_mul_f32_e32 v67, v68, v67
	v_bfe_u32 v68, v67, 16, 1
	v_add3_u32 v178, v67, v68, s10
	v_add_f32_e32 v68, 1.0, v69
	v_lshlrev_b32_e32 v67, 16, v214
	v_rcp_f32_e32 v68, v68
	v_mul_f32_e32 v67, v64, v67
	v_bfe_u32 v70, v67, 16, 1
	v_add3_u32 v67, v67, v70, s10
	ds_write_b16_d16_hi v83, v67 offset:3168
	v_fma_f32 v67, v80, v68, v149
	v_mul_f32_e32 v64, v64, v67
	v_max_f32_e32 v76, 0xda24260, v64
	v_rcp_f32_e32 v64, v76
	v_mul_f32_e32 v67, v69, v68
	v_mul_f32_e32 v67, v80, v67
	ds_write_b16_d16_hi v83, v81 offset:2448
	v_mul_f32_e32 v64, v67, v64
	v_bfe_u32 v67, v64, 16, 1
	v_add3_u32 v64, v64, v67, s10
	v_lshlrev_b32_e32 v67, 16, v216
	v_mul_f32_e32 v67, v76, v67
	v_bfe_u32 v68, v67, 16, 1
	v_add3_u32 v67, v67, v68, s10
	ds_write_b16_d16_hi v83, v108 offset:7056
	ds_write_b16_d16_hi v83, v181 offset:7200
	ds_write_b16_d16_hi v83, v65 offset:7344
	ds_write_b16_d16_hi v83, v182 offset:7488
	ds_write_b16_d16_hi v83, v66 offset:7632
	ds_write_b16_d16_hi v83, v178 offset:7776
	ds_write_b16_d16_hi v83, v67 offset:3312
	ds_write_b16_d16_hi v83, v64 offset:7920
	s_waitcnt vmcnt(14)
	v_lshlrev_b32_e32 v72, 16, v219
	v_max_f32_e32 v72, v72, v72
	v_med3_f32 v72, v72, s9, v244
	v_mul_f32_e32 v72, 0xbfb8aa3b, v72
	v_and_b32_e32 v103, 0xffff0000, v108
	v_exp_f32_e32 v108, v72
	v_lshl_or_b32 v78, v120, 16, v127
	s_waitcnt vmcnt(1)
	v_lshlrev_b32_e32 v106, 16, v220
	s_waitcnt vmcnt(1)
	v_lshlrev_b32_e32 v104, 16, v225
	v_add_f32_e32 v77, 1.0, v108
	v_rcp_f32_e32 v110, v77
	v_max_f32_e32 v104, v104, v104
	v_med3_f32 v104, v104, s9, v244
	v_mul_f32_e32 v104, 0xbfb8aa3b, v104
	v_fma_f32 v112, v80, v110, v149
	v_mul_f32_e32 v76, v76, v112
	v_max_f32_e32 v112, 0xda24260, v76
	v_lshl_or_b32 v76, v121, 16, v88
	v_mul_f32_e32 v88, v108, v110
	v_lshlrev_b32_e32 v110, 16, v221
	v_max_f32_e32 v110, v110, v110
	v_rcp_f32_e32 v114, v112
	v_med3_f32 v110, v110, s9, v244
	v_mul_f32_e32 v110, 0xbfb8aa3b, v110
	v_exp_f32_e32 v110, v110
	v_mul_f32_e32 v88, v80, v88
	v_mul_f32_e32 v88, v88, v114
	v_bfe_u32 v108, v88, 16, 1
	v_add3_u32 v120, v88, v108, s10
	v_add_f32_e32 v108, 1.0, v110
	v_lshlrev_b32_e32 v88, 16, v218
	v_rcp_f32_e32 v108, v108
	v_mul_f32_e32 v88, v112, v88
	v_bfe_u32 v114, v88, 16, 1
	v_add3_u32 v88, v88, v114, s10
	ds_write_b16_d16_hi v83, v88 offset:3456
	v_fma_f32 v88, v80, v108, v149
	v_mul_f32_e32 v88, v112, v88
	v_max_f32_e32 v88, 0xda24260, v88
	v_rcp_f32_e32 v112, v88
	v_mul_f32_e32 v108, v110, v108
	v_mul_f32_e32 v108, v80, v108
	v_mul_f32_e32 v106, v88, v106
	v_mul_f32_e32 v108, v108, v112
	v_bfe_u32 v110, v108, 16, 1
	v_add3_u32 v108, v108, v110, s10
	v_lshlrev_b32_e32 v110, 16, v223
	v_max_f32_e32 v110, v110, v110
	v_med3_f32 v110, v110, s9, v244
	v_mul_f32_e32 v110, 0xbfb8aa3b, v110
	v_exp_f32_e32 v110, v110
	v_bfe_u32 v114, v106, 16, 1
	v_add3_u32 v106, v106, v114, s10
	ds_write_b16_d16_hi v83, v106 offset:3600
	v_add_f32_e32 v112, 1.0, v110
	v_rcp_f32_e32 v112, v112
	v_and_b32_e32 v121, 0xffff0000, v108
	ds_write_b16_d16_hi v83, v108 offset:8208
	v_exp_f32_e32 v104, v104
	v_fma_f32 v106, v80, v112, v149
	v_mul_f32_e32 v88, v88, v106
	v_max_f32_e32 v88, 0xda24260, v88
	v_rcp_f32_e32 v106, v88
	v_mul_f32_e32 v108, v110, v112
	v_mul_f32_e32 v108, v80, v108
	v_lshl_or_b32 v79, v122, 16, v128
	v_mul_f32_e32 v106, v108, v106
	v_bfe_u32 v108, v106, 16, 1
	v_add3_u32 v122, v106, v108, s10
	v_add_f32_e32 v108, 1.0, v104
	v_lshlrev_b32_e32 v106, 16, v222
	v_rcp_f32_e32 v108, v108
	v_mul_f32_e32 v106, v88, v106
	v_bfe_u32 v110, v106, 16, 1
	v_add3_u32 v106, v106, v110, s10
	ds_write_b16_d16_hi v83, v106 offset:3744
	v_fma_f32 v106, v80, v108, v149
	v_mul_f32_e32 v88, v88, v106
	v_max_f32_e32 v88, 0xda24260, v88
	v_rcp_f32_e32 v106, v88
	v_mul_f32_e32 v104, v104, v108
	v_mul_f32_e32 v104, v80, v104
	v_lshlrev_b32_e32 v108, 16, v224
	v_mul_f32_e32 v104, v104, v106
	v_bfe_u32 v106, v104, 16, 1
	v_add3_u32 v104, v104, v106, s10
	v_lshlrev_b32_e32 v106, 16, v227
	v_max_f32_e32 v106, v106, v106
	v_med3_f32 v106, v106, s9, v244
	v_mul_f32_e32 v106, 0xbfb8aa3b, v106
	v_exp_f32_e32 v106, v106
	v_mul_f32_e32 v108, v88, v108
	v_bfe_u32 v112, v108, 16, 1
	v_add3_u32 v108, v108, v112, s10
	v_add_f32_e32 v110, 1.0, v106
	v_rcp_f32_e32 v110, v110
	ds_write_b16_d16_hi v83, v108 offset:3888
	v_lshl_or_b32 v74, v144, 16, v131
	v_and_b32_e32 v131, 0xffff0000, v104
	v_fma_f32 v108, v80, v110, v149
	v_mul_f32_e32 v88, v88, v108
	v_max_f32_e32 v88, 0xda24260, v88
	v_rcp_f32_e32 v108, v88
	ds_write_b16_d16_hi v83, v104 offset:8496
	v_mul_f32_e32 v104, v106, v110
	v_mul_f32_e32 v104, v80, v104
	v_mul_f32_e32 v104, v104, v108
	s_waitcnt vmcnt(1)
	v_lshlrev_b32_e32 v108, 16, v229
	v_max_f32_e32 v108, v108, v108
	v_med3_f32 v108, v108, s9, v244
	v_mul_f32_e32 v108, 0xbfb8aa3b, v108
	v_exp_f32_e32 v108, v108
	v_bfe_u32 v106, v104, 16, 1
	v_lshl_or_b32 v75, v153, 16, v132
	v_add3_u32 v132, v104, v106, s10
	v_add_f32_e32 v106, 1.0, v108
	v_lshlrev_b32_e32 v104, 16, v226
	v_rcp_f32_e32 v106, v106
	v_mul_f32_e32 v104, v88, v104
	v_bfe_u32 v110, v104, 16, 1
	v_add3_u32 v104, v104, v110, s10
	ds_write_b16_d16_hi v83, v104 offset:4032
	v_fma_f32 v104, v80, v106, v149
	v_mul_f32_e32 v88, v88, v104
	v_max_f32_e32 v88, 0xda24260, v88
	v_rcp_f32_e32 v104, v88
	v_mul_f32_e32 v106, v108, v106
	v_mul_f32_e32 v106, v80, v106
	s_waitcnt vmcnt(1)
	v_lshlrev_b32_e32 v102, 16, v228
	v_mul_f32_e32 v104, v106, v104
	v_bfe_u32 v106, v104, 16, 1
	v_add3_u32 v104, v104, v106, s10
	v_lshlrev_b32_e32 v106, 16, v231
	v_max_f32_e32 v106, v106, v106
	v_med3_f32 v106, v106, s9, v244
	v_mul_f32_e32 v106, 0xbfb8aa3b, v106
	v_exp_f32_e32 v106, v106
	v_mul_f32_e32 v102, v88, v102
	v_bfe_u32 v110, v102, 16, 1
	v_add3_u32 v102, v102, v110, s10
	v_add_f32_e32 v108, 1.0, v106
	v_rcp_f32_e32 v108, v108
	ds_write_b16_d16_hi v83, v102 offset:4176
	s_waitcnt vmcnt(0)
	v_lshlrev_b32_e32 v86, 16, v233
	v_max_f32_e32 v86, v86, v86
	v_fma_f32 v102, v80, v108, v149
	v_mul_f32_e32 v88, v88, v102
	v_max_f32_e32 v88, 0xda24260, v88
	v_rcp_f32_e32 v102, v88
	v_med3_f32 v86, v86, s9, v244
	v_mul_f32_e32 v86, 0xbfb8aa3b, v86
	v_lshl_or_b32 v69, v151, 16, v135
	v_and_b32_e32 v135, 0xffff0000, v104
	ds_write_b16_d16_hi v83, v104 offset:8784
	v_mul_f32_e32 v104, v106, v108
	v_exp_f32_e32 v86, v86
	v_mul_f32_e32 v104, v80, v104
	v_mul_f32_e32 v102, v104, v102
	v_bfe_u32 v104, v102, 16, 1
	v_lshl_or_b32 v70, v150, 16, v136
	v_add3_u32 v136, v102, v104, s10
	v_add_f32_e32 v104, 1.0, v86
	v_rcp_f32_e32 v104, v104
	v_lshlrev_b32_e32 v102, 16, v230
	v_mul_f32_e32 v102, v88, v102
	v_bfe_u32 v106, v102, 16, 1
	v_fmac_f32_e32 v149, v80, v104
	v_mul_f32_e32 v88, v88, v149
	v_add3_u32 v102, v102, v106, s10
	v_max_f32_e32 v88, 0xda24260, v88
	ds_write_b16_d16_hi v83, v102 offset:4320
	v_rcp_f32_e32 v102, v88
	v_mul_f32_e32 v86, v86, v104
	v_mul_f32_e32 v80, v80, v86
	v_and_b32_e32 v81, 0xffff0000, v64
	v_mul_f32_e32 v80, v80, v102
	v_bfe_u32 v86, v80, 16, 1
	v_add3_u32 v80, v80, v86, s10
	v_lshlrev_b32_e32 v86, 16, v232
	v_mul_f32_e32 v86, v88, v86
	v_bfe_u32 v102, v86, 16, 1
	v_add3_u32 v86, v86, v102, s10
	v_and_b32_e32 v85, 0xffff0000, v66
	v_and_b32_e32 v87, 0xffff0000, v65
	v_and_b32_e32 v105, 0xffff0000, v159
	v_and_b32_e32 v107, 0xffff0000, v163
	v_and_b32_e32 v109, 0xffff0000, v115
	v_and_b32_e32 v111, 0xffff0000, v172
	v_and_b32_e32 v113, 0xffff0000, v176
	v_and_b32_e32 v115, 0xffff0000, v175
	v_and_b32_e32 v117, 0xffff0000, v117
	v_and_b32_e32 v119, 0xffff0000, v119
	v_lshl_or_b32 v67, v142, 16, v141
	v_lshl_or_b32 v66, v143, 16, v140
	v_lshl_or_b32 v65, v145, 16, v139
	v_lshl_or_b32 v64, v146, 16, v138
	v_lshl_or_b32 v71, v147, 16, v137
	v_lshl_or_b32 v68, v152, 16, v134
	v_lshl_or_b32 v73, v154, 16, v130
	v_lshl_or_b32 v72, v155, 16, v129
	v_lshl_or_b32 v77, v118, 16, v126
	ds_write_b16_d16_hi v83, v120 offset:8064
	ds_write_b16_d16_hi v83, v122 offset:8352
	ds_write_b16_d16_hi v83, v132 offset:8640
	ds_write_b16_d16_hi v83, v136 offset:8928
	v_and_b32_e32 v137, 0xffff0000, v80
	ds_write_b16_d16_hi v83, v86 offset:4464
	ds_write_b16_d16_hi v83, v80 offset:9072
	v_and_b32_e32 v112, 0xffff0000, v170
	v_and_b32_e32 v104, 0xffff0000, v157
	v_and_b32_e32 v80, 0xffff0000, v178
	v_pk_mul_f32 v[112:113], v[88:89], v[112:113] op_sel_hi:[0,1]
	v_and_b32_e32 v108, 0xffff0000, v84
	v_pk_mul_f32 v[104:105], v[88:89], v[104:105] op_sel_hi:[0,1]
	v_and_b32_e32 v84, 0xffff0000, v182
	v_pk_mul_f32 v[80:81], v[88:89], v[80:81] op_sel_hi:[0,1]
	v_and_b32_e32 v120, 0xffff0000, v120
	v_cvt_pk_bf16_f32 v129, v112, v113
	v_cvt_pk_bf16_f32 v113, v104, v105
	v_pk_mul_f32 v[84:85], v[88:89], v[84:85] op_sel_hi:[0,1]
	v_cvt_pk_bf16_f32 v105, v80, v81
	v_pk_mul_f32 v[80:81], v[88:89], v[120:121] op_sel_hi:[0,1]
	v_and_b32_e32 v130, 0xffff0000, v122
	v_and_b32_e32 v102, 0xffff0000, v156
	v_and_b32_e32 v86, 0xffff0000, v181
	v_cvt_pk_bf16_f32 v104, v84, v85
	v_cvt_pk_bf16_f32 v84, v80, v81
	v_pk_mul_f32 v[80:81], v[88:89], v[130:131] op_sel_hi:[0,1]
	v_and_b32_e32 v134, 0xffff0000, v132
	v_and_b32_e32 v118, 0xffff0000, v133
	v_and_b32_e32 v116, 0xffff0000, v116
	v_and_b32_e32 v114, 0xffff0000, v123
	v_and_b32_e32 v110, 0xffff0000, v171
	v_and_b32_e32 v106, 0xffff0000, v158
	v_pk_mul_f32 v[102:103], v[88:89], v[102:103] op_sel_hi:[0,1]
	v_pk_mul_f32 v[86:87], v[88:89], v[86:87] op_sel_hi:[0,1]
	v_cvt_pk_bf16_f32 v85, v80, v81
	v_pk_mul_f32 v[80:81], v[88:89], v[134:135] op_sel_hi:[0,1]
	v_and_b32_e32 v136, 0xffff0000, v136
	s_movk_i32 s0, 0x50
	v_pk_mul_f32 v[118:119], v[88:89], v[118:119] op_sel_hi:[0,1]
	v_pk_mul_f32 v[116:117], v[88:89], v[116:117] op_sel_hi:[0,1]
	v_pk_mul_f32 v[114:115], v[88:89], v[114:115] op_sel_hi:[0,1]
	v_pk_mul_f32 v[110:111], v[88:89], v[110:111] op_sel_hi:[0,1]
	v_pk_mul_f32 v[108:109], v[88:89], v[108:109] op_sel_hi:[0,1]
	v_pk_mul_f32 v[106:107], v[88:89], v[106:107] op_sel_hi:[0,1]
	v_cvt_pk_bf16_f32 v102, v102, v103
	v_cvt_pk_bf16_f32 v103, v86, v87
	v_cvt_pk_bf16_f32 v86, v80, v81
	v_pk_mul_f32 v[80:81], v[88:89], v[136:137] op_sel_hi:[0,1]
	v_mad_u64_u32 v[138:139], s[2:3], v82, s0, v[92:93]
	v_cvt_pk_bf16_f32 v126, v118, v119
	v_cvt_pk_bf16_f32 v127, v116, v117
	v_cvt_pk_bf16_f32 v128, v114, v115
	v_cvt_pk_bf16_f32 v110, v110, v111
	v_cvt_pk_bf16_f32 v111, v108, v109
	v_cvt_pk_bf16_f32 v112, v106, v107
	v_cvt_pk_bf16_f32 v87, v80, v81
	v_lshl_add_u32 v80, v82, 2, v92
	ds_write_b128 v138, v[126:129] offset:9216
	ds_write_b128 v138, v[110:113] offset:9232
	ds_write_b128 v138, v[102:105] offset:9248
	ds_write_b128 v138, v[84:87] offset:9264
	ds_write_b32 v80, v88 offset:19456
	ds_write_b128 v138, v[76:79] offset:14336
	ds_write_b128 v138, v[72:75] offset:14352
	ds_write_b128 v138, v[68:71] offset:14368
	ds_write_b128 v138, v[64:67] offset:14384
	s_waitcnt lgkmcnt(0)
	v_or_b32_e32 v88, v95, v124
	v_lshlrev_b64 v[64:65], 11, v[88:89]
	v_lshl_add_u64 v[64:65], s[16:17], 0, v[64:65]
	v_lshlrev_b32_e32 v80, 2, v125
	s_movk_i32 s48, 0x90
	v_lshl_add_u64 v[64:65], v[64:65], 0, v[90:91]
	v_ashrrev_i32_e32 v81, 31, v80
	v_mad_u32_u24 v88, v124, s48, v92
	v_lshl_add_u64 v[104:105], v[80:81], 1, v[64:65]
	v_lshl_add_u32 v81, v125, 4, v88
	ds_read_b128 v[64:67], v81 offset:4608
	ds_read_b128 v[68:71], v81
	ds_read_b128 v[82:85], v81 offset:32
	ds_read_b128 v[106:109], v81 offset:4640
	s_waitcnt lgkmcnt(2)
	v_mfma_f32_32x32x16_bf16 v[64:79], v[64:67], v[68:71], 0
	v_cmp_le_i32_e32 vcc, v80, v124
	v_cvt_pk_bf16_f32 v32, v32, v33
	v_cvt_pk_bf16_f32 v33, v34, v35
	v_cvt_pk_bf16_f32 v34, v36, v37
	v_cvt_pk_bf16_f32 v35, v38, v39
	v_cvt_pk_bf16_f32 v36, v48, v49
	v_cvt_pk_bf16_f32 v37, v50, v51
	s_waitcnt lgkmcnt(0)
	v_mfma_f32_32x32x16_bf16 v[64:79], v[106:109], v[82:85], v[64:79]
	ds_read_b128 v[82:85], v81 offset:4672
	ds_read_b128 v[106:109], v81 offset:64
	v_cvt_pk_bf16_f32 v38, v52, v53
	v_cvt_pk_bf16_f32 v39, v54, v55
	s_mov_b32 s6, 0x16f00000
	s_mov_b64 s[4:5], 0x16f00600
	v_lshl_add_u64 v[102:103], v[104:105], 0, s[4:5]
	s_waitcnt lgkmcnt(0)
	v_mfma_f32_32x32x16_bf16 v[64:79], v[82:85], v[106:109], v[64:79]
	ds_read_b128 v[82:85], v81 offset:4704
	ds_read_b128 v[106:109], v81 offset:96
	v_or_b32_e32 v81, 2, v80
	s_waitcnt lgkmcnt(0)
	v_mfma_f32_32x32x16_bf16 v[64:79], v[82:85], v[106:109], v[64:79]
	s_nop 11
	v_cndmask_b32_e32 v64, 0, v64, vcc
	v_cmp_lt_i32_e32 vcc, v80, v124
	s_nop 1
	v_cndmask_b32_e32 v65, 0, v65, vcc
	v_cmp_le_i32_e32 vcc, v81, v124
	v_or_b32_e32 v81, 3, v80
	v_cvt_pk_bf16_f32 v84, v64, v65
	v_cndmask_b32_e32 v66, 0, v66, vcc
	v_cmp_le_i32_e32 vcc, v81, v124
	v_add_u32_e32 v81, 8, v80
	v_lshlrev_b32_e32 v64, 3, v125
	v_cndmask_b32_e32 v67, 0, v67, vcc
	v_cmp_le_i32_e32 vcc, v81, v124
	v_add_u32_e32 v81, 9, v80
	v_mul_u32_u24_e32 v65, 0x50, v124
	v_cndmask_b32_e32 v68, 0, v68, vcc
	v_cmp_le_i32_e32 vcc, v81, v124
	v_add_u32_e32 v81, 10, v80
	v_add3_u32 v114, v92, v64, v65
	v_cndmask_b32_e32 v69, 0, v69, vcc
	v_cmp_le_i32_e32 vcc, v81, v124
	v_add_u32_e32 v81, 11, v80
	v_cvt_pk_bf16_f32 v86, v68, v69
	v_cndmask_b32_e32 v70, 0, v70, vcc
	v_cmp_le_i32_e32 vcc, v81, v124
	v_add_u32_e32 v81, 16, v80
	v_add_u32_e32 v68, 0x3800, v114
	v_cndmask_b32_e32 v71, 0, v71, vcc
	v_cmp_le_i32_e32 vcc, v81, v124
	v_add_u32_e32 v81, 17, v80
	v_cvt_pk_bf16_f32 v85, v66, v67
	v_cndmask_b32_e32 v72, 0, v72, vcc
	v_cmp_le_i32_e32 vcc, v81, v124
	v_add_u32_e32 v81, 18, v80
	v_add_u32_e32 v88, v88, v64
	v_cndmask_b32_e32 v73, 0, v73, vcc
	v_cmp_le_i32_e32 vcc, v81, v124
	v_add_u32_e32 v81, 19, v80
	ds_read2_b64 v[64:67], v68 offset1:2
	ds_read2_b64 v[106:109], v68 offset0:4 offset1:6
	v_cndmask_b32_e32 v74, 0, v74, vcc
	v_cmp_le_i32_e32 vcc, v81, v124
	v_add_u32_e32 v81, 24, v80
	v_cvt_pk_bf16_f32 v87, v70, v71
	v_cndmask_b32_e32 v75, 0, v75, vcc
	v_cmp_le_i32_e32 vcc, v81, v124
	v_add_u32_e32 v81, 25, v80
	s_nop 0
	v_cndmask_b32_e32 v76, 0, v76, vcc
	v_cmp_le_i32_e32 vcc, v81, v124
	v_add_u32_e32 v81, 26, v80
	v_add_u32_e32 v80, 27, v80
	v_cndmask_b32_e32 v77, 0, v77, vcc
	v_cmp_le_i32_e32 vcc, v81, v124
	v_cvt_pk_bf16_f32 v81, v74, v75
	v_cvt_pk_bf16_f32 v82, v76, v77
	v_cndmask_b32_e32 v78, 0, v78, vcc
	v_cmp_le_i32_e32 vcc, v80, v124
	v_cvt_pk_bf16_f32 v80, v72, v73
	s_nop 0
	v_cndmask_b32_e32 v79, 0, v79, vcc
	v_cvt_pk_bf16_f32 v83, v78, v79
	s_waitcnt lgkmcnt(1)
	v_mfma_f32_32x32x16_bf16 v[64:79], v[64:67], v[84:87], 0
	s_waitcnt lgkmcnt(0)
	v_mfma_f32_32x32x16_bf16 v[64:79], v[106:109], v[80:83], v[64:79]
	ds_read2_b64 v[106:109], v88 offset1:2
	ds_read2_b64 v[110:113], v88 offset0:4 offset1:6
	s_waitcnt lgkmcnt(1)
	v_mfma_f32_32x32x16_bf16 v[64:79], v[32:35], v[106:109], v[64:79]
	v_cvt_pk_bf16_f32 v32, v40, v41
	v_cvt_pk_bf16_f32 v33, v42, v43
	v_cvt_pk_bf16_f32 v34, v44, v45
	v_cvt_pk_bf16_f32 v35, v46, v47
	s_waitcnt lgkmcnt(0)
	s_nop 0
	v_mfma_f32_32x32x16_bf16 v[64:79], v[32:35], v[110:113], v[64:79]
	ds_read2_b64 v[32:35], v88 offset0:8 offset1:10
	s_waitcnt lgkmcnt(0)
	v_mfma_f32_32x32x16_bf16 v[64:79], v[36:39], v[32:35], v[64:79]
	ds_read2_b64 v[32:35], v88 offset0:12 offset1:14
	v_cvt_pk_bf16_f32 v36, v56, v57
	v_cvt_pk_bf16_f32 v37, v58, v59
	v_cvt_pk_bf16_f32 v38, v60, v61
	v_cvt_pk_bf16_f32 v39, v62, v63
	s_waitcnt lgkmcnt(0)
	s_nop 0
	v_mfma_f32_32x32x16_bf16 v[64:79], v[36:39], v[32:35], v[64:79]
	v_add_co_u32_e32 v34, vcc, s6, v104
	s_nop 1
	v_addc_co_u32_e32 v35, vcc, 0, v105, vcc
	s_nop 7
	v_cvt_pk_bf16_f32 v32, v64, v65
	v_cvt_pk_bf16_f32 v33, v66, v67
	global_store_dwordx2 v[34:35], v[32:33], off offset:1536
	v_cvt_pk_bf16_f32 v32, v68, v69
	v_cvt_pk_bf16_f32 v33, v70, v71
	global_store_dwordx2 v[102:103], v[32:33], off offset:16
	v_cvt_pk_bf16_f32 v32, v72, v73
	v_cvt_pk_bf16_f32 v33, v74, v75
	global_store_dwordx2 v[102:103], v[32:33], off offset:32
	v_cvt_pk_bf16_f32 v32, v76, v77
	v_cvt_pk_bf16_f32 v33, v78, v79
	global_store_dwordx2 v[102:103], v[32:33], off offset:48
	v_add_u32_e32 v48, 0x4000, v114
	ds_read2_b64 v[32:35], v48 offset0:64 offset1:66
	ds_read2_b64 v[48:51], v48 offset0:68 offset1:70
	ds_read2_b64 v[52:55], v88 offset1:2
	v_cvt_pk_bf16_f32 v0, v0, v1
	v_cvt_pk_bf16_f32 v1, v2, v3
	v_cvt_pk_bf16_f32 v2, v4, v5
	v_cvt_pk_bf16_f32 v3, v6, v7
	ds_read2_b64 v[4:7], v88 offset0:4 offset1:6
	v_cvt_pk_bf16_f32 v8, v8, v9
	v_cvt_pk_bf16_f32 v9, v10, v11
	s_waitcnt lgkmcnt(3)
	v_mfma_f32_32x32x16_bf16 v[32:47], v[32:35], v[84:87], 0
	v_cvt_pk_bf16_f32 v10, v12, v13
	v_cvt_pk_bf16_f32 v11, v14, v15
	v_cvt_pk_bf16_f32 v12, v16, v17
	v_cvt_pk_bf16_f32 v13, v18, v19
	v_cvt_pk_bf16_f32 v14, v20, v21
	v_cvt_pk_bf16_f32 v15, v22, v23
	s_waitcnt lgkmcnt(2)
	v_mfma_f32_32x32x16_bf16 v[32:47], v[48:51], v[80:83], v[32:47]
	s_waitcnt lgkmcnt(1)
	v_mfma_f32_32x32x16_bf16 v[32:47], v[0:3], v[52:55], v[32:47]
	ds_read2_b64 v[0:3], v88 offset0:8 offset1:10
	s_waitcnt lgkmcnt(1)
	v_mfma_f32_32x32x16_bf16 v[32:47], v[8:11], v[4:7], v[32:47]
	ds_read2_b64 v[4:7], v88 offset0:12 offset1:14
	v_cvt_pk_bf16_f32 v8, v24, v25
	v_cvt_pk_bf16_f32 v9, v26, v27
	v_cvt_pk_bf16_f32 v10, v28, v29
	v_cvt_pk_bf16_f32 v11, v30, v31
	s_waitcnt lgkmcnt(1)
	v_mfma_f32_32x32x16_bf16 v[32:47], v[12:15], v[0:3], v[32:47]
	s_waitcnt lgkmcnt(0)
	v_mfma_f32_32x32x16_bf16 v[32:47], v[8:11], v[4:7], v[32:47]
	s_nop 11
	v_cvt_pk_bf16_f32 v0, v32, v33
	v_cvt_pk_bf16_f32 v1, v34, v35
	v_cvt_pk_bf16_f32 v2, v36, v37
	v_cvt_pk_bf16_f32 v3, v38, v39
	v_cvt_pk_bf16_f32 v4, v40, v41
	v_cvt_pk_bf16_f32 v5, v42, v43
	v_cvt_pk_bf16_f32 v6, v44, v45
	v_cvt_pk_bf16_f32 v7, v46, v47
	global_store_dwordx2 v[102:103], v[0:1], off offset:64
	global_store_dwordx2 v[102:103], v[2:3], off offset:80
	global_store_dwordx2 v[102:103], v[4:5], off offset:96
	global_store_dwordx2 v[102:103], v[6:7], off offset:112
	s_waitcnt lgkmcnt(0)
	v_lshl_add_u64 v[0:1], s[44:45], 0, v[160:161]
	v_add_co_u32_e32 v2, vcc, s20, v0
	s_movk_i32 s11, 0x3000
	s_nop 0
	v_addc_co_u32_e32 v3, vcc, 0, v1, vcc
	v_add_co_u32_e32 v4, vcc, s11, v0
	s_movk_i32 s7, 0x4000
	s_nop 0
	v_addc_co_u32_e32 v5, vcc, 0, v1, vcc
	v_add_co_u32_e32 v0, vcc, s7, v0
	v_readlane_b32 s0, v255, 22
	s_nop 0
	v_addc_co_u32_e32 v1, vcc, 0, v1, vcc
	global_load_dword v24, v[2:3], off offset:3072
	global_load_dword v25, v[4:5], off offset:1024
	global_load_dword v26, v[4:5], off offset:3072
	global_load_dword v27, v[0:1], off offset:1024
	v_or_b32_e32 v0, 1, v148
	v_mad_i64_i32 v[0:1], s[2:3], v0, 36, v[96:97]
	v_lshlrev_b64 v[0:1], 13, v[0:1]
	v_readlane_b32 s1, v255, 23
	v_readlane_b32 s2, v255, 1
	v_readlane_b32 s3, v255, 2
	v_lshl_add_u64 v[0:1], s[0:1], 0, v[0:1]
	v_lshl_add_u64 v[0:1], v[0:1], 0, v[98:99]
	v_lshl_add_u64 v[0:1], v[0:1], 0, v[100:101]
	global_load_dwordx2 v[2:3], v[0:1], off
	global_load_dwordx2 v[4:5], v[0:1], off offset:16
	global_load_dwordx2 v[6:7], v[0:1], off offset:32
	global_load_dwordx2 v[8:9], v[0:1], off offset:48
	s_movk_i32 s0, 0x1000
	v_add_co_u32_e32 v10, vcc, s0, v0
	s_mov_b32 s1, 0xf149f2ca
	s_nop 0
	v_addc_co_u32_e32 v11, vcc, 0, v1, vcc
	global_load_dwordx2 v[12:13], v[10:11], off
	global_load_dwordx2 v[14:15], v[10:11], off offset:16
	global_load_dwordx2 v[16:17], v[10:11], off offset:32
	global_load_dwordx2 v[18:19], v[10:11], off offset:48
	global_load_dwordx2 v[20:21], v[0:1], off offset:64
	global_load_dwordx2 v[22:23], v[0:1], off offset:80
	global_load_dwordx2 v[58:59], v[0:1], off offset:96
	s_nop 0
	global_load_dwordx2 v[0:1], v[0:1], off offset:112
	s_nop 0
	global_load_dwordx2 v[64:65], v[10:11], off offset:64
	global_load_dwordx2 v[72:73], v[10:11], off offset:80
	global_load_dwordx2 v[76:77], v[10:11], off offset:96
	s_nop 0
	global_load_dwordx2 v[10:11], v[10:11], off offset:112
	s_mov_b64 s[40:41], s[44:45]
	s_mov_b64 s[12:13], s[44:45]
	s_waitcnt vmcnt(18)
	v_max3_f32 v28, v24, s1, v25
	s_waitcnt vmcnt(16)
	v_max3_f32 v28, v28, v26, v27
	v_sub_f32_e32 v25, v25, v28
	v_mul_f32_e32 v25, 0x3fb8aa3b, v25
	v_sub_f32_e32 v24, v24, v28
	v_sub_f32_e32 v26, v26, v28
	v_exp_f32_e32 v25, v25
	v_mul_f32_e32 v24, 0x3fb8aa3b, v24
	v_mul_f32_e32 v26, 0x3fb8aa3b, v26
	v_sub_f32_e32 v27, v27, v28
	v_exp_f32_e32 v50, v24
	v_exp_f32_e32 v51, v26
	v_mul_f32_e32 v27, 0x3fb8aa3b, v27
	v_exp_f32_e32 v52, v27
	s_waitcnt vmcnt(15)
	v_lshlrev_b32_e32 v32, 16, v2
	v_and_b32_e32 v33, 0xffff0000, v2
	v_add_f32_e32 v2, 0, v25
	v_cndmask_b32_e64 v2, v2, 0, s[2:3]
	v_readlane_b32 s2, v255, 3
	v_lshlrev_b32_e32 v34, 16, v3
	v_and_b32_e32 v35, 0xffff0000, v3
	s_waitcnt vmcnt(14)
	v_lshlrev_b32_e32 v36, 16, v4
	v_and_b32_e32 v37, 0xffff0000, v4
	v_add_f32_e32 v3, 0, v50
	v_add_f32_e32 v4, v51, v2
	v_readlane_b32 s3, v255, 4
	v_add_f32_e32 v3, v25, v3
	v_add_f32_e32 v3, v51, v3
	v_cndmask_b32_e64 v2, v4, v2, s[2:3]
	v_readlane_b32 s2, v255, 5
	v_add_f32_e32 v4, v52, v2
	v_readlane_b32 s3, v255, 6
	v_add_f32_e32 v3, v52, v3
	v_lshlrev_b32_e32 v38, 16, v5
	v_cndmask_b32_e64 v2, v4, v2, s[2:3]
	v_div_scale_f32 v4, s[2:3], v3, v3, v2
	v_and_b32_e32 v39, 0xffff0000, v5
	v_rcp_f32_e32 v5, v4
	s_waitcnt vmcnt(13)
	v_lshlrev_b32_e32 v42, 16, v7
	v_and_b32_e32 v43, 0xffff0000, v7
	v_lshlrev_b32_e32 v40, 16, v6
	v_fma_f32 v7, -v4, v5, 1.0
	v_and_b32_e32 v41, 0xffff0000, v6
	v_div_scale_f32 v6, vcc, v2, v3, v2
	v_fmac_f32_e32 v5, v7, v5
	v_mul_f32_e32 v7, v6, v5
	s_waitcnt vmcnt(12)
	v_lshlrev_b32_e32 v44, 16, v8
	v_and_b32_e32 v45, 0xffff0000, v8
	v_fma_f32 v8, -v4, v7, v6
	v_fmac_f32_e32 v7, v8, v5
	v_fma_f32 v4, -v4, v7, v6
	s_waitcnt vmcnt(9)
	v_lshlrev_b32_e32 v24, 16, v16
	v_and_b32_e32 v25, 0xffff0000, v16
	v_div_fmas_f32 v4, v4, v5, v7
	v_mov_b32_e32 v16, v94
	v_div_fixup_f32 v116, v4, v3, v2
	s_add_u32 s2, s40, 0xb200000
	v_lshlrev_b32_e32 v46, 16, v9
	v_and_b32_e32 v47, 0xffff0000, v9
	v_lshlrev_b32_e32 v26, 16, v12
	v_and_b32_e32 v27, 0xffff0000, v12
	v_lshlrev_b32_e32 v28, 16, v13
	v_and_b32_e32 v29, 0xffff0000, v13
	v_lshlrev_b32_e32 v30, 16, v14
	v_and_b32_e32 v31, 0xffff0000, v14
	v_lshlrev_b32_e32 v48, 16, v15
	v_and_b32_e32 v49, 0xffff0000, v15
	v_lshlrev_b32_e32 v84, 16, v17
	v_and_b32_e32 v85, 0xffff0000, v17
	s_waitcnt vmcnt(8)
	v_lshlrev_b32_e32 v86, 16, v18
	v_and_b32_e32 v87, 0xffff0000, v18
	v_lshlrev_b32_e32 v96, 16, v19
	v_and_b32_e32 v97, 0xffff0000, v19
	s_waitcnt vmcnt(7)
	v_lshlrev_b32_e32 v54, 16, v20
	v_and_b32_e32 v55, 0xffff0000, v20
	v_lshlrev_b32_e32 v50, 16, v21
	v_and_b32_e32 v51, 0xffff0000, v21
	s_waitcnt vmcnt(6)
	v_lshlrev_b32_e32 v52, 16, v22
	v_and_b32_e32 v53, 0xffff0000, v22
	v_lshlrev_b32_e32 v82, 16, v23
	v_and_b32_e32 v83, 0xffff0000, v23
	s_waitcnt vmcnt(5)
	v_lshlrev_b32_e32 v56, 16, v58
	v_and_b32_e32 v57, 0xffff0000, v58
	v_lshlrev_b32_e32 v58, 16, v59
	v_and_b32_e32 v59, 0xffff0000, v59
	s_waitcnt vmcnt(4)
	v_lshlrev_b32_e32 v60, 16, v0
	v_and_b32_e32 v61, 0xffff0000, v0
	v_lshlrev_b32_e32 v62, 16, v1
	v_and_b32_e32 v63, 0xffff0000, v1
	s_waitcnt vmcnt(3)
	v_lshlrev_b32_e32 v66, 16, v64
	v_and_b32_e32 v67, 0xffff0000, v64
	v_lshlrev_b32_e32 v68, 16, v65
	v_and_b32_e32 v69, 0xffff0000, v65
	s_waitcnt vmcnt(2)
	v_lshlrev_b32_e32 v70, 16, v72
	v_and_b32_e32 v71, 0xffff0000, v72
	v_lshlrev_b32_e32 v72, 16, v73
	v_and_b32_e32 v73, 0xffff0000, v73
	s_waitcnt vmcnt(1)
	v_lshlrev_b32_e32 v74, 16, v76
	v_and_b32_e32 v75, 0xffff0000, v76
	v_lshlrev_b32_e32 v76, 16, v77
	v_and_b32_e32 v77, 0xffff0000, v77
	s_waitcnt vmcnt(0)
	v_lshlrev_b32_e32 v78, 16, v10
	v_and_b32_e32 v79, 0xffff0000, v10
	v_lshlrev_b32_e32 v80, 16, v11
	v_and_b32_e32 v81, 0xffff0000, v11
	v_sub_f32_e32 v117, 1.0, v116
	v_and_b32_e32 v118, 31, v16
	v_ashrrev_i32_e32 v119, 5, v16
	s_addc_u32 s3, s41, 0
	v_mov_b64_e32 v[64:65], s[2:3]
	s_movk_i32 s1, 0x1200
	v_mad_i64_i32 v[0:1], s[2:3], v95, s1, v[64:65]
	v_ashrrev_i32_e32 v17, 31, v16
	v_lshl_add_u64 v[0:1], v[0:1], 0, v[90:91]
	v_lshl_add_u64 v[0:1], v[16:17], 1, v[0:1]
	s_mov_b32 s37, 0x23000
	v_add_co_u32_e32 v12, vcc, s37, v0
	s_movk_i32 s2, 0x5000
	s_nop 0
	v_addc_co_u32_e32 v13, vcc, 0, v1, vcc
	global_load_ushort v88, v[12:13], off offset:3072
	global_load_ushort v109, v[12:13], off offset:1536
	v_add_co_u32_e32 v2, vcc, s20, v0
	s_mov_b32 s28, 0x9000
	s_nop 0
	v_addc_co_u32_e32 v3, vcc, 0, v1, vcc
	v_add_co_u32_e32 v4, vcc, s2, v0
	s_movk_i32 s2, 0x7000
	s_nop 0
	v_addc_co_u32_e32 v5, vcc, 0, v1, vcc
	v_add_co_u32_e32 v6, vcc, s2, v0
	s_mov_b32 s29, 0xb000
	s_nop 0
	v_addc_co_u32_e32 v7, vcc, 0, v1, vcc
	v_add_co_u32_e32 v18, vcc, s28, v0
	s_mov_b32 s18, 0xe000
	s_nop 0
	v_addc_co_u32_e32 v19, vcc, 0, v1, vcc
	v_add_co_u32_e32 v20, vcc, s29, v0
	s_mov_b32 s2, 0x10000
	s_nop 0
	v_addc_co_u32_e32 v21, vcc, 0, v1, vcc
	v_add_co_u32_e32 v22, vcc, s18, v0
	s_mov_b32 s30, 0x17000
	s_nop 0
	v_addc_co_u32_e32 v23, vcc, 0, v1, vcc
	v_add_co_u32_e32 v98, vcc, s2, v0
	s_mov_b32 s2, 0x14000
	s_nop 0
	v_addc_co_u32_e32 v99, vcc, 0, v1, vcc
	v_add_co_u32_e32 v8, vcc, s51, v0
	s_mov_b32 s31, 0x19000
	s_nop 0
	v_addc_co_u32_e32 v9, vcc, 0, v1, vcc
	v_add_co_u32_e32 v10, vcc, s2, v0
	s_mov_b32 s34, 0x1b000
	s_nop 0
	v_addc_co_u32_e32 v11, vcc, 0, v1, vcc
	v_add_co_u32_e32 v14, vcc, s30, v0
	s_mov_b32 s35, 0x1d000
	s_nop 0
	v_addc_co_u32_e32 v15, vcc, 0, v1, vcc
	v_add_co_u32_e32 v100, vcc, s31, v0
	s_mov_b32 s19, 0x20000
	s_nop 0
	v_addc_co_u32_e32 v101, vcc, 0, v1, vcc
	v_add_co_u32_e32 v102, vcc, s34, v0
	s_mov_b32 s36, 0x22000
	s_nop 0
	v_addc_co_u32_e32 v103, vcc, 0, v1, vcc
	v_add_co_u32_e32 v104, vcc, s35, v0
	s_mov_b32 s21, 0x21000
	s_nop 0
	v_addc_co_u32_e32 v105, vcc, 0, v1, vcc
	v_add_co_u32_e32 v106, vcc, s19, v0
	s_mov_b32 s42, 0x1f000
	s_nop 0
	v_addc_co_u32_e32 v107, vcc, 0, v1, vcc
	v_add_co_u32_e32 v120, vcc, s36, v0
	s_mov_b32 s17, 0x1e000
	s_nop 0
	v_addc_co_u32_e32 v121, vcc, 0, v1, vcc
	v_add_co_u32_e32 v110, vcc, s21, v0
	s_mov_b32 s16, 0x1c000
	s_nop 0
	v_addc_co_u32_e32 v111, vcc, 0, v1, vcc
	global_load_ushort v113, v[110:111], off offset:512
	global_load_ushort v108, v[110:111], off offset:1024
	global_load_ushort v122, v[110:111], off offset:2048
	s_nop 0
	global_load_ushort v110, v[12:13], off offset:2048
	global_load_ushort v112, v[120:121], off offset:1536
	global_load_ushort v145, v[120:121], off offset:2560
	global_load_ushort v123, v[104:105], off offset:3584
	global_load_ushort v124, v[106:107], off offset:512
	global_load_ushort v154, v[120:121], off offset:1024
	global_load_ushort v155, v[106:107], off offset:1536
	global_load_ushort v156, v[106:107], off
	global_load_ushort v159, v[104:105], off offset:3072
	global_load_ushort v162, v[104:105], off
	global_load_ushort v166, v[102:103], off offset:3584
	s_waitcnt vmcnt(15)
	v_lshlrev_b32_e32 v12, 16, v88
	v_max_f32_e32 v12, v12, v12
	v_med3_f32 v12, v12, s9, v244
	v_mul_f32_e32 v12, 0xbfb8aa3b, v12
	v_exp_f32_e32 v88, v12
	v_add_co_u32_e32 v12, vcc, s42, v0
	s_mov_b32 s2, 0x1a000
	v_add_f32_e32 v111, 1.0, v88
	v_addc_co_u32_e32 v13, vcc, 0, v1, vcc
	v_rcp_f32_e32 v111, v111
	v_add_co_u32_e32 v136, vcc, s17, v0
	s_waitcnt vmcnt(14)
	v_lshlrev_b32_e32 v109, 16, v109
	v_addc_co_u32_e32 v137, vcc, 0, v1, vcc
	v_add_co_u32_e32 v134, vcc, s16, v0
	v_fma_f32 v114, v117, v111, v116
	s_nop 0
	v_addc_co_u32_e32 v135, vcc, 0, v1, vcc
	v_max_f32_e32 v152, 0xda24260, v114
	v_add_co_u32_e32 v120, vcc, s2, v0
	v_mul_f32_e32 v88, v88, v111
	v_rcp_f32_e32 v111, v152
	v_addc_co_u32_e32 v121, vcc, 0, v1, vcc
	s_mov_b32 s2, 0x18000
	v_add_co_u32_e32 v138, vcc, s2, v0
	s_mov_b32 s2, 0x16000
	s_nop 0
	v_addc_co_u32_e32 v139, vcc, 0, v1, vcc
	v_mul_f32_e32 v88, v117, v88
	v_mul_f32_e32 v109, v152, v109
	global_load_ushort v125, v[14:15], off offset:512
	global_load_ushort v127, v[100:101], off offset:1536
	global_load_ushort v128, v[102:103], off offset:2560
	global_load_ushort v167, v[102:103], off offset:2048
	global_load_ushort v169, v[100:101], off offset:2560
	global_load_ushort v172, v[100:101], off offset:1024
	global_load_ushort v168, v[14:15], off offset:1536
	global_load_ushort v164, v[14:15], off
	v_add_co_u32_e32 v14, vcc, s2, v0
	v_bfe_u32 v114, v109, 16, 1
	v_mul_f32_e32 v88, v88, v111
	v_addc_co_u32_e32 v15, vcc, 0, v1, vcc
	s_mov_b32 s43, 0x15000
	v_add3_u32 v153, v109, v114, s10
	v_bfe_u32 v109, v88, 16, 1
	v_add_co_u32_e32 v140, vcc, s43, v0
	v_add3_u32 v114, v88, v109, s10
	s_nop 0
	v_addc_co_u32_e32 v141, vcc, 0, v1, vcc
	global_load_ushort v126, v[22:23], off offset:512
	global_load_ushort v129, v[98:99], off offset:1536
	global_load_ushort v130, v[8:9], off offset:2560
	global_load_ushort v131, v[10:11], off offset:3584
	global_load_ushort v158, v[10:11], off offset:3072
	global_load_ushort v115, v[10:11], off
	global_load_ushort v111, v[8:9], off offset:3584
	global_load_ushort v109, v[8:9], off offset:2048
	global_load_ushort v173, v[12:13], off offset:1024
	global_load_ushort v174, v[136:137], off offset:3584
	global_load_ushort v175, v[134:135], off offset:2560
	global_load_ushort v176, v[120:121], off offset:1536
	global_load_ushort v133, v[120:121], off offset:2048
	s_nop 0
	global_load_ushort v134, v[134:135], off offset:3072
	s_nop 0
	global_load_ushort v177, v[136:137], off offset:512
	global_load_ushort v135, v[12:13], off
	global_load_ushort v178, v[120:121], off offset:3072
	global_load_ushort v171, v[138:139], off offset:2048
	global_load_ushort v170, v[138:139], off offset:512
	global_load_ushort v165, v[14:15], off offset:1024
	global_load_ushort v163, v[140:141], off offset:3584
	global_load_ushort v160, v[140:141], off offset:512
	global_load_ushort v137, v[14:15], off
	s_nop 0
	global_load_ushort v139, v[138:139], off offset:1024
	s_mov_b32 s44, 0x13000
	v_add_co_u32_e32 v146, vcc, s44, v0
	s_mov_b32 s45, 0x11000
	s_nop 0
	v_addc_co_u32_e32 v147, vcc, 0, v1, vcc
	v_add_co_u32_e32 v106, vcc, s45, v0
	s_mov_b32 s46, 0xf000
	s_nop 0
	v_addc_co_u32_e32 v107, vcc, 0, v1, vcc
	v_add_co_u32_e32 v102, vcc, s46, v0
	s_mov_b32 s47, 0xd000
	s_nop 0
	v_addc_co_u32_e32 v103, vcc, 0, v1, vcc
	v_add_co_u32_e32 v104, vcc, s47, v0
	s_mov_b32 s15, 0xa000
	s_nop 0
	v_addc_co_u32_e32 v105, vcc, 0, v1, vcc
	v_add_co_u32_e32 v100, vcc, s15, v0
	s_mov_b32 s14, 0x8000
	s_waitcnt vmcnt(40)
	v_lshlrev_b32_e32 v8, 16, v145
	v_max_f32_e32 v8, v8, v8
	v_med3_f32 v8, v8, s9, v244
	v_mul_f32_e32 v8, 0xbfb8aa3b, v8
	v_exp_f32_e32 v88, v8
	v_addc_co_u32_e32 v101, vcc, 0, v1, vcc
	v_lshlrev_b32_e32 v122, 16, v122
	v_add_f32_e32 v120, 1.0, v88
	v_rcp_f32_e32 v120, v120
	v_add_co_u32_e32 v10, vcc, s14, v0
	v_max_f32_e32 v122, v122, v122
	v_fma_f32 v121, v117, v120, v116
	v_mul_f32_e32 v121, v152, v121
	v_addc_co_u32_e32 v11, vcc, 0, v1, vcc
	v_max_f32_e32 v121, 0xda24260, v121
	v_med3_f32 v122, v122, s9, v244
	v_add_co_u32_e32 v12, vcc, s27, v0
	v_rcp_f32_e32 v152, v121
	v_mul_f32_e32 v122, 0xbfb8aa3b, v122
	v_addc_co_u32_e32 v13, vcc, 0, v1, vcc
	v_exp_f32_e32 v122, v122
	v_add_co_u32_e32 v14, vcc, s7, v0
	v_mul_f32_e32 v88, v88, v120
	s_nop 0
	v_addc_co_u32_e32 v15, vcc, 0, v1, vcc
	v_mul_f32_e32 v88, v117, v88
	v_add_co_u32_e32 v8, vcc, s0, v0
	v_mul_f32_e32 v88, v88, v152
	global_load_ushort v132, v[0:1], off offset:2560
	global_load_ushort v136, v[2:3], off offset:3584
	global_load_ushort v138, v[4:5], off offset:512
	global_load_ushort v140, v[6:7], off offset:1536
	global_load_ushort v141, v[18:19], off offset:2560
	global_load_ushort v143, v[20:21], off offset:3584
	global_load_ushort v144, v[22:23], off offset:-4096
	global_load_ushort v142, v[4:5], off offset:-4096
	v_addc_co_u32_e32 v9, vcc, 0, v1, vcc
	global_load_ushort v157, v[146:147], off offset:2560
	global_load_ushort v150, v[146:147], off offset:3072
	global_load_ushort v151, v[106:107], off offset:2048
	global_load_ushort v149, v[102:103], off offset:1024
	global_load_ushort v148, v[100:101], off offset:3072
	s_nop 0
	global_load_ushort v146, v[10:11], off offset:2048
	global_load_ushort v147, v[12:13], off offset:1024
	global_load_ushort v145, v[8:9], off offset:3072
	s_mov_b32 s101, 0
	s_mov_b32 s100, 0xa000
	v_lshl_add_u64 v[196:197], v[0:1], 0, s[100:101]
	global_load_ushort v200, v[196:197], off offset:-2048
	global_load_ushort v201, v[196:197], off offset:-512
	global_load_ushort v202, v[196:197], off offset:2560
	s_mov_b32 s100, 0xb800
	v_lshl_add_u64 v[198:199], v[0:1], 0, s[100:101]
	global_load_ushort v203, v[198:199], off offset:-2048
	global_load_ushort v206, v[198:199], off offset:1024
	global_load_ushort v207, v[198:199], off offset:2560
	s_mov_b32 s100, 0xd600
	v_lshl_add_u64 v[196:197], v[0:1], 0, s[100:101]
	global_load_ushort v208, v[196:197], off offset:-2048
	global_load_ushort v209, v[196:197], off offset:-512
	global_load_ushort v210, v[196:197], off offset:2560
	s_mov_b32 s100, 0xee00
	v_lshl_add_u64 v[198:199], v[0:1], 0, s[100:101]
	global_load_ushort v211, v[198:199], off offset:-2048
	global_load_ushort v212, v[198:199], off offset:1024
	global_load_ushort v213, v[198:199], off offset:2560
	s_mov_b32 s100, 0x10c00
	v_lshl_add_u64 v[196:197], v[0:1], 0, s[100:101]
	global_load_ushort v214, v[196:197], off offset:-2048
	global_load_ushort v215, v[196:197], off offset:-512
	global_load_ushort v216, v[196:197], off offset:2560
	s_mov_b32 s100, 0x12400
	v_lshl_add_u64 v[198:199], v[0:1], 0, s[100:101]
	global_load_ushort v217, v[198:199], off offset:-2048
	s_mov_b32 s100, 0x1000
	v_lshl_add_u64 v[196:197], v[0:1], 0, s[100:101]
	global_load_ushort v218, v[196:197], off offset:-2048
	global_load_ushort v219, v[196:197], off offset:-512
	global_load_ushort v220, v[196:197], off offset:2560
	s_mov_b32 s100, 0x2800
	v_lshl_add_u64 v[198:199], v[0:1], 0, s[100:101]
	global_load_ushort v221, v[198:199], off offset:-2048
	global_load_ushort v222, v[198:199], off offset:1024
	global_load_ushort v223, v[198:199], off offset:2560
	s_mov_b32 s100, 0x4600
	v_lshl_add_u64 v[196:197], v[0:1], 0, s[100:101]
	global_load_ushort v224, v[196:197], off offset:-2048
	global_load_ushort v225, v[196:197], off offset:-512
	global_load_ushort v226, v[196:197], off offset:2560
	s_mov_b32 s100, 0x5e00
	v_lshl_add_u64 v[198:199], v[0:1], 0, s[100:101]
	global_load_ushort v227, v[198:199], off offset:-2048
	global_load_ushort v228, v[198:199], off offset:1024
	global_load_ushort v229, v[198:199], off offset:2560
	s_mov_b32 s100, 0x7c00
	v_lshl_add_u64 v[196:197], v[0:1], 0, s[100:101]
	global_load_ushort v230, v[196:197], off offset:-2048
	global_load_ushort v231, v[196:197], off offset:-512
	global_load_ushort v232, v[196:197], off offset:2560
	s_mov_b32 s100, 0x9400
	v_lshl_add_u64 v[198:199], v[0:1], 0, s[100:101]
	global_load_ushort v233, v[198:199], off offset:-2048
	v_bfe_u32 v120, v88, 16, 1
	v_add_f32_e32 v152, 1.0, v122
	v_add3_u32 v88, v88, v120, s10
	s_waitcnt vmcnt(63)
	v_lshlrev_b32_e32 v120, 16, v154
	v_rcp_f32_e32 v152, v152
	v_lshl_add_u32 v17, v16, 1, v92
	v_mul_f32_e32 v120, v121, v120
	ds_write_b16_d16_hi v17, v153 offset:4464
	v_bfe_u32 v153, v120, 16, 1
	v_add3_u32 v120, v120, v153, s10
	ds_write_b16_d16_hi v17, v120 offset:4320
	v_fma_f32 v120, v117, v152, v116
	v_mul_f32_e32 v120, v121, v120
	v_mul_f32_e32 v122, v122, v152
	s_waitcnt vmcnt(63)
	v_lshlrev_b32_e32 v152, 16, v155
	v_max_f32_e32 v120, 0xda24260, v120
	v_max_f32_e32 v152, v152, v152
	v_rcp_f32_e32 v121, v120
	v_med3_f32 v152, v152, s9, v244
	v_mul_f32_e32 v152, 0xbfb8aa3b, v152
	v_exp_f32_e32 v152, v152
	v_mul_f32_e32 v122, v117, v122
	v_mul_f32_e32 v121, v122, v121
	v_bfe_u32 v122, v121, 16, 1
	v_add3_u32 v153, v121, v122, s10
	v_add_f32_e32 v121, 1.0, v152
	v_lshlrev_b32_e32 v113, 16, v113
	v_rcp_f32_e32 v121, v121
	v_mul_f32_e32 v113, v120, v113
	v_bfe_u32 v122, v113, 16, 1
	v_add3_u32 v113, v113, v122, s10
	ds_write_b16_d16_hi v17, v113 offset:4176
	v_fma_f32 v113, v117, v121, v116
	s_waitcnt vmcnt(63)
	v_lshlrev_b32_e32 v122, 16, v173
	v_mul_f32_e32 v113, v120, v113
	v_max_f32_e32 v122, v122, v122
	v_max_f32_e32 v113, 0xda24260, v113
	v_med3_f32 v122, v122, s9, v244
	v_rcp_f32_e32 v120, v113
	v_mul_f32_e32 v122, 0xbfb8aa3b, v122
	v_exp_f32_e32 v122, v122
	v_mul_f32_e32 v121, v152, v121
	v_mul_f32_e32 v121, v117, v121
	v_mul_f32_e32 v120, v121, v120
	v_bfe_u32 v121, v120, 16, 1
	v_add_f32_e32 v152, 1.0, v122
	v_add3_u32 v120, v120, v121, s10
	v_lshlrev_b32_e32 v121, 16, v156
	v_rcp_f32_e32 v152, v152
	v_mul_f32_e32 v121, v113, v121
	v_bfe_u32 v154, v121, 16, 1
	v_add3_u32 v121, v121, v154, s10
	ds_write_b16_d16_hi v17, v121 offset:4032
	v_fma_f32 v121, v117, v152, v116
	v_mul_f32_e32 v113, v113, v121
	v_mul_f32_e32 v122, v122, v152
	s_waitcnt vmcnt(57)
	v_lshlrev_b32_e32 v152, 16, v177
	v_max_f32_e32 v113, 0xda24260, v113
	v_max_f32_e32 v152, v152, v152
	v_rcp_f32_e32 v121, v113
	v_med3_f32 v152, v152, s9, v244
	v_mul_f32_e32 v152, 0xbfb8aa3b, v152
	v_exp_f32_e32 v152, v152
	v_mul_f32_e32 v122, v117, v122
	v_mul_f32_e32 v121, v122, v121
	v_bfe_u32 v122, v121, 16, 1
	v_add3_u32 v154, v121, v122, s10
	v_add_f32_e32 v122, 1.0, v152
	v_lshlrev_b32_e32 v121, 16, v174
	v_rcp_f32_e32 v122, v122
	v_mul_f32_e32 v121, v113, v121
	v_bfe_u32 v155, v121, 16, 1
	v_add3_u32 v121, v121, v155, s10
	ds_write_b16_d16_hi v17, v121 offset:3888
	v_fma_f32 v121, v117, v122, v116
	v_mul_f32_e32 v122, v152, v122
	v_lshlrev_b32_e32 v152, 16, v162
	v_mul_f32_e32 v113, v113, v121
	v_max_f32_e32 v152, v152, v152
	v_max_f32_e32 v113, 0xda24260, v113
	v_med3_f32 v152, v152, s9, v244
	v_rcp_f32_e32 v121, v113
	v_mul_f32_e32 v152, 0xbfb8aa3b, v152
	v_exp_f32_e32 v152, v152
	v_mul_f32_e32 v122, v117, v122
	v_mul_f32_e32 v121, v122, v121
	v_bfe_u32 v122, v121, 16, 1
	v_add_f32_e32 v155, 1.0, v152
	v_add3_u32 v121, v121, v122, s10
	v_lshlrev_b32_e32 v122, 16, v159
	v_rcp_f32_e32 v155, v155
	v_mul_f32_e32 v122, v113, v122
	v_bfe_u32 v156, v122, 16, 1
	v_add3_u32 v122, v122, v156, s10
	ds_write_b16_d16_hi v17, v122 offset:3744
	v_fma_f32 v122, v117, v155, v116
	v_mul_f32_e32 v113, v113, v122
	v_mul_f32_e32 v152, v152, v155
	v_lshlrev_b32_e32 v155, 16, v166
	v_max_f32_e32 v113, 0xda24260, v113
	v_max_f32_e32 v155, v155, v155
	v_rcp_f32_e32 v122, v113
	v_med3_f32 v155, v155, s9, v244
	v_mul_f32_e32 v155, 0xbfb8aa3b, v155
	v_exp_f32_e32 v156, v155
	v_mul_f32_e32 v152, v117, v152
	v_mul_f32_e32 v122, v152, v122
	v_bfe_u32 v152, v122, 16, 1
	v_add3_u32 v155, v122, v152, s10
	v_add_f32_e32 v152, 1.0, v156
	v_lshlrev_b32_e32 v122, 16, v175
	v_rcp_f32_e32 v152, v152
	v_mul_f32_e32 v122, v113, v122
	v_bfe_u32 v159, v122, 16, 1
	v_add3_u32 v122, v122, v159, s10
	ds_write_b16_d16_hi v17, v122 offset:3600
	v_fma_f32 v122, v117, v152, v116
	v_mul_f32_e32 v113, v113, v122
	v_max_f32_e32 v113, 0xda24260, v113
	v_rcp_f32_e32 v122, v113
	v_mul_f32_e32 v152, v156, v152
	v_mul_f32_e32 v152, v117, v152
	ds_write_b16_d16_hi v17, v114 offset:9072
	v_mul_f32_e32 v122, v152, v122
	v_bfe_u32 v152, v122, 16, 1
	v_add3_u32 v122, v122, v152, s10
	v_lshlrev_b32_e32 v152, 16, v167
	v_mul_f32_e32 v152, v113, v152
	v_bfe_u32 v156, v152, 16, 1
	v_add3_u32 v152, v152, v156, s10
	ds_write_b16_d16_hi v17, v88 offset:8928
	ds_write_b16_d16_hi v17, v153 offset:8784
	ds_write_b16_d16_hi v17, v120 offset:8640
	ds_write_b16_d16_hi v17, v154 offset:8496
	ds_write_b16_d16_hi v17, v121 offset:8352
	ds_write_b16_d16_hi v17, v155 offset:8208
	ds_write_b16_d16_hi v17, v152 offset:3456
	ds_write_b16_d16_hi v17, v122 offset:8064
	s_waitcnt vmcnt(55)
	v_lshlrev_b32_e32 v152, 16, v178
	v_max_f32_e32 v152, v152, v152
	v_med3_f32 v152, v152, s9, v244
	v_mul_f32_e32 v152, 0xbfb8aa3b, v152
	v_exp_f32_e32 v152, v152
	v_lshlrev_b32_e32 v109, 16, v109
	v_add_f32_e32 v156, 1.0, v152
	v_rcp_f32_e32 v156, v156
	s_nop 0
	v_fma_f32 v159, v117, v156, v116
	v_mul_f32_e32 v113, v113, v159
	v_max_f32_e32 v113, 0xda24260, v113
	v_mul_f32_e32 v152, v152, v156
	v_rcp_f32_e32 v156, v113
	v_mul_f32_e32 v152, v117, v152
	v_mul_f32_e32 v152, v152, v156
	v_bfe_u32 v156, v152, 16, 1
	v_add3_u32 v156, v152, v156, s10
	v_lshlrev_b32_e32 v152, 16, v176
	v_mul_f32_e32 v152, v113, v152
	v_bfe_u32 v159, v152, 16, 1
	v_add3_u32 v152, v152, v159, s10
	ds_write_b16_d16_hi v17, v152 offset:3312
	ds_write_b16_d16_hi v17, v156 offset:7920
	v_lshlrev_b32_e32 v152, 16, v169
	v_max_f32_e32 v152, v152, v152
	v_med3_f32 v152, v152, s9, v244
	v_mul_f32_e32 v152, 0xbfb8aa3b, v152
	v_exp_f32_e32 v152, v152
	s_nop 0
	v_add_f32_e32 v159, 1.0, v152
	v_rcp_f32_e32 v159, v159
	s_nop 0
	v_fma_f32 v162, v117, v159, v116
	v_mul_f32_e32 v113, v113, v162
	v_max_f32_e32 v173, 0xda24260, v113
	v_rcp_f32_e32 v113, v173
	v_mul_f32_e32 v152, v152, v159
	v_mul_f32_e32 v152, v117, v152
	v_mul_f32_e32 v113, v152, v113
	v_bfe_u32 v152, v113, 16, 1
	v_add3_u32 v152, v113, v152, s10
	v_lshlrev_b32_e32 v113, 16, v172
	v_mul_f32_e32 v113, v173, v113
	v_bfe_u32 v159, v113, 16, 1
	v_add3_u32 v172, v113, v159, s10
	s_nop 0
	s_nop 0
	v_add_co_u32_e32 v22, vcc, s50, v0
	s_nop 1
	v_addc_co_u32_e32 v23, vcc, 0, v1, vcc
	s_nop 0
	s_nop 0
	s_waitcnt vmcnt(54)
	v_lshlrev_b32_e32 v18, 16, v171
	v_max_f32_e32 v18, v18, v18
	v_med3_f32 v18, v18, s9, v244
	v_mul_f32_e32 v18, 0xbfb8aa3b, v18
	v_exp_f32_e32 v18, v18
	ds_write_b16_d16_hi v17, v172 offset:3168
	ds_write_b16_d16_hi v17, v152 offset:7776
	v_add_f32_e32 v22, 1.0, v18
	v_rcp_f32_e32 v22, v22
	s_nop 0
	v_fma_f32 v23, v117, v22, v116
	v_mul_f32_e32 v18, v18, v22
	v_mul_f32_e32 v22, v173, v23
	v_max_f32_e32 v22, 0xda24260, v22
	v_rcp_f32_e32 v23, v22
	v_mul_f32_e32 v18, v117, v18
	v_mul_f32_e32 v18, v18, v23
	v_bfe_u32 v23, v18, 16, 1
	v_add3_u32 v23, v18, v23, s10
	s_waitcnt vmcnt(53)
	v_lshlrev_b32_e32 v18, 16, v170
	v_mul_f32_e32 v18, v22, v18
	v_bfe_u32 v100, v18, 16, 1
	v_add3_u32 v18, v18, v100, s10
	ds_write_b16_d16_hi v17, v18 offset:3024
	ds_write_b16_d16_hi v17, v23 offset:7632
	v_lshlrev_b32_e32 v18, 16, v168
	v_max_f32_e32 v18, v18, v18
	v_med3_f32 v18, v18, s9, v244
	v_mul_f32_e32 v18, 0xbfb8aa3b, v18
	v_exp_f32_e32 v18, v18
	s_nop 0
	v_add_f32_e32 v100, 1.0, v18
	v_rcp_f32_e32 v100, v100
	s_nop 0
	v_fma_f32 v101, v117, v100, v116
	v_mul_f32_e32 v22, v22, v101
	v_max_f32_e32 v22, 0xda24260, v22
	v_mul_f32_e32 v18, v18, v100
	v_rcp_f32_e32 v100, v22
	v_mul_f32_e32 v18, v117, v18
	v_mul_f32_e32 v18, v18, v100
	v_bfe_u32 v100, v18, 16, 1
	v_add3_u32 v18, v18, v100, s10
	v_lshlrev_b32_e32 v100, 16, v164
	v_mul_f32_e32 v100, v22, v100
	v_bfe_u32 v101, v100, 16, 1
	v_add3_u32 v100, v100, v101, s10
	ds_write_b16_d16_hi v17, v100 offset:2880
	ds_write_b16_d16_hi v17, v18 offset:7488
	s_waitcnt vmcnt(52)
	v_lshlrev_b32_e32 v100, 16, v165
	v_max_f32_e32 v100, v100, v100
	v_med3_f32 v100, v100, s9, v244
	v_mul_f32_e32 v100, 0xbfb8aa3b, v100
	v_exp_f32_e32 v100, v100
	s_nop 0
	v_add_f32_e32 v101, 1.0, v100
	v_rcp_f32_e32 v101, v101
	s_nop 0
	v_fma_f32 v105, v117, v101, v116
	v_mul_f32_e32 v22, v22, v105
	v_max_f32_e32 v22, 0xda24260, v22
	v_mul_f32_e32 v100, v100, v101
	v_rcp_f32_e32 v101, v22
	v_mul_f32_e32 v100, v117, v100
	v_mul_f32_e32 v100, v100, v101
	v_bfe_u32 v101, v100, 16, 1
	v_add3_u32 v101, v100, v101, s10
	s_waitcnt vmcnt(51)
	v_lshlrev_b32_e32 v100, 16, v163
	v_mul_f32_e32 v100, v22, v100
	v_bfe_u32 v105, v100, 16, 1
	v_add3_u32 v100, v100, v105, s10
	ds_write_b16_d16_hi v17, v100 offset:2736
	ds_write_b16_d16_hi v17, v101 offset:7344
	s_waitcnt vmcnt(50)
	v_lshlrev_b32_e32 v100, 16, v160
	v_max_f32_e32 v100, v100, v100
	v_med3_f32 v100, v100, s9, v244
	v_mul_f32_e32 v100, 0xbfb8aa3b, v100
	v_exp_f32_e32 v100, v100
	s_nop 0
	v_add_f32_e32 v105, 1.0, v100
	v_rcp_f32_e32 v105, v105
	s_nop 0
	v_fma_f32 v160, v117, v105, v116
	v_mul_f32_e32 v22, v22, v160
	v_mul_f32_e32 v100, v100, v105
	v_max_f32_e32 v105, 0xda24260, v22
	v_rcp_f32_e32 v22, v105
	v_mul_f32_e32 v100, v117, v100
	v_mul_f32_e32 v22, v100, v22
	v_bfe_u32 v100, v22, 16, 1
	v_add3_u32 v22, v22, v100, s10
	v_lshlrev_b32_e32 v100, 16, v158
	v_mul_f32_e32 v100, v105, v100
	v_bfe_u32 v158, v100, 16, 1
	v_add3_u32 v100, v100, v158, s10
	ds_write_b16_d16_hi v17, v100 offset:2592
	ds_write_b16_d16_hi v17, v22 offset:7200
	v_lshlrev_b32_e32 v100, 16, v115
	v_max_f32_e32 v100, v100, v100
	v_med3_f32 v100, v100, s9, v244
	v_mul_f32_e32 v100, 0xbfb8aa3b, v100
	v_exp_f32_e32 v100, v100
	s_nop 0
	v_add_f32_e32 v115, 1.0, v100
	v_rcp_f32_e32 v115, v115
	s_nop 0
	v_fma_f32 v158, v117, v115, v116
	v_mul_f32_e32 v105, v105, v158
	v_mul_f32_e32 v100, v100, v115
	v_max_f32_e32 v115, 0xda24260, v105
	v_rcp_f32_e32 v105, v115
	v_mul_f32_e32 v100, v117, v100
	v_mul_f32_e32 v100, v100, v105
	v_bfe_u32 v105, v100, 16, 1
	v_add3_u32 v105, v100, v105, s10
	s_waitcnt vmcnt(39)
	v_lshlrev_b32_e32 v100, 16, v157
	v_mul_f32_e32 v100, v115, v100
	v_bfe_u32 v157, v100, 16, 1
	v_add3_u32 v100, v100, v157, s10
	ds_write_b16_d16_hi v17, v100 offset:2448
	ds_write_b16_d16_hi v17, v105 offset:7056
	v_lshlrev_b32_e32 v100, 16, v111
	v_max_f32_e32 v100, v100, v100
	v_med3_f32 v100, v100, s9, v244
	v_mul_f32_e32 v100, 0xbfb8aa3b, v100
	v_exp_f32_e32 v100, v100
	s_nop 0
	v_add_f32_e32 v111, 1.0, v100
	v_rcp_f32_e32 v111, v111
	s_nop 0
	v_fma_f32 v157, v117, v111, v116
	v_mul_f32_e32 v100, v100, v111
	v_mul_f32_e32 v111, v115, v157
	v_max_f32_e32 v111, 0xda24260, v111
	v_rcp_f32_e32 v115, v111
	v_mul_f32_e32 v100, v117, v100
	v_mul_f32_e32 v109, v111, v109
	v_mul_f32_e32 v100, v100, v115
	v_bfe_u32 v115, v100, 16, 1
	v_add3_u32 v100, v100, v115, s10
	v_bfe_u32 v115, v109, 16, 1
	v_add3_u32 v109, v109, v115, s10
	ds_write_b16_d16_hi v17, v109 offset:2304
	ds_write_b16_d16_hi v17, v100 offset:6912
	s_waitcnt vmcnt(16)
	v_lshlrev_b32_e32 v109, 16, v217
	v_max_f32_e32 v109, v109, v109
	v_med3_f32 v109, v109, s9, v244
	v_mul_f32_e32 v109, 0xbfb8aa3b, v109
	v_exp_f32_e32 v109, v109
	s_nop 0
	v_add_f32_e32 v115, 1.0, v109
	v_rcp_f32_e32 v115, v115
	s_nop 0
	v_fma_f32 v157, v117, v115, v116
	v_mul_f32_e32 v111, v111, v157
	v_max_f32_e32 v111, 0xda24260, v111
	v_mul_f32_e32 v109, v109, v115
	v_rcp_f32_e32 v115, v111
	v_mul_f32_e32 v109, v117, v109
	v_mul_f32_e32 v109, v109, v115
	v_bfe_u32 v115, v109, 16, 1
	v_add3_u32 v109, v109, v115, s10
	s_waitcnt vmcnt(16)
	v_lshlrev_b32_e32 v115, 16, v216
	v_mul_f32_e32 v115, v111, v115
	v_bfe_u32 v157, v115, 16, 1
	v_add3_u32 v115, v115, v157, s10
	ds_write_b16_d16_hi v17, v115 offset:2160
	ds_write_b16_d16_hi v17, v109 offset:6768
	s_waitcnt vmcnt(16)
	v_lshlrev_b32_e32 v115, 16, v215
	v_max_f32_e32 v115, v115, v115
	v_med3_f32 v115, v115, s9, v244
	v_mul_f32_e32 v115, 0xbfb8aa3b, v115
	v_exp_f32_e32 v115, v115
	v_add_co_u32_e32 v4, vcc, s11, v0
	v_add_f32_e32 v157, 1.0, v115
	v_rcp_f32_e32 v157, v157
	v_addc_co_u32_e32 v5, vcc, 0, v1, vcc
	v_fma_f32 v158, v117, v157, v116
	v_mul_f32_e32 v111, v111, v158
	v_max_f32_e32 v111, 0xda24260, v111
	v_mul_f32_e32 v115, v115, v157
	v_rcp_f32_e32 v157, v111
	v_mul_f32_e32 v115, v117, v115
	v_mul_f32_e32 v115, v115, v157
	v_bfe_u32 v157, v115, 16, 1
	v_add3_u32 v157, v115, v157, s10
	s_waitcnt vmcnt(16)
	v_lshlrev_b32_e32 v115, 16, v214
	v_mul_f32_e32 v115, v111, v115
	v_bfe_u32 v158, v115, 16, 1
	v_add3_u32 v115, v115, v158, s10
	s_waitcnt vmcnt(16)
	v_lshlrev_b32_e32 v0, 16, v213
	v_max_f32_e32 v0, v0, v0
	v_med3_f32 v0, v0, s9, v244
	v_mul_f32_e32 v0, 0xbfb8aa3b, v0
	v_exp_f32_e32 v0, v0
	ds_write_b16_d16_hi v17, v115 offset:2016
	ds_write_b16_d16_hi v17, v157 offset:6624
	v_add_f32_e32 v1, 1.0, v0
	v_rcp_f32_e32 v1, v1
	s_nop 0
	v_fma_f32 v2, v117, v1, v116
	v_mul_f32_e32 v0, v0, v1
	v_mul_f32_e32 v1, v111, v2
	v_max_f32_e32 v1, 0xda24260, v1
	v_rcp_f32_e32 v2, v1
	v_mul_f32_e32 v0, v117, v0
	v_mul_f32_e32 v0, v0, v2
	v_bfe_u32 v2, v0, 16, 1
	v_add3_u32 v0, v0, v2, s10
	s_waitcnt vmcnt(16)
	v_lshlrev_b32_e32 v2, 16, v212
	v_mul_f32_e32 v2, v1, v2
	v_bfe_u32 v3, v2, 16, 1
	v_add3_u32 v2, v2, v3, s10
	ds_write_b16_d16_hi v17, v2 offset:1872
	ds_write_b16_d16_hi v17, v0 offset:6480
	s_waitcnt vmcnt(16)
	v_lshlrev_b32_e32 v2, 16, v211
	v_max_f32_e32 v2, v2, v2
	v_med3_f32 v2, v2, s9, v244
	v_mul_f32_e32 v2, 0xbfb8aa3b, v2
	v_exp_f32_e32 v2, v2
	s_nop 0
	v_add_f32_e32 v3, 1.0, v2
	v_rcp_f32_e32 v3, v3
	s_nop 0
	v_fma_f32 v4, v117, v3, v116
	v_mul_f32_e32 v1, v1, v4
	v_max_f32_e32 v1, 0xda24260, v1
	v_mul_f32_e32 v2, v2, v3
	v_rcp_f32_e32 v3, v1
	v_mul_f32_e32 v2, v117, v2
	v_mul_f32_e32 v2, v2, v3
	v_bfe_u32 v3, v2, 16, 1
	v_add3_u32 v159, v2, v3, s10
	s_waitcnt vmcnt(16)
	v_lshlrev_b32_e32 v2, 16, v210
	v_mul_f32_e32 v2, v1, v2
	v_bfe_u32 v3, v2, 16, 1
	v_add3_u32 v2, v2, v3, s10
	ds_write_b16_d16_hi v17, v2 offset:1728
	ds_write_b16_d16_hi v17, v159 offset:6336
	s_waitcnt vmcnt(16)
	v_lshlrev_b32_e32 v2, 16, v209
	v_max_f32_e32 v2, v2, v2
	v_med3_f32 v2, v2, s9, v244
	v_mul_f32_e32 v2, 0xbfb8aa3b, v2
	v_exp_f32_e32 v2, v2
	s_nop 0
	v_add_f32_e32 v3, 1.0, v2
	v_rcp_f32_e32 v3, v3
	s_nop 0
	v_fma_f32 v4, v117, v3, v116
	v_mul_f32_e32 v1, v1, v4
	v_max_f32_e32 v1, 0xda24260, v1
	v_mul_f32_e32 v2, v2, v3
	v_rcp_f32_e32 v3, v1
	v_mul_f32_e32 v2, v117, v2
	v_mul_f32_e32 v2, v2, v3
	v_bfe_u32 v3, v2, 16, 1
	v_add3_u32 v2, v2, v3, s10
	s_waitcnt vmcnt(16)
	v_lshlrev_b32_e32 v3, 16, v208
	v_mul_f32_e32 v3, v1, v3
	v_bfe_u32 v4, v3, 16, 1
	v_add3_u32 v3, v3, v4, s10
	ds_write_b16_d16_hi v17, v3 offset:1584
	ds_write_b16_d16_hi v17, v2 offset:6192
	s_waitcnt vmcnt(16)
	v_lshlrev_b32_e32 v3, 16, v207
	v_max_f32_e32 v3, v3, v3
	v_med3_f32 v3, v3, s9, v244
	v_mul_f32_e32 v3, 0xbfb8aa3b, v3
	v_exp_f32_e32 v3, v3
	s_nop 0
	v_add_f32_e32 v4, 1.0, v3
	v_rcp_f32_e32 v4, v4
	s_nop 0
	v_fma_f32 v5, v117, v4, v116
	v_mul_f32_e32 v1, v1, v5
	v_max_f32_e32 v1, 0xda24260, v1
	v_mul_f32_e32 v3, v3, v4
	v_rcp_f32_e32 v4, v1
	v_mul_f32_e32 v3, v117, v3
	v_mul_f32_e32 v3, v3, v4
	v_bfe_u32 v4, v3, 16, 1
	v_add3_u32 v102, v3, v4, s10
	s_waitcnt vmcnt(16)
	v_lshlrev_b32_e32 v3, 16, v206
	v_mul_f32_e32 v3, v1, v3
	v_bfe_u32 v4, v3, 16, 1
	v_add3_u32 v3, v3, v4, s10
	ds_write_b16_d16_hi v17, v3 offset:1440
	ds_write_b16_d16_hi v17, v102 offset:6048
	s_waitcnt vmcnt(16)
	v_lshlrev_b32_e32 v3, 16, v203
	v_max_f32_e32 v3, v3, v3
	v_med3_f32 v3, v3, s9, v244
	v_mul_f32_e32 v3, 0xbfb8aa3b, v3
	v_exp_f32_e32 v3, v3
	s_nop 0
	v_add_f32_e32 v4, 1.0, v3
	v_rcp_f32_e32 v4, v4
	s_nop 0
	v_fma_f32 v5, v117, v4, v116
	v_mul_f32_e32 v1, v1, v5
	v_max_f32_e32 v1, 0xda24260, v1
	v_mul_f32_e32 v3, v3, v4
	v_rcp_f32_e32 v4, v1
	v_mul_f32_e32 v3, v117, v3
	v_mul_f32_e32 v3, v3, v4
	v_bfe_u32 v4, v3, 16, 1
	v_add3_u32 v3, v3, v4, s10
	s_waitcnt vmcnt(16)
	v_lshlrev_b32_e32 v4, 16, v202
	v_mul_f32_e32 v4, v1, v4
	v_bfe_u32 v5, v4, 16, 1
	v_add3_u32 v4, v4, v5, s10
	ds_write_b16_d16_hi v17, v4 offset:1296
	ds_write_b16_d16_hi v17, v3 offset:5904
	s_waitcnt vmcnt(16)
	v_lshlrev_b32_e32 v4, 16, v201
	v_max_f32_e32 v4, v4, v4
	v_med3_f32 v4, v4, s9, v244
	v_mul_f32_e32 v4, 0xbfb8aa3b, v4
	v_exp_f32_e32 v4, v4
	s_nop 0
	v_add_f32_e32 v5, 1.0, v4
	v_rcp_f32_e32 v5, v5
	s_nop 0
	v_fma_f32 v6, v117, v5, v116
	v_mul_f32_e32 v1, v1, v6
	v_max_f32_e32 v12, 0xda24260, v1
	v_rcp_f32_e32 v1, v12
	v_mul_f32_e32 v4, v4, v5
	v_mul_f32_e32 v4, v117, v4
	v_mul_f32_e32 v1, v4, v1
	v_bfe_u32 v4, v1, 16, 1
	v_add3_u32 v20, v1, v4, s10
	s_waitcnt vmcnt(16)
	v_lshlrev_b32_e32 v1, 16, v200
	v_mul_f32_e32 v1, v12, v1
	v_bfe_u32 v4, v1, 16, 1
	v_add3_u32 v1, v1, v4, s10
	ds_write_b16_d16_hi v17, v1 offset:1152
	ds_write_b16_d16_hi v17, v20 offset:5760
	s_waitcnt vmcnt(0)
	v_lshlrev_b32_e32 v8, 16, v233
	v_max_f32_e32 v8, v8, v8
	v_med3_f32 v8, v8, s9, v244
	v_mul_f32_e32 v8, 0xbfb8aa3b, v8
	v_exp_f32_e32 v98, v8
	v_and_b32_e32 v113, 0xffff0000, v2
	v_lshl_or_b32 v2, v108, 16, v124
	v_and_b32_e32 v115, 0xffff0000, v3
	v_add_f32_e32 v13, 1.0, v98
	v_rcp_f32_e32 v104, v13
	v_lshl_or_b32 v3, v110, 16, v112
	v_lshl_or_b32 v11, v151, 16, v129
	v_and_b32_e32 v19, 0xffff0000, v114
	v_fma_f32 v106, v117, v104, v116
	v_mul_f32_e32 v12, v12, v106
	v_max_f32_e32 v106, 0xda24260, v12
	v_rcp_f32_e32 v108, v106
	v_mul_f32_e32 v98, v98, v104
	v_mul_f32_e32 v98, v117, v98
	v_lshl_or_b32 v7, v133, 16, v127
	v_mul_f32_e32 v98, v98, v108
	v_bfe_u32 v104, v98, 16, 1
	v_add3_u32 v98, v98, v104, s10
	s_waitcnt vmcnt(0)
	v_lshlrev_b32_e32 v104, 16, v231
	v_max_f32_e32 v104, v104, v104
	v_med3_f32 v104, v104, s9, v244
	v_mul_f32_e32 v104, 0xbfb8aa3b, v104
	v_exp_f32_e32 v104, v104
	v_lshlrev_b32_e32 v108, 16, v232
	v_mul_f32_e32 v108, v106, v108
	v_bfe_u32 v112, v108, 16, 1
	v_add_f32_e32 v110, 1.0, v104
	v_rcp_f32_e32 v110, v110
	v_add3_u32 v108, v108, v112, s10
	ds_write_b16_d16_hi v17, v108 offset:1008
	v_and_b32_e32 v129, 0xffff0000, v98
	v_fma_f32 v108, v117, v110, v116
	v_mul_f32_e32 v106, v106, v108
	v_max_f32_e32 v106, 0xda24260, v106
	v_rcp_f32_e32 v108, v106
	ds_write_b16_d16_hi v17, v98 offset:5616
	v_mul_f32_e32 v98, v104, v110
	v_mul_f32_e32 v98, v117, v98
	v_mul_f32_e32 v98, v98, v108
	s_waitcnt vmcnt(0)
	v_lshlrev_b32_e32 v108, 16, v229
	v_max_f32_e32 v108, v108, v108
	v_med3_f32 v108, v108, s9, v244
	v_mul_f32_e32 v108, 0xbfb8aa3b, v108
	v_exp_f32_e32 v108, v108
	v_bfe_u32 v104, v98, 16, 1
	v_add3_u32 v98, v98, v104, s10
	v_lshlrev_b32_e32 v104, 16, v230
	v_add_f32_e32 v110, 1.0, v108
	v_rcp_f32_e32 v110, v110
	v_mul_f32_e32 v104, v106, v104
	v_bfe_u32 v112, v104, 16, 1
	v_add3_u32 v104, v104, v112, s10
	ds_write_b16_d16_hi v17, v104 offset:864
	v_fma_f32 v104, v117, v110, v116
	v_mul_f32_e32 v104, v106, v104
	v_max_f32_e32 v104, 0xda24260, v104
	v_rcp_f32_e32 v106, v104
	v_mul_f32_e32 v108, v108, v110
	v_mul_f32_e32 v108, v117, v108
	s_waitcnt vmcnt(0)
	v_lshlrev_b32_e32 v110, 16, v228
	v_mul_f32_e32 v106, v108, v106
	v_bfe_u32 v108, v106, 16, 1
	v_add3_u32 v106, v106, v108, s10
	s_waitcnt vmcnt(0)
	v_lshlrev_b32_e32 v108, 16, v227
	v_max_f32_e32 v108, v108, v108
	v_med3_f32 v108, v108, s9, v244
	v_mul_f32_e32 v108, 0xbfb8aa3b, v108
	v_exp_f32_e32 v108, v108
	v_mul_f32_e32 v110, v104, v110
	v_bfe_u32 v114, v110, 16, 1
	v_add3_u32 v110, v110, v114, s10
	v_add_f32_e32 v112, 1.0, v108
	v_rcp_f32_e32 v112, v112
	ds_write_b16_d16_hi v17, v110 offset:720
	v_and_b32_e32 v127, 0xffff0000, v106
	ds_write_b16_d16_hi v17, v106 offset:5328
	v_fma_f32 v110, v117, v112, v116
	v_mul_f32_e32 v104, v104, v110
	v_max_f32_e32 v104, 0xda24260, v104
	v_rcp_f32_e32 v110, v104
	v_mul_f32_e32 v106, v108, v112
	v_mul_f32_e32 v106, v117, v106
	v_lshl_or_b32 v1, v135, 16, v123
	v_mul_f32_e32 v106, v106, v110
	s_waitcnt vmcnt(0)
	v_lshlrev_b32_e32 v110, 16, v225
	v_max_f32_e32 v110, v110, v110
	v_med3_f32 v110, v110, s9, v244
	v_mul_f32_e32 v110, 0xbfb8aa3b, v110
	v_exp_f32_e32 v110, v110
	v_bfe_u32 v108, v106, 16, 1
	v_add3_u32 v106, v106, v108, s10
	v_lshlrev_b32_e32 v108, 16, v226
	v_add_f32_e32 v112, 1.0, v110
	v_rcp_f32_e32 v112, v112
	v_mul_f32_e32 v108, v104, v108
	v_bfe_u32 v114, v108, 16, 1
	v_add3_u32 v108, v108, v114, s10
	ds_write_b16_d16_hi v17, v108 offset:576
	v_fma_f32 v108, v117, v112, v116
	v_mul_f32_e32 v104, v104, v108
	v_max_f32_e32 v104, 0xda24260, v104
	v_rcp_f32_e32 v108, v104
	v_mul_f32_e32 v110, v110, v112
	v_mul_f32_e32 v110, v117, v110
	s_waitcnt vmcnt(0)
	v_lshlrev_b32_e32 v112, 16, v224
	v_mul_f32_e32 v108, v110, v108
	v_bfe_u32 v110, v108, 16, 1
	v_add3_u32 v108, v108, v110, s10
	s_waitcnt vmcnt(0)
	v_lshlrev_b32_e32 v110, 16, v223
	v_max_f32_e32 v110, v110, v110
	v_med3_f32 v110, v110, s9, v244
	v_mul_f32_e32 v110, 0xbfb8aa3b, v110
	v_exp_f32_e32 v110, v110
	v_mul_f32_e32 v112, v104, v112
	v_bfe_u32 v123, v112, 16, 1
	v_add3_u32 v112, v112, v123, s10
	v_add_f32_e32 v114, 1.0, v110
	v_rcp_f32_e32 v114, v114
	ds_write_b16_d16_hi v17, v112 offset:432
	v_lshl_or_b32 v5, v137, 16, v131
	v_and_b32_e32 v131, 0xffff0000, v108
	v_fma_f32 v112, v117, v114, v116
	v_mul_f32_e32 v104, v104, v112
	v_max_f32_e32 v104, 0xda24260, v104
	v_rcp_f32_e32 v112, v104
	ds_write_b16_d16_hi v17, v108 offset:5040
	v_mul_f32_e32 v108, v110, v114
	v_mul_f32_e32 v108, v117, v108
	v_mul_f32_e32 v108, v108, v112
	s_waitcnt vmcnt(0)
	v_lshlrev_b32_e32 v112, 16, v221
	v_max_f32_e32 v112, v112, v112
	v_med3_f32 v112, v112, s9, v244
	v_mul_f32_e32 v112, 0xbfb8aa3b, v112
	v_exp_f32_e32 v112, v112
	v_bfe_u32 v110, v108, 16, 1
	v_add3_u32 v108, v108, v110, s10
	v_lshlrev_b32_e32 v110, 16, v222
	v_add_f32_e32 v114, 1.0, v112
	v_rcp_f32_e32 v114, v114
	v_mul_f32_e32 v110, v104, v110
	v_bfe_u32 v123, v110, 16, 1
	v_add3_u32 v110, v110, v123, s10
	ds_write_b16_d16_hi v17, v110 offset:288
	v_fma_f32 v110, v117, v114, v116
	v_mul_f32_e32 v104, v104, v110
	v_max_f32_e32 v104, 0xda24260, v104
	v_rcp_f32_e32 v110, v104
	v_mul_f32_e32 v112, v112, v114
	v_mul_f32_e32 v112, v117, v112
	s_waitcnt vmcnt(0)
	v_lshlrev_b32_e32 v114, 16, v220
	v_mul_f32_e32 v110, v112, v110
	v_bfe_u32 v112, v110, 16, 1
	v_add3_u32 v110, v110, v112, s10
	s_waitcnt vmcnt(0)
	v_lshlrev_b32_e32 v112, 16, v219
	v_max_f32_e32 v112, v112, v112
	v_med3_f32 v112, v112, s9, v244
	v_mul_f32_e32 v112, 0xbfb8aa3b, v112
	v_exp_f32_e32 v112, v112
	v_mul_f32_e32 v114, v104, v114
	v_bfe_u32 v124, v114, 16, 1
	v_add3_u32 v114, v114, v124, s10
	v_add_f32_e32 v123, 1.0, v112
	v_rcp_f32_e32 v123, v123
	ds_write_b16_d16_hi v17, v114 offset:144
	v_lshl_or_b32 v12, v145, 16, v132
	v_lshl_or_b32 v6, v139, 16, v125
	v_fma_f32 v114, v117, v123, v116
	v_mul_f32_e32 v104, v104, v114
	v_max_f32_e32 v132, 0xda24260, v104
	v_rcp_f32_e32 v104, v132
	v_and_b32_e32 v125, 0xffff0000, v110
	ds_write_b16_d16_hi v17, v110 offset:4752
	v_mul_f32_e32 v110, v112, v123
	v_mul_f32_e32 v110, v117, v110
	v_mul_f32_e32 v104, v110, v104
	v_bfe_u32 v110, v104, 16, 1
	v_add3_u32 v104, v104, v110, s10
	s_waitcnt vmcnt(0)
	v_lshlrev_b32_e32 v110, 16, v218
	v_mul_f32_e32 v110, v132, v110
	v_bfe_u32 v112, v110, 16, 1
	v_add3_u32 v110, v110, v112, s10
	v_and_b32_e32 v111, 0xffff0000, v0
	v_and_b32_e32 v109, 0xffff0000, v109
	v_and_b32_e32 v107, 0xffff0000, v105
	v_and_b32_e32 v105, 0xffff0000, v101
	v_and_b32_e32 v103, 0xffff0000, v23
	v_and_b32_e32 v101, 0xffff0000, v156
	v_and_b32_e32 v99, 0xffff0000, v155
	v_and_b32_e32 v23, 0xffff0000, v154
	v_and_b32_e32 v21, 0xffff0000, v153
	v_lshl_or_b32 v0, v134, 16, v128
	v_lshl_or_b32 v4, v150, 16, v130
	v_lshl_or_b32 v10, v149, 16, v126
	v_lshl_or_b32 v9, v144, 16, v143
	v_lshl_or_b32 v8, v148, 16, v141
	v_lshl_or_b32 v15, v146, 16, v140
	v_lshl_or_b32 v14, v147, 16, v138
	v_lshl_or_b32 v13, v142, 16, v136
	ds_write_b16_d16_hi v17, v98 offset:5472
	ds_write_b16_d16_hi v17, v106 offset:5184
	ds_write_b16_d16_hi v17, v108 offset:4896
	ds_write_b16_d16_hi v17, v110
	ds_write_b16_d16_hi v17, v104 offset:4608
	v_and_b32_e32 v124, 0xffff0000, v104
	v_and_b32_e32 v130, 0xffff0000, v108
	v_and_b32_e32 v126, 0xffff0000, v106
	v_and_b32_e32 v128, 0xffff0000, v98
	s_movk_i32 s0, 0x50
	v_pk_mul_f32 v[124:125], v[132:133], v[124:125] op_sel_hi:[0,1]
	v_pk_mul_f32 v[130:131], v[132:133], v[130:131] op_sel_hi:[0,1]
	v_pk_mul_f32 v[126:127], v[132:133], v[126:127] op_sel_hi:[0,1]
	v_pk_mul_f32 v[128:129], v[132:133], v[128:129] op_sel_hi:[0,1]
	v_and_b32_e32 v114, 0xffff0000, v20
	v_and_b32_e32 v112, 0xffff0000, v102
	v_and_b32_e32 v110, 0xffff0000, v159
	v_and_b32_e32 v108, 0xffff0000, v157
	v_and_b32_e32 v106, 0xffff0000, v100
	v_and_b32_e32 v104, 0xffff0000, v22
	v_and_b32_e32 v102, 0xffff0000, v18
	v_and_b32_e32 v100, 0xffff0000, v152
	v_and_b32_e32 v98, 0xffff0000, v122
	v_and_b32_e32 v22, 0xffff0000, v121
	v_and_b32_e32 v20, 0xffff0000, v120
	v_and_b32_e32 v18, 0xffff0000, v88
	v_mad_u64_u32 v[134:135], s[2:3], v16, s0, v[92:93]
	v_cvt_pk_bf16_f32 v124, v124, v125
	v_cvt_pk_bf16_f32 v125, v130, v131
	v_cvt_pk_bf16_f32 v126, v126, v127
	v_cvt_pk_bf16_f32 v127, v128, v129
	v_pk_mul_f32 v[114:115], v[132:133], v[114:115] op_sel_hi:[0,1]
	v_pk_mul_f32 v[112:113], v[132:133], v[112:113] op_sel_hi:[0,1]
	v_pk_mul_f32 v[110:111], v[132:133], v[110:111] op_sel_hi:[0,1]
	v_pk_mul_f32 v[108:109], v[132:133], v[108:109] op_sel_hi:[0,1]
	v_pk_mul_f32 v[106:107], v[132:133], v[106:107] op_sel_hi:[0,1]
	v_pk_mul_f32 v[104:105], v[132:133], v[104:105] op_sel_hi:[0,1]
	v_pk_mul_f32 v[102:103], v[132:133], v[102:103] op_sel_hi:[0,1]
	v_pk_mul_f32 v[100:101], v[132:133], v[100:101] op_sel_hi:[0,1]
	v_pk_mul_f32 v[98:99], v[132:133], v[98:99] op_sel_hi:[0,1]
	v_pk_mul_f32 v[22:23], v[132:133], v[22:23] op_sel_hi:[0,1]
	v_pk_mul_f32 v[20:21], v[132:133], v[20:21] op_sel_hi:[0,1]
	v_pk_mul_f32 v[18:19], v[132:133], v[18:19] op_sel_hi:[0,1]
	ds_write_b128 v134, v[124:127] offset:9216
	v_cvt_pk_bf16_f32 v124, v114, v115
	v_cvt_pk_bf16_f32 v125, v112, v113
	v_cvt_pk_bf16_f32 v126, v110, v111
	v_cvt_pk_bf16_f32 v127, v108, v109
	v_cvt_pk_bf16_f32 v106, v106, v107
	v_cvt_pk_bf16_f32 v107, v104, v105
	v_cvt_pk_bf16_f32 v108, v102, v103
	v_cvt_pk_bf16_f32 v109, v100, v101
	v_cvt_pk_bf16_f32 v98, v98, v99
	v_cvt_pk_bf16_f32 v99, v22, v23
	v_cvt_pk_bf16_f32 v100, v20, v21
	v_cvt_pk_bf16_f32 v101, v18, v19
	v_lshl_add_u32 v16, v16, 2, v92
	ds_write_b128 v134, v[124:127] offset:9232
	ds_write_b128 v134, v[106:109] offset:9248
	ds_write_b128 v134, v[98:101] offset:9264
	ds_write_b32 v16, v132 offset:19456
	ds_write_b128 v134, v[12:15] offset:14336
	ds_write_b128 v134, v[8:11] offset:14352
	ds_write_b128 v134, v[4:7] offset:14368
	ds_write_b128 v134, v[0:3] offset:14384
	s_waitcnt lgkmcnt(0)
	v_or_b32_e32 v88, v95, v118
	v_lshlrev_b64 v[0:1], 11, v[88:89]
	v_lshlrev_b32_e32 v100, 2, v119
	v_lshl_add_u64 v[0:1], s[40:41], 0, v[0:1]
	v_ashrrev_i32_e32 v101, 31, v100
	v_mad_u32_u24 v106, v118, s48, v92
	v_lshlrev_b32_e32 v95, 4, v119
	v_lshl_add_u64 v[0:1], v[0:1], 0, v[90:91]
	v_lshlrev_b64 v[102:103], 1, v[100:101]
	v_add_u32_e32 v107, v106, v95
	v_lshl_add_u64 v[104:105], v[0:1], 0, v[102:103]
	ds_read_b128 v[0:3], v107 offset:4608
	ds_read_b128 v[4:7], v107
	ds_read_b128 v[16:19], v107 offset:32
	ds_read_b128 v[20:23], v107 offset:4640
	s_waitcnt lgkmcnt(2)
	v_mfma_f32_32x32x16_bf16 v[0:15], v[0:3], v[4:7], 0
	v_cmp_ge_i32_e32 vcc, v100, v118
	v_cvt_pk_bf16_f32 v120, v32, v33
	v_cvt_pk_bf16_f32 v121, v34, v35
	v_cvt_pk_bf16_f32 v122, v36, v37
	v_cvt_pk_bf16_f32 v123, v38, v39
	v_lshl_add_u64 v[98:99], v[104:105], 0, s[4:5]
	s_waitcnt lgkmcnt(0)
	v_mfma_f32_32x32x16_bf16 v[0:15], v[20:23], v[16:19], v[0:15]
	ds_read_b128 v[16:19], v107 offset:4672
	ds_read_b128 v[20:23], v107 offset:64
	s_waitcnt lgkmcnt(0)
	v_mfma_f32_32x32x16_bf16 v[0:15], v[16:19], v[20:23], v[0:15]
	ds_read_b128 v[16:19], v107 offset:4704
	ds_read_b128 v[20:23], v107 offset:96
	s_waitcnt lgkmcnt(0)
	v_mfma_f32_32x32x16_bf16 v[0:15], v[16:19], v[20:23], v[0:15]
	v_or_b32_e32 v16, 1, v100
	s_nop 10
	v_cndmask_b32_e32 v0, 0, v0, vcc
	v_cmp_ge_i32_e32 vcc, v16, v118
	v_or_b32_e32 v16, 2, v100
	s_nop 0
	v_cndmask_b32_e32 v1, 0, v1, vcc
	v_cmp_ge_i32_e32 vcc, v16, v118
	v_or_b32_e32 v16, 3, v100
	s_nop 0
	v_cndmask_b32_e32 v2, 0, v2, vcc
	v_cmp_ge_i32_e32 vcc, v16, v118
	v_add_u32_e32 v16, 8, v100
	s_nop 0
	v_cndmask_b32_e32 v3, 0, v3, vcc
	v_cmp_ge_i32_e32 vcc, v16, v118
	v_add_u32_e32 v16, 9, v100
	v_cvt_pk_bf16_f32 v17, v2, v3
	v_cndmask_b32_e32 v4, 0, v4, vcc
	v_cmp_ge_i32_e32 vcc, v16, v118
	v_add_u32_e32 v16, 10, v100
	s_nop 0
	v_cndmask_b32_e32 v5, 0, v5, vcc
	v_cmp_ge_i32_e32 vcc, v16, v118
	v_add_u32_e32 v16, 11, v100
	v_cvt_pk_bf16_f32 v18, v4, v5
	v_cndmask_b32_e32 v6, 0, v6, vcc
	v_cmp_ge_i32_e32 vcc, v16, v118
	v_add_u32_e32 v16, 16, v100
	s_nop 0
	v_cndmask_b32_e32 v7, 0, v7, vcc
	v_cmp_ge_i32_e32 vcc, v16, v118
	v_add_u32_e32 v16, 17, v100
	v_cvt_pk_bf16_f32 v19, v6, v7
	v_cndmask_b32_e32 v8, 0, v8, vcc
	v_cmp_ge_i32_e32 vcc, v16, v118
	v_add_u32_e32 v16, 18, v100
	s_nop 0
	v_cndmask_b32_e32 v9, 0, v9, vcc
	v_cmp_ge_i32_e32 vcc, v16, v118
	v_add_u32_e32 v16, 19, v100
	v_cvt_pk_bf16_f32 v20, v8, v9
	v_cndmask_b32_e32 v10, 0, v10, vcc
	v_cmp_ge_i32_e32 vcc, v16, v118
	v_add_u32_e32 v16, 24, v100
	s_nop 0
	v_cndmask_b32_e32 v11, 0, v11, vcc
	v_cmp_ge_i32_e32 vcc, v16, v118
	v_add_u32_e32 v16, 25, v100
	v_cvt_pk_bf16_f32 v21, v10, v11
	v_cndmask_b32_e32 v12, 0, v12, vcc
	v_cmp_ge_i32_e32 vcc, v16, v118
	v_add_u32_e32 v16, 26, v100
	s_nop 0
	v_cndmask_b32_e32 v13, 0, v13, vcc
	v_cmp_ge_i32_e32 vcc, v16, v118
	v_add_u32_e32 v16, 27, v100
	v_cvt_pk_bf16_f32 v22, v12, v13
	v_cndmask_b32_e32 v14, 0, v14, vcc
	v_cmp_ge_i32_e32 vcc, v16, v118
	v_cvt_pk_bf16_f32 v16, v0, v1
	v_lshlrev_b32_e32 v0, 3, v119
	v_mul_u32_u24_e32 v1, 0x50, v118
	v_add3_u32 v107, v92, v0, v1
	v_add_u32_e32 v4, 0x3800, v107
	v_add_u32_e32 v106, v106, v0
	ds_read2_b64 v[0:3], v4 offset1:2
	ds_read2_b64 v[108:111], v4 offset0:4 offset1:6
	v_cndmask_b32_e32 v15, 0, v15, vcc
	v_cvt_pk_bf16_f32 v23, v14, v15
	s_waitcnt lgkmcnt(1)
	v_mfma_f32_32x32x16_bf16 v[0:15], v[0:3], v[16:19], 0
	v_add_co_u32_e32 v104, vcc, s6, v104
	s_nop 1
	v_addc_co_u32_e32 v105, vcc, 0, v105, vcc
	s_waitcnt lgkmcnt(0)
	v_mfma_f32_32x32x16_bf16 v[0:15], v[108:111], v[20:23], v[0:15]
	ds_read2_b64 v[108:111], v106 offset1:2
	ds_read2_b64 v[112:115], v106 offset0:4 offset1:6
	s_waitcnt lgkmcnt(1)
	v_mfma_f32_32x32x16_bf16 v[0:15], v[120:123], v[108:111], v[0:15]
	v_cvt_pk_bf16_f32 v108, v40, v41
	v_cvt_pk_bf16_f32 v109, v42, v43
	v_cvt_pk_bf16_f32 v110, v44, v45
	v_cvt_pk_bf16_f32 v111, v46, v47
	s_waitcnt lgkmcnt(0)
	s_nop 0
	v_mfma_f32_32x32x16_bf16 v[0:15], v[108:111], v[112:115], v[0:15]
	ds_read2_b64 v[108:111], v106 offset0:8 offset1:10
	v_cvt_pk_bf16_f32 v112, v54, v55
	v_cvt_pk_bf16_f32 v113, v50, v51
	v_cvt_pk_bf16_f32 v114, v52, v53
	v_cvt_pk_bf16_f32 v115, v82, v83
	s_waitcnt lgkmcnt(0)
	s_nop 0
	v_mfma_f32_32x32x16_bf16 v[0:15], v[112:115], v[108:111], v[0:15]
	ds_read2_b64 v[108:111], v106 offset0:12 offset1:14
	v_cvt_pk_bf16_f32 v112, v56, v57
	v_cvt_pk_bf16_f32 v113, v58, v59
	v_cvt_pk_bf16_f32 v114, v60, v61
	v_cvt_pk_bf16_f32 v115, v62, v63
	s_waitcnt lgkmcnt(0)
	s_nop 0
	v_mfma_f32_32x32x16_bf16 v[0:15], v[112:115], v[108:111], v[0:15]
	global_load_dwordx2 v[108:109], v[104:105], off offset:1536
	s_waitcnt vmcnt(0)
	v_lshlrev_b32_e32 v110, 16, v108
	v_and_b32_e32 v111, 0xffff0000, v108
	s_nop 7
	v_pk_add_f32 v[0:1], v[0:1], v[110:111]
	v_lshlrev_b32_e32 v108, 16, v109
	v_and_b32_e32 v109, 0xffff0000, v109
	v_pk_add_f32 v[2:3], v[2:3], v[108:109]
	v_mul_f32_e32 v108, v1, v1
	v_pk_fma_f32 v[108:109], v[0:1], v[0:1], v[108:109] op_sel_hi:[1,1,0]
	v_cvt_pk_bf16_f32 v0, v0, v1
	v_cvt_pk_bf16_f32 v1, v2, v3
	global_store_dwordx2 v[104:105], v[0:1], off offset:1536
	global_load_dwordx2 v[0:1], v[98:99], off offset:16
	v_mul_f32_e32 v110, v3, v3
	v_pk_fma_f32 v[110:111], v[2:3], v[2:3], v[110:111] op_sel_hi:[1,1,0]
	s_waitcnt vmcnt(0)
	v_lshlrev_b32_e32 v2, 16, v0
	v_and_b32_e32 v3, 0xffff0000, v0
	v_lshlrev_b32_e32 v0, 16, v1
	v_and_b32_e32 v1, 0xffff0000, v1
	v_pk_add_f32 v[2:3], v[4:5], v[2:3]
	v_pk_add_f32 v[0:1], v[6:7], v[0:1]
	v_mul_f32_e32 v4, v3, v3
	v_mul_f32_e32 v6, v1, v1
	v_pk_fma_f32 v[4:5], v[2:3], v[2:3], v[4:5] op_sel_hi:[1,1,0]
	v_pk_fma_f32 v[6:7], v[0:1], v[0:1], v[6:7] op_sel_hi:[1,1,0]
	v_cvt_pk_bf16_f32 v2, v2, v3
	v_cvt_pk_bf16_f32 v3, v0, v1
	global_load_dwordx2 v[0:1], v[98:99], off offset:32
	v_pk_add_f32 v[4:5], v[4:5], v[6:7]
	global_store_dwordx2 v[98:99], v[2:3], off offset:16
	v_pk_add_f32 v[108:109], v[108:109], v[110:111]
	s_waitcnt vmcnt(1)
	v_lshlrev_b32_e32 v2, 16, v0
	v_and_b32_e32 v3, 0xffff0000, v0
	v_pk_add_f32 v[2:3], v[8:9], v[2:3]
	v_lshlrev_b32_e32 v0, 16, v1
	v_and_b32_e32 v1, 0xffff0000, v1
	v_pk_add_f32 v[6:7], v[10:11], v[0:1]
	v_mul_f32_e32 v0, v3, v3
	v_pk_fma_f32 v[0:1], v[2:3], v[2:3], v[0:1] op_sel_hi:[1,1,0]
	v_cvt_pk_bf16_f32 v2, v2, v3
	v_cvt_pk_bf16_f32 v3, v6, v7
	global_store_dwordx2 v[98:99], v[2:3], off offset:32
	global_load_dwordx2 v[2:3], v[98:99], off offset:48
	v_mul_f32_e32 v8, v7, v7
	v_pk_fma_f32 v[8:9], v[6:7], v[6:7], v[8:9] op_sel_hi:[1,1,0]
	v_pk_add_f32 v[4:5], v[108:109], v[4:5]
	v_pk_add_f32 v[0:1], v[0:1], v[8:9]
	s_nop 0
	v_pk_add_f32 v[0:1], v[4:5], v[0:1]
	s_waitcnt vmcnt(0)
	v_lshlrev_b32_e32 v4, 16, v2
	v_and_b32_e32 v5, 0xffff0000, v2
	v_lshlrev_b32_e32 v2, 16, v3
	v_and_b32_e32 v3, 0xffff0000, v3
	v_pk_add_f32 v[4:5], v[12:13], v[4:5]
	v_pk_add_f32 v[2:3], v[14:15], v[2:3]
	v_mul_f32_e32 v6, v5, v5
	v_mul_f32_e32 v8, v3, v3
	v_pk_fma_f32 v[6:7], v[4:5], v[4:5], v[6:7] op_sel_hi:[1,1,0]
	v_pk_fma_f32 v[8:9], v[2:3], v[2:3], v[8:9] op_sel_hi:[1,1,0]
	s_nop 0
	v_pk_add_f32 v[6:7], v[6:7], v[8:9]
	s_nop 0
	v_pk_add_f32 v[112:113], v[0:1], v[6:7]
	v_cvt_pk_bf16_f32 v0, v4, v5
	v_cvt_pk_bf16_f32 v1, v2, v3
	global_store_dwordx2 v[98:99], v[0:1], off offset:48
	v_add_u32_e32 v4, 0x4000, v107
	ds_read2_b64 v[0:3], v4 offset0:64 offset1:66
	ds_read2_b64 v[108:111], v4 offset0:68 offset1:70
	s_waitcnt lgkmcnt(1)
	v_mfma_f32_32x32x16_bf16 v[0:15], v[0:3], v[16:19], 0
	s_waitcnt lgkmcnt(0)
	v_mfma_f32_32x32x16_bf16 v[0:15], v[108:111], v[20:23], v[0:15]
	v_cvt_pk_bf16_f32 v108, v26, v27
	v_cvt_pk_bf16_f32 v109, v28, v29
	v_cvt_pk_bf16_f32 v110, v30, v31
	v_cvt_pk_bf16_f32 v111, v48, v49
	ds_read2_b64 v[16:19], v106 offset1:2
	ds_read2_b64 v[20:23], v106 offset0:4 offset1:6
	s_waitcnt lgkmcnt(1)
	v_mfma_f32_32x32x16_bf16 v[0:15], v[108:111], v[16:19], v[0:15]
	v_cvt_pk_bf16_f32 v16, v24, v25
	v_cvt_pk_bf16_f32 v17, v84, v85
	v_cvt_pk_bf16_f32 v18, v86, v87
	v_cvt_pk_bf16_f32 v19, v96, v97
	s_waitcnt lgkmcnt(0)
	s_nop 0
	v_mfma_f32_32x32x16_bf16 v[0:15], v[16:19], v[20:23], v[0:15]
	ds_read2_b64 v[16:19], v106 offset0:8 offset1:10
	v_cvt_pk_bf16_f32 v20, v66, v67
	v_cvt_pk_bf16_f32 v21, v68, v69
	v_cvt_pk_bf16_f32 v22, v70, v71
	v_cvt_pk_bf16_f32 v23, v72, v73
	s_waitcnt lgkmcnt(0)
	s_nop 0
	v_mfma_f32_32x32x16_bf16 v[0:15], v[20:23], v[16:19], v[0:15]
	ds_read2_b64 v[16:19], v106 offset0:12 offset1:14
	v_cvt_pk_bf16_f32 v20, v74, v75
	v_cvt_pk_bf16_f32 v21, v76, v77
	v_cvt_pk_bf16_f32 v22, v78, v79
	v_cvt_pk_bf16_f32 v23, v80, v81
	s_waitcnt lgkmcnt(0)
	s_nop 0
	v_mfma_f32_32x32x16_bf16 v[0:15], v[20:23], v[16:19], v[0:15]
	global_load_dwordx2 v[16:17], v[98:99], off offset:64
	s_waitcnt vmcnt(0)
	v_lshlrev_b32_e32 v18, 16, v16
	v_and_b32_e32 v19, 0xffff0000, v16
	s_nop 7
	v_pk_add_f32 v[0:1], v[0:1], v[18:19]
	v_lshlrev_b32_e32 v16, 16, v17
	v_and_b32_e32 v17, 0xffff0000, v17
	v_pk_add_f32 v[2:3], v[2:3], v[16:17]
	v_mul_f32_e32 v16, v1, v1
	v_pk_fma_f32 v[16:17], v[0:1], v[0:1], v[16:17] op_sel_hi:[1,1,0]
	v_cvt_pk_bf16_f32 v0, v0, v1
	v_cvt_pk_bf16_f32 v1, v2, v3
	global_store_dwordx2 v[98:99], v[0:1], off offset:64
	global_load_dwordx2 v[0:1], v[98:99], off offset:80
	v_mul_f32_e32 v18, v3, v3
	v_pk_fma_f32 v[18:19], v[2:3], v[2:3], v[18:19] op_sel_hi:[1,1,0]
	s_waitcnt vmcnt(0)
	v_lshlrev_b32_e32 v2, 16, v0
	v_and_b32_e32 v3, 0xffff0000, v0
	v_lshlrev_b32_e32 v0, 16, v1
	v_and_b32_e32 v1, 0xffff0000, v1
	v_pk_add_f32 v[2:3], v[4:5], v[2:3]
	v_pk_add_f32 v[0:1], v[6:7], v[0:1]
	v_mul_f32_e32 v4, v3, v3
	v_mul_f32_e32 v6, v1, v1
	v_pk_fma_f32 v[4:5], v[2:3], v[2:3], v[4:5] op_sel_hi:[1,1,0]
	v_pk_fma_f32 v[6:7], v[0:1], v[0:1], v[6:7] op_sel_hi:[1,1,0]
	v_cvt_pk_bf16_f32 v2, v2, v3
	v_cvt_pk_bf16_f32 v3, v0, v1
	global_load_dwordx2 v[0:1], v[98:99], off offset:96
	v_pk_add_f32 v[4:5], v[4:5], v[6:7]
	global_store_dwordx2 v[98:99], v[2:3], off offset:80
	v_pk_add_f32 v[16:17], v[16:17], v[18:19]
	s_waitcnt vmcnt(1)
	v_lshlrev_b32_e32 v2, 16, v0
	v_and_b32_e32 v3, 0xffff0000, v0
	v_lshlrev_b32_e32 v0, 16, v1
	v_and_b32_e32 v1, 0xffff0000, v1
	v_pk_add_f32 v[2:3], v[8:9], v[2:3]
	v_pk_add_f32 v[6:7], v[10:11], v[0:1]
	v_mov_b32_e32 v0, v2
	v_mov_b32_e32 v8, v3
	v_cvt_pk_bf16_f32 v2, v2, v3
	v_cvt_pk_bf16_f32 v3, v6, v7
	global_store_dwordx2 v[98:99], v[2:3], off offset:96
	global_load_dwordx2 v[2:3], v[98:99], off offset:112
	v_mov_b32_e32 v9, v7
	v_mov_b32_e32 v1, v6
	v_pk_mul_f32 v[8:9], v[8:9], v[8:9]
	v_pk_add_f32 v[16:17], v[112:113], v[16:17]
	v_pk_fma_f32 v[0:1], v[0:1], v[0:1], v[8:9]
	v_pk_add_f32 v[4:5], v[16:17], v[4:5]
	v_pk_add_f32 v[0:1], v[0:1], v[0:1] op_sel:[0,1] op_sel_hi:[1,0]
	s_nop 0
	v_pk_add_f32 v[0:1], v[4:5], v[0:1]
	s_waitcnt vmcnt(0)
	v_lshlrev_b32_e32 v4, 16, v2
	v_and_b32_e32 v5, 0xffff0000, v2
	v_lshlrev_b32_e32 v2, 16, v3
	v_and_b32_e32 v3, 0xffff0000, v3
	v_pk_add_f32 v[4:5], v[12:13], v[4:5]
	v_pk_add_f32 v[2:3], v[14:15], v[2:3]
	v_mov_b32_e32 v8, v5
	v_mov_b32_e32 v9, v3
	v_mov_b32_e32 v6, v4
	v_mov_b32_e32 v7, v2
	v_pk_mul_f32 v[8:9], v[8:9], v[8:9]
	s_nop 0
	v_pk_fma_f32 v[6:7], v[6:7], v[6:7], v[8:9]
	s_nop 0
	v_pk_add_f32 v[6:7], v[6:7], v[6:7] op_sel:[0,1] op_sel_hi:[1,0]
	s_nop 0
	v_pk_add_f32 v[114:115], v[0:1], v[6:7]
	v_cvt_pk_bf16_f32 v0, v4, v5
	v_cvt_pk_bf16_f32 v1, v2, v3
	global_store_dwordx2 v[98:99], v[0:1], off offset:112
	v_add_u32_e32 v95, v92, v95
	v_mad_u32_u24 v115, v118, s0, v95
	ds_read_b128 v[0:3], v95 offset:19456
	ds_read_b128 v[4:7], v95 offset:19488
	ds_read_b128 v[8:11], v95 offset:19520
	ds_read_b128 v[12:15], v95 offset:19552
	ds_read_b128 v[16:19], v115 offset:9216
	ds_read_b128 v[20:23], v115 offset:14336
	ds_read_b128 v[106:109], v115 offset:9248
	ds_read_b128 v[110:113], v115 offset:14368
	ds_read_b128 v[118:121], v115 offset:16896
	s_waitcnt lgkmcnt(8)
	v_pk_mul_f32 v[34:35], v[2:3], v[34:35]
	v_pk_mul_f32 v[32:33], v[0:1], v[32:33]
	s_waitcnt lgkmcnt(7)
	v_pk_mul_f32 v[38:39], v[6:7], v[38:39]
	v_pk_mul_f32 v[36:37], v[4:5], v[36:37]
	s_waitcnt lgkmcnt(6)
	v_pk_mul_f32 v[42:43], v[10:11], v[42:43]
	v_pk_mul_f32 v[40:41], v[8:9], v[40:41]
	s_waitcnt lgkmcnt(5)
	v_pk_mul_f32 v[46:47], v[14:15], v[46:47]
	v_pk_mul_f32 v[44:45], v[12:13], v[44:45]
	v_pk_mul_f32 v[0:1], v[0:1], v[26:27]
	v_pk_mul_f32 v[2:3], v[2:3], v[28:29]
	v_pk_mul_f32 v[4:5], v[4:5], v[30:31]
	v_pk_mul_f32 v[6:7], v[6:7], v[48:49]
	v_pk_mul_f32 v[8:9], v[8:9], v[24:25]
	v_pk_mul_f32 v[10:11], v[10:11], v[84:85]
	v_pk_mul_f32 v[12:13], v[12:13], v[86:87]
	v_pk_mul_f32 v[14:15], v[14:15], v[96:97]
	s_waitcnt lgkmcnt(3)
	v_mfma_f32_32x32x16_bf16 v[32:47], v[16:19], v[20:23], v[32:47]
	ds_read_b128 v[84:87], v115 offset:16928
	s_movk_i32 s4, 0x50
	s_waitcnt lgkmcnt(1)
	v_mfma_f32_32x32x16_bf16 v[0:15], v[16:19], v[118:121], v[0:15]
	v_mfma_f32_32x32x16_bf16 v[32:47], v[106:109], v[110:113], v[32:47]
	s_waitcnt lgkmcnt(0)
	v_mfma_f32_32x32x16_bf16 v[0:15], v[106:109], v[84:87], v[0:15]
	ds_read_b128 v[16:19], v95 offset:19584
	ds_read_b128 v[24:27], v95 offset:19616
	ds_read_b128 v[28:31], v95 offset:19648
	ds_read_b128 v[106:109], v95 offset:19680
	ds_read_b128 v[122:125], v115 offset:11776
	s_waitcnt lgkmcnt(4)
	v_pk_mul_f32 v[50:51], v[18:19], v[50:51]
	v_pk_mul_f32 v[48:49], v[16:17], v[54:55]
	s_waitcnt lgkmcnt(3)
	v_pk_mul_f32 v[54:55], v[26:27], v[82:83]
	v_pk_mul_f32 v[52:53], v[24:25], v[52:53]
	s_waitcnt lgkmcnt(2)
	v_pk_mul_f32 v[58:59], v[30:31], v[58:59]
	v_pk_mul_f32 v[56:57], v[28:29], v[56:57]
	s_waitcnt lgkmcnt(1)
	v_pk_mul_f32 v[62:63], v[108:109], v[62:63]
	v_pk_mul_f32 v[60:61], v[106:107], v[60:61]
	ds_read_b128 v[126:129], v115 offset:11808
	v_pk_mul_f32 v[16:17], v[16:17], v[66:67]
	s_waitcnt lgkmcnt(1)
	v_mfma_f32_32x32x16_bf16 v[48:63], v[122:125], v[20:23], v[48:63]
	v_mul_f32_e64 v18, v18, v68
	v_mul_f32_e64 v19, v19, v69
	v_mul_f32_e64 v20, v24, v70
	v_mul_f32_e64 v21, v25, v71
	v_mul_f32_e64 v22, v26, v72
	v_mul_f32_e64 v23, v27, v73
	v_pk_mul_f32 v[24:25], v[28:29], v[74:75]
	v_pk_mul_f32 v[26:27], v[30:31], v[76:77]
	v_pk_mul_f32 v[28:29], v[106:107], v[78:79]
	v_pk_mul_f32 v[30:31], v[108:109], v[80:81]
	s_waitcnt lgkmcnt(0)
	s_waitcnt lgkmcnt(0)
	v_mfma_f32_32x32x16_bf16 v[48:63], v[126:129], v[110:113], v[48:63]
	v_mfma_f32_32x32x16_bf16 v[16:31], v[122:125], v[118:121], v[16:31]
	v_mfma_f32_32x32x16_bf16 v[16:31], v[126:129], v[84:87], v[16:31]
	v_mad_i64_i32 v[64:65], s[2:3], v88, s1, v[64:65]
	v_lshl_add_u64 v[64:65], v[64:65], 0, v[90:91]
	v_lshl_add_u64 v[64:65], v[64:65], 0, v[102:103]
	s_mov_b64 s[48:49], 0x1000
	s_movk_i32 s5, 0x1000
	v_lshl_add_u64 v[72:73], v[64:65], 0, s[48:49]
	v_add_co_u32_e32 v64, vcc, s5, v64
	global_load_dwordx2 v[74:75], v[104:105], off offset:1536
	s_nop 0
	v_addc_co_u32_e32 v65, vcc, 0, v65, vcc
	global_load_dwordx2 v[76:77], v[64:65], off
	v_readlane_b32 s0, v255, 18
	v_readlane_b32 s1, v255, 19
	s_add_u32 s2, s40, s0
	v_mov_b32_e32 v66, v114
	s_addc_u32 s3, s41, s1
	s_nop 0
	v_permlane32_swap_b32_e32 v114, v66
	v_lshl_add_u64 v[64:65], v[100:101], 2, s[2:3]
	s_mov_b64 s[2:3], 0x4800
	v_add_f32_e32 v66, v114, v66
	v_lshl_add_u64 v[70:71], v[64:65], 0, s[2:3]
	v_add_co_u32_e32 v64, vcc, s7, v64
	v_fmamk_f32 v66, v66, 0x3c800000, v237
	s_nop 0
	v_addc_co_u32_e32 v65, vcc, 0, v65, vcc
	v_rsq_f32_e32 v68, v66
	global_load_dwordx4 v[64:67], v[64:65], off offset:2048
	s_movk_i32 s6, 0x1200
	s_waitcnt vmcnt(2)
	v_lshlrev_b32_e32 v82, 16, v74
	v_and_b32_e32 v83, 0xffff0000, v74
	v_lshlrev_b32_e32 v74, 16, v75
	s_waitcnt vmcnt(1)
	v_lshlrev_b32_e32 v78, 16, v76
	v_mul_f32_e32 v69, 0xbfb8aa3b, v78
	v_exp_f32_e32 v69, v69
	v_and_b32_e32 v79, 0xffff0000, v76
	v_lshlrev_b32_e32 v76, 16, v77
	v_and_b32_e32 v77, 0xffff0000, v77
	v_add_f32_e32 v69, 1.0, v69
	v_rcp_f32_e32 v80, v69
	v_mul_f32_e32 v69, 0xbfb8aa3b, v79
	v_exp_f32_e32 v69, v69
	v_and_b32_e32 v75, 0xffff0000, v75
	v_add_f32_e32 v69, 1.0, v69
	v_rcp_f32_e32 v81, v69
	v_pk_mul_f32 v[82:83], v[68:69], v[82:83] op_sel_hi:[0,1]
	v_pk_mul_f32 v[74:75], v[68:69], v[74:75] op_sel_hi:[0,1]
	s_waitcnt vmcnt(0)
	v_pk_mul_f32 v[64:65], v[64:65], v[82:83]
	v_pk_mul_f32 v[78:79], v[80:81], v[78:79]
	v_pk_mul_f32 v[66:67], v[66:67], v[74:75]
	v_pk_mul_f32 v[64:65], v[64:65], v[78:79]
	s_nop 0
	v_cvt_pk_bf16_f32 v64, v64, v65
	v_mul_f32_e32 v65, 0xbfb8aa3b, v76
	v_exp_f32_e32 v65, v65
	s_nop 0
	v_add_f32_e32 v65, 1.0, v65
	v_rcp_f32_e32 v78, v65
	v_mul_f32_e32 v65, 0xbfb8aa3b, v77
	v_exp_f32_e32 v65, v65
	s_nop 0
	v_add_f32_e32 v65, 1.0, v65
	v_rcp_f32_e32 v79, v65
	s_nop 0
	v_pk_mul_f32 v[74:75], v[78:79], v[76:77]
	s_nop 0
	v_pk_mul_f32 v[66:67], v[66:67], v[74:75]
	s_nop 0
	v_cvt_pk_bf16_f32 v65, v66, v67
	global_store_dwordx2 v[104:105], v[64:65], off offset:1536
	global_load_dwordx4 v[64:67], v[70:71], off offset:32
	s_nop 0
	global_load_dwordx2 v[74:75], v[72:73], off offset:16
	global_load_dwordx2 v[76:77], v[98:99], off offset:16
	s_waitcnt vmcnt(1)
	v_lshlrev_b32_e32 v78, 16, v74
	v_mul_f32_e32 v69, 0xbfb8aa3b, v78
	v_exp_f32_e32 v69, v69
	v_and_b32_e32 v79, 0xffff0000, v74
	s_waitcnt vmcnt(0)
	v_lshlrev_b32_e32 v82, 16, v76
	v_and_b32_e32 v83, 0xffff0000, v76
	v_add_f32_e32 v69, 1.0, v69
	v_rcp_f32_e32 v80, v69
	v_mul_f32_e32 v69, 0xbfb8aa3b, v79
	v_exp_f32_e32 v69, v69
	v_lshlrev_b32_e32 v74, 16, v75
	v_and_b32_e32 v75, 0xffff0000, v75
	v_lshlrev_b32_e32 v76, 16, v77
	v_add_f32_e32 v69, 1.0, v69
	v_rcp_f32_e32 v81, v69
	v_pk_mul_f32 v[82:83], v[68:69], v[82:83] op_sel_hi:[0,1]
	v_pk_mul_f32 v[64:65], v[64:65], v[82:83]
	v_and_b32_e32 v77, 0xffff0000, v77
	v_pk_mul_f32 v[78:79], v[80:81], v[78:79]
	v_pk_mul_f32 v[76:77], v[68:69], v[76:77] op_sel_hi:[0,1]
	v_pk_mul_f32 v[64:65], v[64:65], v[78:79]
	v_pk_mul_f32 v[66:67], v[66:67], v[76:77]
	v_cvt_pk_bf16_f32 v64, v64, v65
	v_mul_f32_e32 v65, 0xbfb8aa3b, v74
	v_exp_f32_e32 v65, v65
	s_nop 0
	v_add_f32_e32 v65, 1.0, v65
	v_rcp_f32_e32 v78, v65
	v_mul_f32_e32 v65, 0xbfb8aa3b, v75
	v_exp_f32_e32 v65, v65
	s_nop 0
	v_add_f32_e32 v65, 1.0, v65
	v_rcp_f32_e32 v79, v65
	s_nop 0
	v_pk_mul_f32 v[74:75], v[78:79], v[74:75]
	s_nop 0
	v_pk_mul_f32 v[66:67], v[66:67], v[74:75]
	s_nop 0
	v_cvt_pk_bf16_f32 v65, v66, v67
	global_store_dwordx2 v[98:99], v[64:65], off offset:16
	global_load_dwordx4 v[64:67], v[70:71], off offset:64
	s_nop 0
	global_load_dwordx2 v[74:75], v[72:73], off offset:32
	global_load_dwordx2 v[76:77], v[98:99], off offset:32
	s_waitcnt vmcnt(1)
	v_lshlrev_b32_e32 v78, 16, v74
	v_mul_f32_e32 v69, 0xbfb8aa3b, v78
	v_exp_f32_e32 v69, v69
	v_and_b32_e32 v79, 0xffff0000, v74
	s_waitcnt vmcnt(0)
	v_lshlrev_b32_e32 v82, 16, v76
	v_and_b32_e32 v83, 0xffff0000, v76
	v_add_f32_e32 v69, 1.0, v69
	v_rcp_f32_e32 v80, v69
	v_mul_f32_e32 v69, 0xbfb8aa3b, v79
	v_exp_f32_e32 v69, v69
	v_lshlrev_b32_e32 v74, 16, v75
	v_and_b32_e32 v75, 0xffff0000, v75
	v_lshlrev_b32_e32 v76, 16, v77
	v_add_f32_e32 v69, 1.0, v69
	v_rcp_f32_e32 v81, v69
	v_pk_mul_f32 v[82:83], v[68:69], v[82:83] op_sel_hi:[0,1]
	v_pk_mul_f32 v[64:65], v[64:65], v[82:83]
	v_and_b32_e32 v77, 0xffff0000, v77
	v_pk_mul_f32 v[78:79], v[80:81], v[78:79]
	v_pk_mul_f32 v[76:77], v[68:69], v[76:77] op_sel_hi:[0,1]
	v_pk_mul_f32 v[64:65], v[64:65], v[78:79]
	v_pk_mul_f32 v[66:67], v[66:67], v[76:77]
	v_cvt_pk_bf16_f32 v64, v64, v65
	v_mul_f32_e32 v65, 0xbfb8aa3b, v74
	v_exp_f32_e32 v65, v65
	s_nop 0
	v_add_f32_e32 v65, 1.0, v65
	v_rcp_f32_e32 v78, v65
	v_mul_f32_e32 v65, 0xbfb8aa3b, v75
	v_exp_f32_e32 v65, v65
	s_nop 0
	v_add_f32_e32 v65, 1.0, v65
	v_rcp_f32_e32 v79, v65
	s_nop 0
	v_pk_mul_f32 v[74:75], v[78:79], v[74:75]
	s_nop 0
	v_pk_mul_f32 v[66:67], v[66:67], v[74:75]
	s_nop 0
	v_cvt_pk_bf16_f32 v65, v66, v67
	global_store_dwordx2 v[98:99], v[64:65], off offset:32
	global_load_dwordx4 v[64:67], v[70:71], off offset:96
	s_nop 0
	global_load_dwordx2 v[74:75], v[72:73], off offset:48
	global_load_dwordx2 v[76:77], v[98:99], off offset:48
	s_waitcnt vmcnt(1)
	v_lshlrev_b32_e32 v78, 16, v74
	v_mul_f32_e32 v69, 0xbfb8aa3b, v78
	v_exp_f32_e32 v69, v69
	v_and_b32_e32 v79, 0xffff0000, v74
	s_waitcnt vmcnt(0)
	v_lshlrev_b32_e32 v82, 16, v76
	v_and_b32_e32 v83, 0xffff0000, v76
	v_add_f32_e32 v69, 1.0, v69
	v_rcp_f32_e32 v80, v69
	v_mul_f32_e32 v69, 0xbfb8aa3b, v79
	v_exp_f32_e32 v69, v69
	v_lshlrev_b32_e32 v74, 16, v75
	v_and_b32_e32 v75, 0xffff0000, v75
	v_lshlrev_b32_e32 v76, 16, v77
	v_add_f32_e32 v69, 1.0, v69
	v_rcp_f32_e32 v81, v69
	v_pk_mul_f32 v[82:83], v[68:69], v[82:83] op_sel_hi:[0,1]
	v_pk_mul_f32 v[64:65], v[64:65], v[82:83]
	v_and_b32_e32 v77, 0xffff0000, v77
	v_pk_mul_f32 v[78:79], v[80:81], v[78:79]
	v_pk_mul_f32 v[76:77], v[68:69], v[76:77] op_sel_hi:[0,1]
	v_pk_mul_f32 v[64:65], v[64:65], v[78:79]
	v_pk_mul_f32 v[66:67], v[66:67], v[76:77]
	v_cvt_pk_bf16_f32 v64, v64, v65
	v_mul_f32_e32 v65, 0xbfb8aa3b, v74
	v_exp_f32_e32 v65, v65
	s_nop 0
	v_add_f32_e32 v65, 1.0, v65
	v_rcp_f32_e32 v78, v65
	v_mul_f32_e32 v65, 0xbfb8aa3b, v75
	v_exp_f32_e32 v65, v65
	s_nop 0
	v_add_f32_e32 v65, 1.0, v65
	v_rcp_f32_e32 v79, v65
	s_nop 0
	v_pk_mul_f32 v[74:75], v[78:79], v[74:75]
	s_nop 0
	v_pk_mul_f32 v[66:67], v[66:67], v[74:75]
	s_nop 0
	v_cvt_pk_bf16_f32 v65, v66, v67
	global_store_dwordx2 v[98:99], v[64:65], off offset:48
	global_load_dwordx2 v[74:75], v[98:99], off offset:64
	global_load_dwordx2 v[76:77], v[72:73], off offset:64
	global_load_dwordx4 v[64:67], v[70:71], off offset:128
	s_waitcnt vmcnt(2)
	v_lshlrev_b32_e32 v82, 16, v74
	s_waitcnt vmcnt(1)
	v_lshlrev_b32_e32 v78, 16, v76
	v_mul_f32_e32 v69, 0xbfb8aa3b, v78
	v_exp_f32_e32 v69, v69
	v_and_b32_e32 v79, 0xffff0000, v76
	v_and_b32_e32 v83, 0xffff0000, v74
	v_lshlrev_b32_e32 v76, 16, v77
	v_add_f32_e32 v69, 1.0, v69
	v_rcp_f32_e32 v80, v69
	v_mul_f32_e32 v69, 0xbfb8aa3b, v79
	v_exp_f32_e32 v69, v69
	v_and_b32_e32 v77, 0xffff0000, v77
	v_lshlrev_b32_e32 v74, 16, v75
	v_and_b32_e32 v75, 0xffff0000, v75
	v_add_f32_e32 v69, 1.0, v69
	v_rcp_f32_e32 v81, v69
	v_pk_mul_f32 v[82:83], v[68:69], v[82:83] op_sel_hi:[0,1]
	s_waitcnt vmcnt(0)
	v_pk_mul_f32 v[64:65], v[64:65], v[82:83]
	v_pk_mul_f32 v[74:75], v[68:69], v[74:75] op_sel_hi:[0,1]
	v_pk_mul_f32 v[78:79], v[80:81], v[78:79]
	v_pk_mul_f32 v[66:67], v[66:67], v[74:75]
	v_pk_mul_f32 v[64:65], v[64:65], v[78:79]
	s_nop 0
	v_cvt_pk_bf16_f32 v64, v64, v65
	v_mul_f32_e32 v65, 0xbfb8aa3b, v76
	v_exp_f32_e32 v65, v65
	s_nop 0
	v_add_f32_e32 v65, 1.0, v65
	v_rcp_f32_e32 v78, v65
	v_mul_f32_e32 v65, 0xbfb8aa3b, v77
	v_exp_f32_e32 v65, v65
	s_nop 0
	v_add_f32_e32 v65, 1.0, v65
	v_rcp_f32_e32 v79, v65
	s_nop 0
	v_pk_mul_f32 v[74:75], v[78:79], v[76:77]
	s_nop 0
	v_pk_mul_f32 v[66:67], v[66:67], v[74:75]
	s_nop 0
	v_cvt_pk_bf16_f32 v65, v66, v67
	global_store_dwordx2 v[98:99], v[64:65], off offset:64
	global_load_dwordx2 v[74:75], v[98:99], off offset:80
	global_load_dwordx2 v[76:77], v[72:73], off offset:80
	s_nop 0
	global_load_dwordx4 v[64:67], v[70:71], off offset:160
	s_waitcnt vmcnt(2)
	v_lshlrev_b32_e32 v82, 16, v74
	s_waitcnt vmcnt(1)
	v_lshlrev_b32_e32 v78, 16, v76
	v_mul_f32_e32 v69, 0xbfb8aa3b, v78
	v_exp_f32_e32 v69, v69
	v_and_b32_e32 v79, 0xffff0000, v76
	v_and_b32_e32 v83, 0xffff0000, v74
	v_lshlrev_b32_e32 v76, 16, v77
	v_add_f32_e32 v69, 1.0, v69
	v_rcp_f32_e32 v80, v69
	v_mul_f32_e32 v69, 0xbfb8aa3b, v79
	v_exp_f32_e32 v69, v69
	v_and_b32_e32 v77, 0xffff0000, v77
	v_lshlrev_b32_e32 v74, 16, v75
	v_and_b32_e32 v75, 0xffff0000, v75
	v_add_f32_e32 v69, 1.0, v69
	v_rcp_f32_e32 v81, v69
	v_pk_mul_f32 v[82:83], v[68:69], v[82:83] op_sel_hi:[0,1]
	s_waitcnt vmcnt(0)
	v_pk_mul_f32 v[64:65], v[64:65], v[82:83]
	v_pk_mul_f32 v[74:75], v[68:69], v[74:75] op_sel_hi:[0,1]
	v_pk_mul_f32 v[78:79], v[80:81], v[78:79]
	v_pk_mul_f32 v[66:67], v[66:67], v[74:75]
	v_pk_mul_f32 v[64:65], v[64:65], v[78:79]
	s_nop 0
	v_cvt_pk_bf16_f32 v64, v64, v65
	v_mul_f32_e32 v65, 0xbfb8aa3b, v76
	v_exp_f32_e32 v65, v65
	s_nop 0
	v_add_f32_e32 v65, 1.0, v65
	v_rcp_f32_e32 v78, v65
	v_mul_f32_e32 v65, 0xbfb8aa3b, v77
	v_exp_f32_e32 v65, v65
	s_nop 0
	v_add_f32_e32 v65, 1.0, v65
	v_rcp_f32_e32 v79, v65
	s_nop 0
	v_pk_mul_f32 v[74:75], v[78:79], v[76:77]
	s_nop 0
	v_pk_mul_f32 v[66:67], v[66:67], v[74:75]
	s_nop 0
	v_cvt_pk_bf16_f32 v65, v66, v67
	global_store_dwordx2 v[98:99], v[64:65], off offset:80
	global_load_dwordx2 v[74:75], v[98:99], off offset:96
	global_load_dwordx2 v[76:77], v[72:73], off offset:96
	s_nop 0
	global_load_dwordx4 v[64:67], v[70:71], off offset:192
	s_waitcnt vmcnt(2)
	v_lshlrev_b32_e32 v82, 16, v74
	s_waitcnt vmcnt(1)
	v_lshlrev_b32_e32 v78, 16, v76
	v_mul_f32_e32 v69, 0xbfb8aa3b, v78
	v_exp_f32_e32 v69, v69
	v_and_b32_e32 v79, 0xffff0000, v76
	v_and_b32_e32 v83, 0xffff0000, v74
	v_lshlrev_b32_e32 v76, 16, v77
	v_add_f32_e32 v69, 1.0, v69
	v_rcp_f32_e32 v80, v69
	v_mul_f32_e32 v69, 0xbfb8aa3b, v79
	v_exp_f32_e32 v69, v69
	v_and_b32_e32 v77, 0xffff0000, v77
	v_lshlrev_b32_e32 v74, 16, v75
	v_and_b32_e32 v75, 0xffff0000, v75
	v_add_f32_e32 v69, 1.0, v69
	v_rcp_f32_e32 v81, v69
	v_pk_mul_f32 v[82:83], v[68:69], v[82:83] op_sel_hi:[0,1]
	s_waitcnt vmcnt(0)
	v_pk_mul_f32 v[64:65], v[64:65], v[82:83]
	v_pk_mul_f32 v[74:75], v[68:69], v[74:75] op_sel_hi:[0,1]
	v_pk_mul_f32 v[78:79], v[80:81], v[78:79]
	v_pk_mul_f32 v[66:67], v[66:67], v[74:75]
	v_pk_mul_f32 v[64:65], v[64:65], v[78:79]
	s_nop 0
	v_cvt_pk_bf16_f32 v64, v64, v65
	v_mul_f32_e32 v65, 0xbfb8aa3b, v76
	v_exp_f32_e32 v65, v65
	s_nop 0
	v_add_f32_e32 v65, 1.0, v65
	v_rcp_f32_e32 v78, v65
	v_mul_f32_e32 v65, 0xbfb8aa3b, v77
	v_exp_f32_e32 v65, v65
	s_nop 0
	v_add_f32_e32 v65, 1.0, v65
	v_rcp_f32_e32 v79, v65
	s_nop 0
	v_pk_mul_f32 v[74:75], v[78:79], v[76:77]
	s_nop 0
	v_pk_mul_f32 v[66:67], v[66:67], v[74:75]
	s_nop 0
	v_cvt_pk_bf16_f32 v65, v66, v67
	global_store_dwordx2 v[98:99], v[64:65], off offset:96
	global_load_dwordx2 v[64:65], v[98:99], off offset:112
	s_nop 0
	global_load_dwordx2 v[66:67], v[72:73], off offset:112
	s_nop 0
	global_load_dwordx4 v[70:73], v[70:71], off offset:224
	s_waitcnt vmcnt(2)
	v_lshlrev_b32_e32 v78, 16, v64
	s_waitcnt vmcnt(1)
	v_lshlrev_b32_e32 v74, 16, v66
	v_mul_f32_e32 v69, 0xbfb8aa3b, v74
	v_exp_f32_e32 v69, v69
	v_and_b32_e32 v75, 0xffff0000, v66
	v_lshlrev_b32_e32 v66, 16, v67
	v_and_b32_e32 v79, 0xffff0000, v64
	v_add_f32_e32 v69, 1.0, v69
	v_rcp_f32_e32 v76, v69
	v_mul_f32_e32 v69, 0xbfb8aa3b, v75
	v_exp_f32_e32 v69, v69
	v_and_b32_e32 v67, 0xffff0000, v67
	v_add_f32_e32 v69, 1.0, v69
	v_rcp_f32_e32 v77, v69
	v_pk_mul_f32 v[78:79], v[68:69], v[78:79] op_sel_hi:[0,1]
	v_mul_f32_e32 v69, 0xbfb8aa3b, v66
	v_exp_f32_e32 v69, v69
	s_waitcnt vmcnt(0)
	v_pk_mul_f32 v[70:71], v[70:71], v[78:79]
	v_pk_mul_f32 v[74:75], v[76:77], v[74:75]
	v_add_f32_e32 v69, 1.0, v69
	v_pk_mul_f32 v[70:71], v[70:71], v[74:75]
	v_lshlrev_b32_e32 v74, 16, v65
	v_cvt_pk_bf16_f32 v64, v70, v71
	v_rcp_f32_e32 v70, v69
	v_mul_f32_e32 v69, 0xbfb8aa3b, v67
	v_exp_f32_e32 v69, v69
	v_and_b32_e32 v75, 0xffff0000, v65
	v_add_f32_e32 v69, 1.0, v69
	v_rcp_f32_e32 v71, v69
	v_pk_mul_f32 v[68:69], v[68:69], v[74:75] op_sel_hi:[0,1]
	v_pk_mul_f32 v[68:69], v[72:73], v[68:69]
	v_pk_mul_f32 v[66:67], v[70:71], v[66:67]
	s_nop 0
	v_pk_mul_f32 v[66:67], v[68:69], v[66:67]
	s_nop 0
	v_cvt_pk_bf16_f32 v65, v66, v67
	global_store_dwordx2 v[98:99], v[64:65], off offset:112
	s_add_u32 s2, s12, 0xb200000
	v_and_b32_e32 v114, 31, v94
	v_ashrrev_i32_e32 v115, 5, v94
	s_addc_u32 s3, s13, 0
	v_mov_b64_e32 v[96:97], s[2:3]
	v_mad_i64_i32 v[64:65], s[2:3], v93, s6, v[96:97]
	v_ashrrev_i32_e32 v95, 31, v94
	v_lshl_add_u64 v[64:65], v[64:65], 0, v[90:91]
	v_lshl_add_u64 v[64:65], v[94:95], 1, v[64:65]
	v_add_co_u32_e32 v76, vcc, s37, v64
	s_movk_i32 s2, 0x5000
	s_nop 0
	v_addc_co_u32_e32 v77, vcc, 0, v65, vcc
	global_load_ushort v95, v[76:77], off offset:3072
	global_load_ushort v107, v[76:77], off offset:1536
	v_add_co_u32_e32 v66, vcc, s20, v64
	v_lshl_add_u32 v88, v94, 1, v92
	s_nop 0
	v_addc_co_u32_e32 v67, vcc, 0, v65, vcc
	v_add_co_u32_e32 v68, vcc, s2, v64
	s_movk_i32 s2, 0x7000
	s_nop 0
	v_addc_co_u32_e32 v69, vcc, 0, v65, vcc
	v_add_co_u32_e32 v70, vcc, s2, v64
	s_mov_b32 s2, 0x10000
	s_nop 0
	v_addc_co_u32_e32 v71, vcc, 0, v65, vcc
	v_add_co_u32_e32 v80, vcc, s28, v64
	s_waitcnt vmcnt(0)
	v_lshlrev_b32_e32 v107, 16, v107
	v_addc_co_u32_e32 v81, vcc, 0, v65, vcc
	v_add_co_u32_e32 v82, vcc, s29, v64
	v_readlane_b32 s28, v255, 28
	s_nop 0
	v_addc_co_u32_e32 v83, vcc, 0, v65, vcc
	v_add_co_u32_e32 v84, vcc, s18, v64
	v_readlane_b32 s29, v255, 29
	s_nop 0
	v_addc_co_u32_e32 v85, vcc, 0, v65, vcc
	v_add_co_u32_e32 v86, vcc, s2, v64
	s_mov_b32 s2, 0x14000
	s_nop 0
	v_addc_co_u32_e32 v87, vcc, 0, v65, vcc
	v_add_co_u32_e32 v72, vcc, s51, v64
	s_nop 1
	v_addc_co_u32_e32 v73, vcc, 0, v65, vcc
	v_add_co_u32_e32 v74, vcc, s2, v64
	s_mov_b32 s2, 0x1a000
	s_nop 0
	v_addc_co_u32_e32 v75, vcc, 0, v65, vcc
	v_add_co_u32_e32 v78, vcc, s30, v64
	s_nop 1
	v_addc_co_u32_e32 v79, vcc, 0, v65, vcc
	v_add_co_u32_e32 v98, vcc, s31, v64
	s_mov_b64 s[30:31], 0x4800
	s_nop 0
	v_addc_co_u32_e32 v99, vcc, 0, v65, vcc
	v_add_co_u32_e32 v100, vcc, s34, v64
	s_nop 1
	v_addc_co_u32_e32 v101, vcc, 0, v65, vcc
	v_add_co_u32_e32 v102, vcc, s35, v64
	s_mov_b64 s[34:35], 0x1200
	s_nop 0
	v_addc_co_u32_e32 v103, vcc, 0, v65, vcc
	v_add_co_u32_e32 v104, vcc, s19, v64
	v_readlane_b32 s18, v255, 26
	s_nop 0
	v_addc_co_u32_e32 v105, vcc, 0, v65, vcc
	v_add_co_u32_e32 v118, vcc, s36, v64
	v_readlane_b32 s36, v255, 30
	s_nop 0
	v_addc_co_u32_e32 v119, vcc, 0, v65, vcc
	v_add_co_u32_e32 v108, vcc, s21, v64
	v_readlane_b32 s19, v255, 27
	s_nop 0
	v_addc_co_u32_e32 v109, vcc, 0, v65, vcc
	global_load_ushort v111, v[108:109], off offset:512
	global_load_ushort v106, v[108:109], off offset:1024
	global_load_ushort v113, v[108:109], off offset:2048
	s_nop 0
	global_load_ushort v108, v[76:77], off offset:2048
	global_load_ushort v110, v[118:119], off offset:1536
	global_load_ushort v120, v[118:119], off offset:2560
	global_load_ushort v121, v[102:103], off offset:3584
	global_load_ushort v122, v[104:105], off offset:512
	global_load_ushort v152, v[118:119], off offset:1024
	global_load_ushort v153, v[104:105], off offset:1536
	global_load_ushort v154, v[104:105], off
	global_load_ushort v158, v[102:103], off offset:3072
	global_load_ushort v160, v[102:103], off
	global_load_ushort v165, v[100:101], off offset:3584
	v_lshlrev_b32_e32 v76, 16, v95
	v_max_f32_e32 v76, v76, v76
	v_med3_f32 v76, v76, s9, v244
	v_mul_f32_e32 v76, 0xbfb8aa3b, v76
	v_exp_f32_e32 v95, v76
	v_add_co_u32_e32 v76, vcc, s42, v64
	global_load_ushort v123, v[78:79], off offset:512
	global_load_ushort v124, v[98:99], off offset:1536
	global_load_ushort v126, v[100:101], off offset:2560
	global_load_ushort v166, v[100:101], off offset:2048
	global_load_ushort v168, v[98:99], off offset:2560
	global_load_ushort v171, v[98:99], off offset:1024
	global_load_ushort v167, v[78:79], off offset:1536
	global_load_ushort v163, v[78:79], off
	v_add_f32_e32 v109, 1.0, v95
	v_addc_co_u32_e32 v77, vcc, 0, v65, vcc
	v_rcp_f32_e32 v109, v109
	v_add_co_u32_e32 v134, vcc, s17, v64
	v_readlane_b32 s37, v255, 31
	s_nop 0
	v_addc_co_u32_e32 v135, vcc, 0, v65, vcc
	v_add_co_u32_e32 v132, vcc, s16, v64
	v_fma_f32 v112, v117, v109, v116
	s_nop 0
	v_addc_co_u32_e32 v133, vcc, 0, v65, vcc
	v_max_f32_e32 v150, 0xda24260, v112
	v_add_co_u32_e32 v118, vcc, s2, v64
	v_mul_f32_e32 v95, v95, v109
	v_rcp_f32_e32 v109, v150
	v_addc_co_u32_e32 v119, vcc, 0, v65, vcc
	s_mov_b32 s2, 0x18000
	v_add_co_u32_e32 v136, vcc, s2, v64
	s_mov_b32 s2, 0x16000
	s_nop 0
	v_addc_co_u32_e32 v137, vcc, 0, v65, vcc
	v_mul_f32_e32 v95, v117, v95
	v_mul_f32_e32 v107, v150, v107
	v_add_co_u32_e32 v78, vcc, s2, v64
	v_bfe_u32 v112, v107, 16, 1
	v_mul_f32_e32 v95, v95, v109
	v_addc_co_u32_e32 v79, vcc, 0, v65, vcc
	v_add3_u32 v151, v107, v112, s10
	v_bfe_u32 v107, v95, 16, 1
	v_add_co_u32_e32 v138, vcc, s43, v64
	v_add3_u32 v112, v95, v107, s10
	s_nop 0
	v_addc_co_u32_e32 v139, vcc, 0, v65, vcc
	global_load_ushort v125, v[84:85], off offset:512
	global_load_ushort v127, v[86:87], off offset:1536
	global_load_ushort v128, v[72:73], off offset:2560
	global_load_ushort v129, v[74:75], off offset:3584
	global_load_ushort v157, v[74:75], off offset:3072
	global_load_ushort v155, v[74:75], off
	global_load_ushort v109, v[72:73], off offset:3584
	global_load_ushort v107, v[72:73], off offset:2048
	global_load_ushort v172, v[76:77], off offset:1024
	global_load_ushort v173, v[134:135], off offset:3584
	global_load_ushort v174, v[132:133], off offset:2560
	global_load_ushort v175, v[118:119], off offset:1536
	global_load_ushort v131, v[118:119], off offset:2048
	s_nop 0
	global_load_ushort v132, v[132:133], off offset:3072
	s_nop 0
	global_load_ushort v176, v[134:135], off offset:512
	global_load_ushort v133, v[76:77], off
	global_load_ushort v177, v[118:119], off offset:3072
	global_load_ushort v170, v[136:137], off offset:2048
	global_load_ushort v169, v[136:137], off offset:512
	global_load_ushort v164, v[78:79], off offset:1024
	global_load_ushort v162, v[138:139], off offset:3584
	global_load_ushort v159, v[138:139], off offset:512
	global_load_ushort v135, v[78:79], off
	s_nop 0
	global_load_ushort v137, v[136:137], off offset:1024
	v_add_co_u32_e32 v144, vcc, s44, v64
	global_load_ushort v130, v[64:65], off offset:2560
	global_load_ushort v134, v[66:67], off offset:3584
	global_load_ushort v136, v[68:69], off offset:512
	global_load_ushort v138, v[70:71], off offset:1536
	global_load_ushort v139, v[80:81], off offset:2560
	global_load_ushort v141, v[82:83], off offset:3584
	global_load_ushort v142, v[84:85], off offset:-4096
	global_load_ushort v140, v[68:69], off offset:-4096
	v_addc_co_u32_e32 v145, vcc, 0, v65, vcc
	v_add_co_u32_e32 v100, vcc, s45, v64
	v_readlane_b32 s42, v255, 32
	s_nop 0
	v_addc_co_u32_e32 v101, vcc, 0, v65, vcc
	v_add_co_u32_e32 v102, vcc, s46, v64
	v_readlane_b32 s43, v255, 33
	s_nop 0
	v_addc_co_u32_e32 v103, vcc, 0, v65, vcc
	v_add_co_u32_e32 v104, vcc, s47, v64
	v_readlane_b32 s46, v255, 38
	s_nop 0
	v_addc_co_u32_e32 v105, vcc, 0, v65, vcc
	v_add_co_u32_e32 v98, vcc, s15, v64
	s_waitcnt vmcnt(53)
	v_lshlrev_b32_e32 v111, 16, v111
	v_addc_co_u32_e32 v99, vcc, 0, v65, vcc
	s_waitcnt vmcnt(51)
	v_lshlrev_b32_e32 v113, 16, v113
	s_waitcnt vmcnt(48)
	v_lshlrev_b32_e32 v72, 16, v120
	v_max_f32_e32 v72, v72, v72
	v_med3_f32 v72, v72, s9, v244
	v_mul_f32_e32 v72, 0xbfb8aa3b, v72
	v_exp_f32_e32 v95, v72
	v_add_co_u32_e32 v74, vcc, s14, v64
	v_max_f32_e32 v113, v113, v113
	v_add_f32_e32 v118, 1.0, v95
	v_rcp_f32_e32 v118, v118
	v_addc_co_u32_e32 v75, vcc, 0, v65, vcc
	v_med3_f32 v113, v113, s9, v244
	v_fma_f32 v119, v117, v118, v116
	v_mul_f32_e32 v119, v150, v119
	v_max_f32_e32 v119, 0xda24260, v119
	v_add_co_u32_e32 v76, vcc, s27, v64
	v_rcp_f32_e32 v120, v119
	v_mul_f32_e32 v113, 0xbfb8aa3b, v113
	v_addc_co_u32_e32 v77, vcc, 0, v65, vcc
	v_exp_f32_e32 v113, v113
	v_add_co_u32_e32 v78, vcc, s7, v64
	v_mul_f32_e32 v95, v95, v118
	s_nop 0
	v_addc_co_u32_e32 v79, vcc, 0, v65, vcc
	v_mul_f32_e32 v95, v117, v95
	v_add_co_u32_e32 v72, vcc, s5, v64
	v_mul_f32_e32 v95, v95, v120
	s_nop 0
	v_addc_co_u32_e32 v73, vcc, 0, v65, vcc
	global_load_ushort v156, v[144:145], off offset:2560
	global_load_ushort v148, v[144:145], off offset:3072
	global_load_ushort v149, v[100:101], off offset:2048
	global_load_ushort v147, v[102:103], off offset:1024
	global_load_ushort v146, v[98:99], off offset:3072
	s_nop 0
	global_load_ushort v144, v[74:75], off offset:2048
	global_load_ushort v145, v[76:77], off offset:1024
	global_load_ushort v143, v[72:73], off offset:3072
	s_mov_b32 s101, 0
	s_mov_b32 s100, 0xa000
	v_lshl_add_u64 v[196:197], v[64:65], 0, s[100:101]
	global_load_ushort v200, v[196:197], off offset:-2048
	global_load_ushort v201, v[196:197], off offset:-512
	global_load_ushort v202, v[196:197], off offset:2560
	s_mov_b32 s100, 0xb800
	v_lshl_add_u64 v[198:199], v[64:65], 0, s[100:101]
	global_load_ushort v203, v[198:199], off offset:-2048
	global_load_ushort v206, v[198:199], off offset:1024
	global_load_ushort v207, v[198:199], off offset:2560
	s_mov_b32 s100, 0xd600
	v_lshl_add_u64 v[196:197], v[64:65], 0, s[100:101]
	global_load_ushort v208, v[196:197], off offset:-2048
	global_load_ushort v209, v[196:197], off offset:-512
	global_load_ushort v210, v[196:197], off offset:2560
	s_mov_b32 s100, 0xee00
	v_lshl_add_u64 v[198:199], v[64:65], 0, s[100:101]
	global_load_ushort v211, v[198:199], off offset:-2048
	global_load_ushort v212, v[198:199], off offset:1024
	global_load_ushort v213, v[198:199], off offset:2560
	s_mov_b32 s100, 0x10c00
	v_lshl_add_u64 v[196:197], v[64:65], 0, s[100:101]
	global_load_ushort v214, v[196:197], off offset:-2048
	global_load_ushort v215, v[196:197], off offset:-512
	global_load_ushort v216, v[196:197], off offset:2560
	s_mov_b32 s100, 0x12400
	v_lshl_add_u64 v[198:199], v[64:65], 0, s[100:101]
	global_load_ushort v217, v[198:199], off offset:-2048
	s_mov_b32 s100, 0x1000
	v_lshl_add_u64 v[196:197], v[64:65], 0, s[100:101]
	global_load_ushort v218, v[196:197], off offset:-2048
	global_load_ushort v219, v[196:197], off offset:-512
	global_load_ushort v220, v[196:197], off offset:2560
	s_mov_b32 s100, 0x2800
	v_lshl_add_u64 v[198:199], v[64:65], 0, s[100:101]
	global_load_ushort v221, v[198:199], off offset:-2048
	global_load_ushort v222, v[198:199], off offset:1024
	global_load_ushort v223, v[198:199], off offset:2560
	s_mov_b32 s100, 0x4600
	v_lshl_add_u64 v[196:197], v[64:65], 0, s[100:101]
	global_load_ushort v224, v[196:197], off offset:-2048
	global_load_ushort v225, v[196:197], off offset:-512
	global_load_ushort v226, v[196:197], off offset:2560
	s_mov_b32 s100, 0x5e00
	v_lshl_add_u64 v[198:199], v[64:65], 0, s[100:101]
	global_load_ushort v227, v[198:199], off offset:-2048
	global_load_ushort v228, v[198:199], off offset:1024
	global_load_ushort v229, v[198:199], off offset:2560
	s_mov_b32 s100, 0x7c00
	v_lshl_add_u64 v[196:197], v[64:65], 0, s[100:101]
	global_load_ushort v230, v[196:197], off offset:-2048
	global_load_ushort v231, v[196:197], off offset:-512
	global_load_ushort v232, v[196:197], off offset:2560
	s_mov_b32 s100, 0x9400
	v_lshl_add_u64 v[198:199], v[64:65], 0, s[100:101]
	global_load_ushort v233, v[198:199], off offset:-2048
	v_bfe_u32 v118, v95, 16, 1
	v_add_f32_e32 v120, 1.0, v113
	v_add3_u32 v95, v95, v118, s10
	s_waitcnt vmcnt(63)
	v_lshlrev_b32_e32 v118, 16, v152
	v_rcp_f32_e32 v120, v120
	v_mul_f32_e32 v118, v119, v118
	v_bfe_u32 v150, v118, 16, 1
	v_add3_u32 v118, v118, v150, s10
	ds_write_b16_d16_hi v88, v118 offset:4320
	v_fma_f32 v118, v117, v120, v116
	v_mul_f32_e32 v118, v119, v118
	v_mul_f32_e32 v113, v113, v120
	s_waitcnt vmcnt(63)
	v_lshlrev_b32_e32 v120, 16, v153
	v_max_f32_e32 v118, 0xda24260, v118
	v_max_f32_e32 v120, v120, v120
	v_rcp_f32_e32 v119, v118
	v_med3_f32 v120, v120, s9, v244
	v_mul_f32_e32 v120, 0xbfb8aa3b, v120
	v_exp_f32_e32 v120, v120
	v_mul_f32_e32 v113, v117, v113
	v_mul_f32_e32 v113, v113, v119
	v_bfe_u32 v119, v113, 16, 1
	ds_write_b16_d16_hi v88, v151 offset:4464
	v_add3_u32 v151, v113, v119, s10
	v_add_f32_e32 v113, 1.0, v120
	v_rcp_f32_e32 v113, v113
	v_mul_f32_e32 v111, v118, v111
	v_bfe_u32 v119, v111, 16, 1
	v_add3_u32 v111, v111, v119, s10
	ds_write_b16_d16_hi v88, v111 offset:4176
	v_fma_f32 v111, v117, v113, v116
	s_waitcnt vmcnt(63)
	v_lshlrev_b32_e32 v119, 16, v172
	v_mul_f32_e32 v111, v118, v111
	v_max_f32_e32 v119, v119, v119
	v_max_f32_e32 v111, 0xda24260, v111
	v_med3_f32 v119, v119, s9, v244
	v_rcp_f32_e32 v118, v111
	v_mul_f32_e32 v119, 0xbfb8aa3b, v119
	v_exp_f32_e32 v119, v119
	v_mul_f32_e32 v113, v120, v113
	v_mul_f32_e32 v113, v117, v113
	v_mul_f32_e32 v113, v113, v118
	v_bfe_u32 v118, v113, 16, 1
	v_add_f32_e32 v120, 1.0, v119
	v_add3_u32 v118, v113, v118, s10
	v_lshlrev_b32_e32 v113, 16, v154
	v_rcp_f32_e32 v120, v120
	v_mul_f32_e32 v113, v111, v113
	v_bfe_u32 v150, v113, 16, 1
	v_add3_u32 v113, v113, v150, s10
	ds_write_b16_d16_hi v88, v113 offset:4032
	v_fma_f32 v113, v117, v120, v116
	v_mul_f32_e32 v111, v111, v113
	v_mul_f32_e32 v119, v119, v120
	s_waitcnt vmcnt(57)
	v_lshlrev_b32_e32 v120, 16, v176
	v_max_f32_e32 v111, 0xda24260, v111
	v_max_f32_e32 v120, v120, v120
	v_rcp_f32_e32 v113, v111
	v_med3_f32 v120, v120, s9, v244
	v_mul_f32_e32 v120, 0xbfb8aa3b, v120
	v_exp_f32_e32 v120, v120
	v_mul_f32_e32 v119, v117, v119
	v_mul_f32_e32 v113, v119, v113
	v_bfe_u32 v119, v113, 16, 1
	v_add3_u32 v152, v113, v119, s10
	v_add_f32_e32 v119, 1.0, v120
	v_lshlrev_b32_e32 v113, 16, v173
	v_rcp_f32_e32 v119, v119
	v_mul_f32_e32 v113, v111, v113
	v_bfe_u32 v150, v113, 16, 1
	v_add3_u32 v113, v113, v150, s10
	ds_write_b16_d16_hi v88, v113 offset:3888
	v_fma_f32 v113, v117, v119, v116
	v_mul_f32_e32 v119, v120, v119
	v_lshlrev_b32_e32 v120, 16, v160
	v_mul_f32_e32 v111, v111, v113
	v_max_f32_e32 v120, v120, v120
	v_max_f32_e32 v111, 0xda24260, v111
	v_med3_f32 v120, v120, s9, v244
	v_rcp_f32_e32 v113, v111
	v_mul_f32_e32 v120, 0xbfb8aa3b, v120
	v_exp_f32_e32 v120, v120
	v_mul_f32_e32 v119, v117, v119
	v_mul_f32_e32 v113, v119, v113
	v_bfe_u32 v119, v113, 16, 1
	v_add_f32_e32 v150, 1.0, v120
	v_add3_u32 v119, v113, v119, s10
	v_lshlrev_b32_e32 v113, 16, v158
	v_rcp_f32_e32 v150, v150
	v_mul_f32_e32 v113, v111, v113
	v_bfe_u32 v153, v113, 16, 1
	v_add3_u32 v113, v113, v153, s10
	ds_write_b16_d16_hi v88, v113 offset:3744
	v_fma_f32 v113, v117, v150, v116
	v_mul_f32_e32 v111, v111, v113
	v_mul_f32_e32 v120, v120, v150
	v_lshlrev_b32_e32 v150, 16, v165
	v_max_f32_e32 v111, 0xda24260, v111
	v_max_f32_e32 v150, v150, v150
	v_rcp_f32_e32 v113, v111
	v_med3_f32 v150, v150, s9, v244
	v_mul_f32_e32 v150, 0xbfb8aa3b, v150
	v_exp_f32_e32 v150, v150
	v_mul_f32_e32 v120, v117, v120
	v_mul_f32_e32 v113, v120, v113
	v_bfe_u32 v120, v113, 16, 1
	v_add3_u32 v153, v113, v120, s10
	v_add_f32_e32 v120, 1.0, v150
	v_lshlrev_b32_e32 v113, 16, v174
	v_rcp_f32_e32 v120, v120
	v_mul_f32_e32 v113, v111, v113
	v_bfe_u32 v154, v113, 16, 1
	v_add3_u32 v113, v113, v154, s10
	ds_write_b16_d16_hi v88, v113 offset:3600
	v_fma_f32 v113, v117, v120, v116
	v_mul_f32_e32 v111, v111, v113
	v_max_f32_e32 v111, 0xda24260, v111
	v_rcp_f32_e32 v113, v111
	v_mul_f32_e32 v120, v150, v120
	v_mul_f32_e32 v120, v117, v120
	v_readlane_b32 s47, v255, 39
	v_mul_f32_e32 v113, v120, v113
	v_bfe_u32 v120, v113, 16, 1
	v_add3_u32 v120, v113, v120, s10
	v_lshlrev_b32_e32 v113, 16, v166
	v_mul_f32_e32 v113, v111, v113
	v_bfe_u32 v150, v113, 16, 1
	v_add3_u32 v113, v113, v150, s10
	ds_write_b16_d16_hi v88, v112 offset:9072
	ds_write_b16_d16_hi v88, v95 offset:8928
	ds_write_b16_d16_hi v88, v151 offset:8784
	ds_write_b16_d16_hi v88, v118 offset:8640
	ds_write_b16_d16_hi v88, v152 offset:8496
	ds_write_b16_d16_hi v88, v119 offset:8352
	ds_write_b16_d16_hi v88, v153 offset:8208
	ds_write_b16_d16_hi v88, v113 offset:3456
	ds_write_b16_d16_hi v88, v120 offset:8064
	s_waitcnt vmcnt(55)
	v_lshlrev_b32_e32 v113, 16, v177
	v_max_f32_e32 v113, v113, v113
	v_med3_f32 v113, v113, s9, v244
	v_mul_f32_e32 v113, 0xbfb8aa3b, v113
	v_exp_f32_e32 v113, v113
	v_lshlrev_b32_e32 v107, 16, v107
	v_add_f32_e32 v150, 1.0, v113
	v_rcp_f32_e32 v150, v150
	s_nop 0
	v_fma_f32 v154, v117, v150, v116
	v_mul_f32_e32 v111, v111, v154
	v_max_f32_e32 v111, 0xda24260, v111
	v_mul_f32_e32 v113, v113, v150
	v_rcp_f32_e32 v150, v111
	v_mul_f32_e32 v113, v117, v113
	v_mul_f32_e32 v113, v113, v150
	v_bfe_u32 v150, v113, 16, 1
	v_add3_u32 v154, v113, v150, s10
	v_lshlrev_b32_e32 v113, 16, v175
	v_mul_f32_e32 v113, v111, v113
	v_bfe_u32 v150, v113, 16, 1
	v_add3_u32 v113, v113, v150, s10
	ds_write_b16_d16_hi v88, v113 offset:3312
	ds_write_b16_d16_hi v88, v154 offset:7920
	v_lshlrev_b32_e32 v113, 16, v168
	v_max_f32_e32 v113, v113, v113
	v_med3_f32 v113, v113, s9, v244
	v_mul_f32_e32 v113, 0xbfb8aa3b, v113
	v_exp_f32_e32 v113, v113
	s_nop 0
	v_add_f32_e32 v150, 1.0, v113
	v_rcp_f32_e32 v150, v150
	s_nop 0
	v_fma_f32 v158, v117, v150, v116
	v_mul_f32_e32 v111, v111, v158
	v_max_f32_e32 v172, 0xda24260, v111
	v_rcp_f32_e32 v111, v172
	v_mul_f32_e32 v113, v113, v150
	v_mul_f32_e32 v113, v117, v113
	v_mul_f32_e32 v111, v113, v111
	v_bfe_u32 v113, v111, 16, 1
	v_add3_u32 v150, v111, v113, s10
	v_lshlrev_b32_e32 v111, 16, v171
	v_mul_f32_e32 v111, v172, v111
	v_bfe_u32 v113, v111, 16, 1
	v_add3_u32 v171, v111, v113, s10
	s_nop 0
	v_add_co_u32_e32 v84, vcc, s50, v64
	s_nop 1
	v_addc_co_u32_e32 v85, vcc, 0, v65, vcc
	s_nop 0
	s_nop 0
	s_waitcnt vmcnt(54)
	v_lshlrev_b32_e32 v80, 16, v170
	v_max_f32_e32 v80, v80, v80
	v_med3_f32 v80, v80, s9, v244
	v_mul_f32_e32 v80, 0xbfb8aa3b, v80
	v_exp_f32_e32 v80, v80
	ds_write_b16_d16_hi v88, v171 offset:3168
	ds_write_b16_d16_hi v88, v150 offset:7776
	v_add_f32_e32 v84, 1.0, v80
	v_rcp_f32_e32 v84, v84
	s_nop 0
	v_fma_f32 v85, v117, v84, v116
	v_mul_f32_e32 v80, v80, v84
	v_mul_f32_e32 v84, v172, v85
	v_max_f32_e32 v84, 0xda24260, v84
	v_rcp_f32_e32 v85, v84
	v_mul_f32_e32 v80, v117, v80
	v_mul_f32_e32 v80, v80, v85
	v_bfe_u32 v85, v80, 16, 1
	v_add3_u32 v85, v80, v85, s10
	s_waitcnt vmcnt(53)
	v_lshlrev_b32_e32 v80, 16, v169
	v_mul_f32_e32 v80, v84, v80
	v_bfe_u32 v98, v80, 16, 1
	v_add3_u32 v80, v80, v98, s10
	ds_write_b16_d16_hi v88, v80 offset:3024
	ds_write_b16_d16_hi v88, v85 offset:7632
	v_lshlrev_b32_e32 v80, 16, v167
	v_max_f32_e32 v80, v80, v80
	v_med3_f32 v80, v80, s9, v244
	v_mul_f32_e32 v80, 0xbfb8aa3b, v80
	v_exp_f32_e32 v80, v80
	s_nop 0
	v_add_f32_e32 v98, 1.0, v80
	v_rcp_f32_e32 v98, v98
	s_nop 0
	v_fma_f32 v99, v117, v98, v116
	v_mul_f32_e32 v84, v84, v99
	v_max_f32_e32 v84, 0xda24260, v84
	v_mul_f32_e32 v80, v80, v98
	v_rcp_f32_e32 v98, v84
	v_mul_f32_e32 v80, v117, v80
	v_mul_f32_e32 v80, v80, v98
	v_bfe_u32 v98, v80, 16, 1
	v_add3_u32 v80, v80, v98, s10
	v_lshlrev_b32_e32 v98, 16, v163
	v_mul_f32_e32 v98, v84, v98
	v_bfe_u32 v99, v98, 16, 1
	v_add3_u32 v98, v98, v99, s10
	ds_write_b16_d16_hi v88, v98 offset:2880
	ds_write_b16_d16_hi v88, v80 offset:7488
	s_waitcnt vmcnt(52)
	v_lshlrev_b32_e32 v98, 16, v164
	v_max_f32_e32 v98, v98, v98
	v_med3_f32 v98, v98, s9, v244
	v_mul_f32_e32 v98, 0xbfb8aa3b, v98
	v_exp_f32_e32 v98, v98
	s_nop 0
	v_add_f32_e32 v99, 1.0, v98
	v_rcp_f32_e32 v99, v99
	s_nop 0
	v_fma_f32 v104, v117, v99, v116
	v_mul_f32_e32 v84, v84, v104
	v_max_f32_e32 v84, 0xda24260, v84
	v_mul_f32_e32 v98, v98, v99
	v_rcp_f32_e32 v99, v84
	v_mul_f32_e32 v98, v117, v98
	v_mul_f32_e32 v98, v98, v99
	v_bfe_u32 v99, v98, 16, 1
	v_add3_u32 v99, v98, v99, s10
	s_waitcnt vmcnt(51)
	v_lshlrev_b32_e32 v98, 16, v162
	v_mul_f32_e32 v98, v84, v98
	v_bfe_u32 v104, v98, 16, 1
	v_add3_u32 v98, v98, v104, s10
	ds_write_b16_d16_hi v88, v98 offset:2736
	ds_write_b16_d16_hi v88, v99 offset:7344
	s_waitcnt vmcnt(50)
	v_lshlrev_b32_e32 v98, 16, v159
	v_max_f32_e32 v98, v98, v98
	v_med3_f32 v98, v98, s9, v244
	v_mul_f32_e32 v98, 0xbfb8aa3b, v98
	v_exp_f32_e32 v98, v98
	s_nop 0
	v_add_f32_e32 v104, 1.0, v98
	v_rcp_f32_e32 v104, v104
	s_nop 0
	v_fma_f32 v105, v117, v104, v116
	v_mul_f32_e32 v84, v84, v105
	v_mul_f32_e32 v98, v98, v104
	v_max_f32_e32 v104, 0xda24260, v84
	v_rcp_f32_e32 v84, v104
	v_mul_f32_e32 v98, v117, v98
	v_mul_f32_e32 v84, v98, v84
	v_bfe_u32 v98, v84, 16, 1
	v_add3_u32 v84, v84, v98, s10
	v_lshlrev_b32_e32 v98, 16, v157
	v_mul_f32_e32 v98, v104, v98
	v_bfe_u32 v105, v98, 16, 1
	v_add3_u32 v98, v98, v105, s10
	ds_write_b16_d16_hi v88, v98 offset:2592
	ds_write_b16_d16_hi v88, v84 offset:7200
	v_lshlrev_b32_e32 v98, 16, v155
	v_max_f32_e32 v98, v98, v98
	v_med3_f32 v98, v98, s9, v244
	v_mul_f32_e32 v98, 0xbfb8aa3b, v98
	v_exp_f32_e32 v98, v98
	s_nop 0
	v_add_f32_e32 v105, 1.0, v98
	v_rcp_f32_e32 v105, v105
	s_nop 0
	v_fma_f32 v155, v117, v105, v116
	v_mul_f32_e32 v104, v104, v155
	v_max_f32_e32 v104, 0xda24260, v104
	v_mul_f32_e32 v98, v98, v105
	v_rcp_f32_e32 v105, v104
	v_mul_f32_e32 v98, v117, v98
	v_mul_f32_e32 v98, v98, v105
	v_bfe_u32 v105, v98, 16, 1
	v_add3_u32 v105, v98, v105, s10
	s_waitcnt vmcnt(39)
	v_lshlrev_b32_e32 v98, 16, v156
	v_mul_f32_e32 v98, v104, v98
	v_bfe_u32 v155, v98, 16, 1
	v_add3_u32 v98, v98, v155, s10
	ds_write_b16_d16_hi v88, v98 offset:2448
	ds_write_b16_d16_hi v88, v105 offset:7056
	v_lshlrev_b32_e32 v98, 16, v109
	v_max_f32_e32 v98, v98, v98
	v_med3_f32 v98, v98, s9, v244
	v_mul_f32_e32 v98, 0xbfb8aa3b, v98
	v_exp_f32_e32 v98, v98
	s_nop 0
	v_add_f32_e32 v109, 1.0, v98
	v_rcp_f32_e32 v109, v109
	s_nop 0
	v_fma_f32 v155, v117, v109, v116
	v_mul_f32_e32 v104, v104, v155
	v_max_f32_e32 v104, 0xda24260, v104
	v_mul_f32_e32 v98, v98, v109
	v_rcp_f32_e32 v109, v104
	v_mul_f32_e32 v98, v117, v98
	v_mul_f32_e32 v107, v104, v107
	v_mul_f32_e32 v98, v98, v109
	v_bfe_u32 v109, v98, 16, 1
	v_add3_u32 v98, v98, v109, s10
	v_bfe_u32 v109, v107, 16, 1
	v_add3_u32 v107, v107, v109, s10
	ds_write_b16_d16_hi v88, v107 offset:2304
	ds_write_b16_d16_hi v88, v98 offset:6912
	s_waitcnt vmcnt(16)
	v_lshlrev_b32_e32 v107, 16, v217
	v_max_f32_e32 v107, v107, v107
	v_med3_f32 v107, v107, s9, v244
	v_mul_f32_e32 v107, 0xbfb8aa3b, v107
	v_exp_f32_e32 v107, v107
	s_nop 0
	v_add_f32_e32 v109, 1.0, v107
	v_rcp_f32_e32 v109, v109
	s_nop 0
	v_fma_f32 v155, v117, v109, v116
	v_mul_f32_e32 v104, v104, v155
	v_max_f32_e32 v104, 0xda24260, v104
	v_mul_f32_e32 v107, v107, v109
	v_rcp_f32_e32 v109, v104
	v_mul_f32_e32 v107, v117, v107
	v_mul_f32_e32 v107, v107, v109
	v_bfe_u32 v109, v107, 16, 1
	v_add3_u32 v107, v107, v109, s10
	s_waitcnt vmcnt(16)
	v_lshlrev_b32_e32 v109, 16, v216
	v_mul_f32_e32 v109, v104, v109
	v_bfe_u32 v155, v109, 16, 1
	v_add3_u32 v109, v109, v155, s10
	ds_write_b16_d16_hi v88, v109 offset:2160
	ds_write_b16_d16_hi v88, v107 offset:6768
	s_waitcnt vmcnt(16)
	v_lshlrev_b32_e32 v109, 16, v215
	v_max_f32_e32 v109, v109, v109
	v_med3_f32 v109, v109, s9, v244
	v_mul_f32_e32 v109, 0xbfb8aa3b, v109
	v_exp_f32_e32 v109, v109
	v_add_co_u32_e32 v68, vcc, s11, v64
	v_add_f32_e32 v155, 1.0, v109
	v_rcp_f32_e32 v155, v155
	v_addc_co_u32_e32 v69, vcc, 0, v65, vcc
	v_fma_f32 v156, v117, v155, v116
	v_mul_f32_e32 v104, v104, v156
	v_max_f32_e32 v173, 0xda24260, v104
	v_rcp_f32_e32 v104, v173
	v_mul_f32_e32 v109, v109, v155
	v_mul_f32_e32 v109, v117, v109
	v_mul_f32_e32 v104, v109, v104
	v_bfe_u32 v109, v104, 16, 1
	v_add3_u32 v104, v104, v109, s10
	s_waitcnt vmcnt(16)
	v_lshlrev_b32_e32 v109, 16, v214
	v_mul_f32_e32 v109, v173, v109
	v_bfe_u32 v155, v109, 16, 1
	v_add3_u32 v109, v109, v155, s10
	s_waitcnt vmcnt(16)
	v_lshlrev_b32_e32 v64, 16, v213
	v_max_f32_e32 v64, v64, v64
	v_med3_f32 v64, v64, s9, v244
	v_mul_f32_e32 v64, 0xbfb8aa3b, v64
	v_exp_f32_e32 v64, v64
	ds_write_b16_d16_hi v88, v109 offset:2016
	ds_write_b16_d16_hi v88, v104 offset:6624
	v_add_f32_e32 v65, 1.0, v64
	v_rcp_f32_e32 v65, v65
	s_nop 0
	v_fma_f32 v66, v117, v65, v116
	v_mul_f32_e32 v64, v64, v65
	v_mul_f32_e32 v65, v173, v66
	v_max_f32_e32 v65, 0xda24260, v65
	v_rcp_f32_e32 v66, v65
	v_mul_f32_e32 v64, v117, v64
	v_mul_f32_e32 v64, v64, v66
	v_bfe_u32 v66, v64, 16, 1
	v_add3_u32 v64, v64, v66, s10
	s_waitcnt vmcnt(16)
	v_lshlrev_b32_e32 v66, 16, v212
	v_mul_f32_e32 v66, v65, v66
	v_bfe_u32 v67, v66, 16, 1
	v_add3_u32 v66, v66, v67, s10
	ds_write_b16_d16_hi v88, v66 offset:1872
	ds_write_b16_d16_hi v88, v64 offset:6480
	s_waitcnt vmcnt(16)
	v_lshlrev_b32_e32 v66, 16, v211
	v_max_f32_e32 v66, v66, v66
	v_med3_f32 v66, v66, s9, v244
	v_mul_f32_e32 v66, 0xbfb8aa3b, v66
	v_exp_f32_e32 v66, v66
	s_nop 0
	v_add_f32_e32 v67, 1.0, v66
	v_rcp_f32_e32 v67, v67
	s_nop 0
	v_fma_f32 v68, v117, v67, v116
	v_mul_f32_e32 v65, v65, v68
	v_max_f32_e32 v65, 0xda24260, v65
	v_mul_f32_e32 v66, v66, v67
	v_rcp_f32_e32 v67, v65
	v_mul_f32_e32 v66, v117, v66
	v_mul_f32_e32 v66, v66, v67
	v_bfe_u32 v67, v66, 16, 1
	v_add3_u32 v158, v66, v67, s10
	s_waitcnt vmcnt(16)
	v_lshlrev_b32_e32 v66, 16, v210
	v_mul_f32_e32 v66, v65, v66
	v_bfe_u32 v67, v66, 16, 1
	v_add3_u32 v66, v66, v67, s10
	ds_write_b16_d16_hi v88, v66 offset:1728
	ds_write_b16_d16_hi v88, v158 offset:6336
	s_waitcnt vmcnt(16)
	v_lshlrev_b32_e32 v66, 16, v209
	v_max_f32_e32 v66, v66, v66
	v_med3_f32 v66, v66, s9, v244
	v_mul_f32_e32 v66, 0xbfb8aa3b, v66
	v_exp_f32_e32 v66, v66
	s_nop 0
	v_add_f32_e32 v67, 1.0, v66
	v_rcp_f32_e32 v67, v67
	s_nop 0
	v_fma_f32 v68, v117, v67, v116
	v_mul_f32_e32 v65, v65, v68
	v_max_f32_e32 v65, 0xda24260, v65
	v_mul_f32_e32 v66, v66, v67
	v_rcp_f32_e32 v67, v65
	v_mul_f32_e32 v66, v117, v66
	v_mul_f32_e32 v66, v66, v67
	v_bfe_u32 v67, v66, 16, 1
	v_add3_u32 v66, v66, v67, s10
	s_waitcnt vmcnt(16)
	v_lshlrev_b32_e32 v67, 16, v208
	v_mul_f32_e32 v67, v65, v67
	v_bfe_u32 v68, v67, 16, 1
	v_add3_u32 v67, v67, v68, s10
	ds_write_b16_d16_hi v88, v67 offset:1584
	ds_write_b16_d16_hi v88, v66 offset:6192
	s_waitcnt vmcnt(16)
	v_lshlrev_b32_e32 v67, 16, v207
	v_max_f32_e32 v67, v67, v67
	v_med3_f32 v67, v67, s9, v244
	v_mul_f32_e32 v67, 0xbfb8aa3b, v67
	v_exp_f32_e32 v67, v67
	s_nop 0
	v_add_f32_e32 v68, 1.0, v67
	v_rcp_f32_e32 v68, v68
	s_nop 0
	v_fma_f32 v69, v117, v68, v116
	v_mul_f32_e32 v65, v65, v69
	v_max_f32_e32 v65, 0xda24260, v65
	v_mul_f32_e32 v67, v67, v68
	v_rcp_f32_e32 v68, v65
	v_mul_f32_e32 v67, v117, v67
	v_mul_f32_e32 v67, v67, v68
	v_bfe_u32 v68, v67, 16, 1
	v_add3_u32 v100, v67, v68, s10
	s_waitcnt vmcnt(16)
	v_lshlrev_b32_e32 v67, 16, v206
	v_mul_f32_e32 v67, v65, v67
	v_bfe_u32 v68, v67, 16, 1
	v_add3_u32 v67, v67, v68, s10
	ds_write_b16_d16_hi v88, v67 offset:1440
	ds_write_b16_d16_hi v88, v100 offset:6048
	s_waitcnt vmcnt(16)
	v_lshlrev_b32_e32 v67, 16, v203
	v_max_f32_e32 v67, v67, v67
	v_med3_f32 v67, v67, s9, v244
	v_mul_f32_e32 v67, 0xbfb8aa3b, v67
	v_exp_f32_e32 v67, v67
	s_nop 0
	v_add_f32_e32 v68, 1.0, v67
	v_rcp_f32_e32 v68, v68
	s_nop 0
	v_fma_f32 v69, v117, v68, v116
	v_mul_f32_e32 v65, v65, v69
	v_max_f32_e32 v65, 0xda24260, v65
	v_mul_f32_e32 v67, v67, v68
	v_rcp_f32_e32 v68, v65
	v_mul_f32_e32 v67, v117, v67
	v_mul_f32_e32 v67, v67, v68
	v_bfe_u32 v68, v67, 16, 1
	v_add3_u32 v67, v67, v68, s10
	s_waitcnt vmcnt(16)
	v_lshlrev_b32_e32 v68, 16, v202
	v_mul_f32_e32 v68, v65, v68
	v_bfe_u32 v69, v68, 16, 1
	v_add3_u32 v68, v68, v69, s10
	ds_write_b16_d16_hi v88, v68 offset:1296
	ds_write_b16_d16_hi v88, v67 offset:5904
	s_waitcnt vmcnt(16)
	v_lshlrev_b32_e32 v68, 16, v201
	v_max_f32_e32 v68, v68, v68
	v_med3_f32 v68, v68, s9, v244
	v_mul_f32_e32 v68, 0xbfb8aa3b, v68
	v_exp_f32_e32 v68, v68
	s_nop 0
	v_add_f32_e32 v69, 1.0, v68
	v_rcp_f32_e32 v69, v69
	s_nop 0
	v_fma_f32 v70, v117, v69, v116
	v_mul_f32_e32 v65, v65, v70
	v_max_f32_e32 v76, 0xda24260, v65
	v_rcp_f32_e32 v65, v76
	v_mul_f32_e32 v68, v68, v69
	v_mul_f32_e32 v68, v117, v68
	v_mul_f32_e32 v65, v68, v65
	v_bfe_u32 v68, v65, 16, 1
	v_add3_u32 v82, v65, v68, s10
	s_waitcnt vmcnt(16)
	v_lshlrev_b32_e32 v65, 16, v200
	v_mul_f32_e32 v65, v76, v65
	v_bfe_u32 v68, v65, 16, 1
	v_add3_u32 v65, v65, v68, s10
	ds_write_b16_d16_hi v88, v65 offset:1152
	ds_write_b16_d16_hi v88, v82 offset:5760
	s_waitcnt vmcnt(0)
	v_lshlrev_b32_e32 v72, 16, v233
	v_max_f32_e32 v72, v72, v72
	v_med3_f32 v72, v72, s9, v244
	v_mul_f32_e32 v72, 0xbfb8aa3b, v72
	v_exp_f32_e32 v86, v72
	v_and_b32_e32 v111, 0xffff0000, v66
	v_lshl_or_b32 v66, v106, 16, v122
	v_and_b32_e32 v113, 0xffff0000, v67
	v_add_f32_e32 v77, 1.0, v86
	v_rcp_f32_e32 v102, v77
	v_lshl_or_b32 v67, v108, 16, v110
	v_and_b32_e32 v81, 0xffff0000, v112
	v_lshl_or_b32 v75, v149, 16, v127
	v_fma_f32 v106, v117, v102, v116
	v_mul_f32_e32 v76, v76, v106
	v_max_f32_e32 v106, 0xda24260, v76
	v_rcp_f32_e32 v108, v106
	v_mul_f32_e32 v86, v86, v102
	v_mul_f32_e32 v86, v117, v86
	v_lshl_or_b32 v65, v133, 16, v121
	v_mul_f32_e32 v86, v86, v108
	v_bfe_u32 v102, v86, 16, 1
	v_add3_u32 v86, v86, v102, s10
	s_waitcnt vmcnt(0)
	v_lshlrev_b32_e32 v102, 16, v231
	v_max_f32_e32 v102, v102, v102
	v_med3_f32 v102, v102, s9, v244
	v_mul_f32_e32 v102, 0xbfb8aa3b, v102
	v_exp_f32_e32 v102, v102
	v_lshlrev_b32_e32 v108, 16, v232
	v_mul_f32_e32 v108, v106, v108
	v_bfe_u32 v112, v108, 16, 1
	v_add_f32_e32 v110, 1.0, v102
	v_rcp_f32_e32 v110, v110
	v_add3_u32 v108, v108, v112, s10
	ds_write_b16_d16_hi v88, v108 offset:1008
	v_and_b32_e32 v127, 0xffff0000, v86
	v_fma_f32 v108, v117, v110, v116
	v_mul_f32_e32 v106, v106, v108
	v_max_f32_e32 v106, 0xda24260, v106
	v_rcp_f32_e32 v108, v106
	ds_write_b16_d16_hi v88, v86 offset:5616
	v_mul_f32_e32 v86, v102, v110
	v_mul_f32_e32 v86, v117, v86
	v_mul_f32_e32 v86, v86, v108
	s_waitcnt vmcnt(0)
	v_lshlrev_b32_e32 v108, 16, v229
	v_max_f32_e32 v108, v108, v108
	v_med3_f32 v108, v108, s9, v244
	v_mul_f32_e32 v108, 0xbfb8aa3b, v108
	v_exp_f32_e32 v108, v108
	v_bfe_u32 v102, v86, 16, 1
	v_add3_u32 v86, v86, v102, s10
	v_lshlrev_b32_e32 v102, 16, v230
	v_add_f32_e32 v110, 1.0, v108
	v_rcp_f32_e32 v110, v110
	v_mul_f32_e32 v102, v106, v102
	v_bfe_u32 v112, v102, 16, 1
	v_add3_u32 v102, v102, v112, s10
	ds_write_b16_d16_hi v88, v102 offset:864
	v_fma_f32 v102, v117, v110, v116
	v_mul_f32_e32 v102, v106, v102
	v_max_f32_e32 v102, 0xda24260, v102
	v_rcp_f32_e32 v106, v102
	v_mul_f32_e32 v108, v108, v110
	v_mul_f32_e32 v108, v117, v108
	s_waitcnt vmcnt(0)
	v_lshlrev_b32_e32 v110, 16, v228
	v_mul_f32_e32 v106, v108, v106
	v_bfe_u32 v108, v106, 16, 1
	v_add3_u32 v106, v106, v108, s10
	s_waitcnt vmcnt(0)
	v_lshlrev_b32_e32 v108, 16, v227
	v_max_f32_e32 v108, v108, v108
	v_med3_f32 v108, v108, s9, v244
	v_mul_f32_e32 v108, 0xbfb8aa3b, v108
	v_exp_f32_e32 v108, v108
	v_mul_f32_e32 v110, v102, v110
	v_bfe_u32 v121, v110, 16, 1
	v_add3_u32 v110, v110, v121, s10
	v_add_f32_e32 v112, 1.0, v108
	v_rcp_f32_e32 v112, v112
	ds_write_b16_d16_hi v88, v110 offset:720
	v_lshl_or_b32 v74, v147, 16, v125
	v_and_b32_e32 v125, 0xffff0000, v106
	v_fma_f32 v110, v117, v112, v116
	v_mul_f32_e32 v102, v102, v110
	v_max_f32_e32 v102, 0xda24260, v102
	v_rcp_f32_e32 v110, v102
	ds_write_b16_d16_hi v88, v106 offset:5328
	v_mul_f32_e32 v106, v108, v112
	v_mul_f32_e32 v106, v117, v106
	v_mul_f32_e32 v106, v106, v110
	s_waitcnt vmcnt(0)
	v_lshlrev_b32_e32 v110, 16, v225
	v_max_f32_e32 v110, v110, v110
	v_med3_f32 v110, v110, s9, v244
	v_mul_f32_e32 v110, 0xbfb8aa3b, v110
	v_exp_f32_e32 v110, v110
	v_bfe_u32 v108, v106, 16, 1
	v_add3_u32 v106, v106, v108, s10
	v_lshlrev_b32_e32 v108, 16, v226
	v_add_f32_e32 v112, 1.0, v110
	v_rcp_f32_e32 v112, v112
	v_mul_f32_e32 v108, v102, v108
	v_bfe_u32 v121, v108, 16, 1
	v_add3_u32 v108, v108, v121, s10
	ds_write_b16_d16_hi v88, v108 offset:576
	v_fma_f32 v108, v117, v112, v116
	v_mul_f32_e32 v102, v102, v108
	v_max_f32_e32 v102, 0xda24260, v102
	v_rcp_f32_e32 v108, v102
	v_mul_f32_e32 v110, v110, v112
	v_mul_f32_e32 v110, v117, v110
	s_waitcnt vmcnt(0)
	v_lshlrev_b32_e32 v112, 16, v224
	v_mul_f32_e32 v108, v110, v108
	v_bfe_u32 v110, v108, 16, 1
	v_add3_u32 v108, v108, v110, s10
	s_waitcnt vmcnt(0)
	v_lshlrev_b32_e32 v110, 16, v223
	v_max_f32_e32 v110, v110, v110
	v_med3_f32 v110, v110, s9, v244
	v_mul_f32_e32 v110, 0xbfb8aa3b, v110
	v_exp_f32_e32 v110, v110
	v_mul_f32_e32 v112, v102, v112
	v_bfe_u32 v122, v112, 16, 1
	v_add3_u32 v112, v112, v122, s10
	v_add_f32_e32 v121, 1.0, v110
	v_rcp_f32_e32 v121, v121
	ds_write_b16_d16_hi v88, v112 offset:432
	v_lshl_or_b32 v69, v135, 16, v129
	v_and_b32_e32 v129, 0xffff0000, v108
	v_fma_f32 v112, v117, v121, v116
	v_mul_f32_e32 v102, v102, v112
	v_max_f32_e32 v102, 0xda24260, v102
	v_rcp_f32_e32 v112, v102
	ds_write_b16_d16_hi v88, v108 offset:5040
	v_mul_f32_e32 v108, v110, v121
	v_mul_f32_e32 v108, v117, v108
	v_mul_f32_e32 v108, v108, v112
	s_waitcnt vmcnt(0)
	v_lshlrev_b32_e32 v112, 16, v221
	v_max_f32_e32 v112, v112, v112
	v_med3_f32 v112, v112, s9, v244
	v_mul_f32_e32 v112, 0xbfb8aa3b, v112
	v_exp_f32_e32 v112, v112
	v_bfe_u32 v110, v108, 16, 1
	v_add3_u32 v108, v108, v110, s10
	v_lshlrev_b32_e32 v110, 16, v222
	v_add_f32_e32 v121, 1.0, v112
	v_rcp_f32_e32 v121, v121
	v_mul_f32_e32 v110, v102, v110
	v_bfe_u32 v122, v110, 16, 1
	v_add3_u32 v110, v110, v122, s10
	ds_write_b16_d16_hi v88, v110 offset:288
	v_fma_f32 v110, v117, v121, v116
	v_mul_f32_e32 v102, v102, v110
	v_max_f32_e32 v102, 0xda24260, v102
	v_rcp_f32_e32 v110, v102
	v_mul_f32_e32 v112, v112, v121
	v_mul_f32_e32 v112, v117, v112
	s_waitcnt vmcnt(0)
	v_lshlrev_b32_e32 v121, 16, v220
	v_mul_f32_e32 v110, v112, v110
	v_bfe_u32 v112, v110, 16, 1
	v_add3_u32 v110, v110, v112, s10
	s_waitcnt vmcnt(0)
	v_lshlrev_b32_e32 v112, 16, v219
	v_max_f32_e32 v112, v112, v112
	v_med3_f32 v112, v112, s9, v244
	v_mul_f32_e32 v112, 0xbfb8aa3b, v112
	v_exp_f32_e32 v112, v112
	v_mul_f32_e32 v121, v102, v121
	v_lshl_or_b32 v70, v137, 16, v123
	v_and_b32_e32 v123, 0xffff0000, v110
	v_add_f32_e32 v122, 1.0, v112
	v_rcp_f32_e32 v122, v122
	ds_write_b16_d16_hi v88, v110 offset:4752
	v_lshl_or_b32 v71, v131, 16, v124
	v_bfe_u32 v124, v121, 16, 1
	v_fmac_f32_e32 v116, v117, v122
	v_mul_f32_e32 v102, v102, v116
	v_max_f32_e32 v116, 0xda24260, v102
	v_rcp_f32_e32 v102, v116
	v_mul_f32_e32 v110, v112, v122
	v_mul_f32_e32 v110, v117, v110
	v_readlane_b32 s9, v255, 34
	v_mul_f32_e32 v102, v110, v102
	v_bfe_u32 v110, v102, 16, 1
	v_add3_u32 v102, v102, v110, s10
	s_waitcnt vmcnt(0)
	v_lshlrev_b32_e32 v110, 16, v218
	v_mul_f32_e32 v110, v116, v110
	v_bfe_u32 v112, v110, 16, 1
	v_add3_u32 v121, v121, v124, s10
	v_add3_u32 v110, v110, v112, s10
	v_readlane_b32 s10, v255, 36
	v_and_b32_e32 v109, 0xffff0000, v64
	v_and_b32_e32 v107, 0xffff0000, v107
	v_and_b32_e32 v105, 0xffff0000, v105
	v_and_b32_e32 v103, 0xffff0000, v99
	v_and_b32_e32 v101, 0xffff0000, v85
	v_and_b32_e32 v99, 0xffff0000, v154
	v_and_b32_e32 v87, 0xffff0000, v153
	v_and_b32_e32 v85, 0xffff0000, v152
	v_and_b32_e32 v83, 0xffff0000, v151
	v_lshl_or_b32 v64, v132, 16, v126
	v_lshl_or_b32 v68, v148, 16, v128
	v_lshl_or_b32 v73, v142, 16, v141
	v_lshl_or_b32 v72, v146, 16, v139
	v_lshl_or_b32 v79, v144, 16, v138
	v_lshl_or_b32 v78, v145, 16, v136
	v_lshl_or_b32 v77, v140, 16, v134
	v_lshl_or_b32 v76, v143, 16, v130
	ds_write_b16_d16_hi v88, v86 offset:5472
	ds_write_b16_d16_hi v88, v106 offset:5184
	ds_write_b16_d16_hi v88, v108 offset:4896
	ds_write_b16_d16_hi v88, v121 offset:144
	ds_write_b16_d16_hi v88, v110
	ds_write_b16_d16_hi v88, v102 offset:4608
	v_and_b32_e32 v122, 0xffff0000, v102
	v_and_b32_e32 v128, 0xffff0000, v108
	v_and_b32_e32 v124, 0xffff0000, v106
	v_and_b32_e32 v126, 0xffff0000, v86
	v_pk_mul_f32 v[122:123], v[116:117], v[122:123] op_sel_hi:[0,1]
	v_pk_mul_f32 v[128:129], v[116:117], v[128:129] op_sel_hi:[0,1]
	v_pk_mul_f32 v[124:125], v[116:117], v[124:125] op_sel_hi:[0,1]
	v_pk_mul_f32 v[126:127], v[116:117], v[126:127] op_sel_hi:[0,1]
	v_and_b32_e32 v112, 0xffff0000, v82
	v_and_b32_e32 v110, 0xffff0000, v100
	v_and_b32_e32 v108, 0xffff0000, v158
	v_and_b32_e32 v106, 0xffff0000, v104
	v_and_b32_e32 v104, 0xffff0000, v98
	v_and_b32_e32 v102, 0xffff0000, v84
	v_and_b32_e32 v100, 0xffff0000, v80
	v_and_b32_e32 v98, 0xffff0000, v150
	v_and_b32_e32 v86, 0xffff0000, v120
	v_and_b32_e32 v84, 0xffff0000, v119
	v_and_b32_e32 v82, 0xffff0000, v118
	v_and_b32_e32 v80, 0xffff0000, v95
	v_mad_u64_u32 v[130:131], s[2:3], v94, s4, v[92:93]
	v_cvt_pk_bf16_f32 v122, v122, v123
	v_cvt_pk_bf16_f32 v123, v128, v129
	v_cvt_pk_bf16_f32 v124, v124, v125
	v_cvt_pk_bf16_f32 v125, v126, v127
	v_pk_mul_f32 v[112:113], v[116:117], v[112:113] op_sel_hi:[0,1]
	v_pk_mul_f32 v[110:111], v[116:117], v[110:111] op_sel_hi:[0,1]
	v_pk_mul_f32 v[108:109], v[116:117], v[108:109] op_sel_hi:[0,1]
	v_pk_mul_f32 v[106:107], v[116:117], v[106:107] op_sel_hi:[0,1]
	v_pk_mul_f32 v[104:105], v[116:117], v[104:105] op_sel_hi:[0,1]
	v_pk_mul_f32 v[102:103], v[116:117], v[102:103] op_sel_hi:[0,1]
	v_pk_mul_f32 v[100:101], v[116:117], v[100:101] op_sel_hi:[0,1]
	v_pk_mul_f32 v[98:99], v[116:117], v[98:99] op_sel_hi:[0,1]
	v_pk_mul_f32 v[86:87], v[116:117], v[86:87] op_sel_hi:[0,1]
	v_pk_mul_f32 v[84:85], v[116:117], v[84:85] op_sel_hi:[0,1]
	v_pk_mul_f32 v[82:83], v[116:117], v[82:83] op_sel_hi:[0,1]
	v_pk_mul_f32 v[80:81], v[116:117], v[80:81] op_sel_hi:[0,1]
	ds_write_b128 v130, v[122:125] offset:9216
	v_cvt_pk_bf16_f32 v122, v112, v113
	v_cvt_pk_bf16_f32 v123, v110, v111
	v_cvt_pk_bf16_f32 v124, v108, v109
	v_cvt_pk_bf16_f32 v125, v106, v107
	v_cvt_pk_bf16_f32 v104, v104, v105
	v_cvt_pk_bf16_f32 v105, v102, v103
	v_cvt_pk_bf16_f32 v106, v100, v101
	v_cvt_pk_bf16_f32 v107, v98, v99
	v_cvt_pk_bf16_f32 v98, v86, v87
	v_cvt_pk_bf16_f32 v99, v84, v85
	v_cvt_pk_bf16_f32 v100, v82, v83
	v_cvt_pk_bf16_f32 v101, v80, v81
	v_lshl_add_u32 v80, v94, 2, v92
	ds_write_b128 v130, v[122:125] offset:9232
	ds_write_b128 v130, v[104:107] offset:9248
	ds_write_b128 v130, v[98:101] offset:9264
	ds_write_b32 v80, v116 offset:19456
	ds_write_b128 v130, v[76:79] offset:14336
	ds_write_b128 v130, v[72:75] offset:14352
	ds_write_b128 v130, v[68:71] offset:14368
	ds_write_b128 v130, v[64:67] offset:14384
	s_waitcnt lgkmcnt(0)
	v_or_b32_e32 v88, v93, v114
	v_lshlrev_b64 v[64:65], 11, v[88:89]
	v_lshlrev_b32_e32 v98, 2, v115
	v_lshl_add_u64 v[64:65], s[12:13], 0, v[64:65]
	v_ashrrev_i32_e32 v99, 31, v98
	v_lshl_add_u64 v[64:65], v[64:65], 0, v[90:91]
	v_lshlrev_b64 v[100:101], 1, v[98:99]
	v_lshl_add_u64 v[102:103], v[64:65], 0, v[100:101]
	s_mov_b64 s[2:3], 0x16f00600
	v_lshl_add_u64 v[94:95], v[102:103], 0, s[2:3]
	s_movk_i32 s2, 0x90
	v_mad_u32_u24 v89, v114, s2, v92
	v_lshl_add_u32 v93, v115, 4, v89
	ds_read_b128 v[64:67], v93 offset:4608
	ds_read_b128 v[68:71], v93
	ds_read_b128 v[80:83], v93 offset:32
	ds_read_b128 v[84:87], v93 offset:4640
	s_waitcnt lgkmcnt(2)
	v_mfma_f32_32x32x16_bf16 v[64:79], v[64:67], v[68:71], 0
	v_cmp_ge_i32_e32 vcc, v98, v114
	v_cvt_pk_bf16_f32 v32, v32, v33
	v_cvt_pk_bf16_f32 v33, v34, v35
	v_cvt_pk_bf16_f32 v34, v36, v37
	v_cvt_pk_bf16_f32 v35, v38, v39
	v_cvt_pk_bf16_f32 v36, v48, v49
	v_cvt_pk_bf16_f32 v37, v50, v51
	s_waitcnt lgkmcnt(0)
	v_mfma_f32_32x32x16_bf16 v[64:79], v[84:87], v[80:83], v[64:79]
	ds_read_b128 v[80:83], v93 offset:4672
	ds_read_b128 v[84:87], v93 offset:64
	v_cvt_pk_bf16_f32 v38, v52, v53
	v_cvt_pk_bf16_f32 v39, v54, v55
	s_mov_b32 s2, 0x16f00000
	s_waitcnt lgkmcnt(0)
	v_mfma_f32_32x32x16_bf16 v[64:79], v[80:83], v[84:87], v[64:79]
	ds_read_b128 v[80:83], v93 offset:4704
	ds_read_b128 v[84:87], v93 offset:96
	s_waitcnt lgkmcnt(0)
	v_mfma_f32_32x32x16_bf16 v[64:79], v[80:83], v[84:87], v[64:79]
	v_or_b32_e32 v80, 1, v98
	s_nop 10
	v_cndmask_b32_e32 v64, 0, v64, vcc
	v_cmp_ge_i32_e32 vcc, v80, v114
	v_or_b32_e32 v80, 2, v98
	s_nop 0
	v_cndmask_b32_e32 v65, 0, v65, vcc
	v_cmp_ge_i32_e32 vcc, v80, v114
	v_or_b32_e32 v80, 3, v98
	s_nop 0
	v_cndmask_b32_e32 v66, 0, v66, vcc
	v_cmp_ge_i32_e32 vcc, v80, v114
	v_add_u32_e32 v80, 8, v98
	s_nop 0
	v_cndmask_b32_e32 v67, 0, v67, vcc
	v_cmp_ge_i32_e32 vcc, v80, v114
	v_add_u32_e32 v80, 9, v98
	v_cvt_pk_bf16_f32 v81, v66, v67
	v_cndmask_b32_e32 v68, 0, v68, vcc
	v_cmp_ge_i32_e32 vcc, v80, v114
	v_add_u32_e32 v80, 10, v98
	s_nop 0
	v_cndmask_b32_e32 v69, 0, v69, vcc
	v_cmp_ge_i32_e32 vcc, v80, v114
	v_add_u32_e32 v80, 11, v98
	v_cvt_pk_bf16_f32 v82, v68, v69
	v_cndmask_b32_e32 v70, 0, v70, vcc
	v_cmp_ge_i32_e32 vcc, v80, v114
	v_add_u32_e32 v80, 16, v98
	s_nop 0
	v_cndmask_b32_e32 v71, 0, v71, vcc
	v_cmp_ge_i32_e32 vcc, v80, v114
	v_add_u32_e32 v80, 17, v98
	v_cvt_pk_bf16_f32 v83, v70, v71
	v_cndmask_b32_e32 v72, 0, v72, vcc
	v_cmp_ge_i32_e32 vcc, v80, v114
	v_add_u32_e32 v80, 18, v98
	s_nop 0
	v_cndmask_b32_e32 v73, 0, v73, vcc
	v_cmp_ge_i32_e32 vcc, v80, v114
	v_add_u32_e32 v80, 19, v98
	v_cvt_pk_bf16_f32 v84, v72, v73
	v_cndmask_b32_e32 v74, 0, v74, vcc
	v_cmp_ge_i32_e32 vcc, v80, v114
	v_add_u32_e32 v80, 24, v98
	s_nop 0
	v_cndmask_b32_e32 v75, 0, v75, vcc
	v_cmp_ge_i32_e32 vcc, v80, v114
	v_add_u32_e32 v80, 25, v98
	v_cvt_pk_bf16_f32 v85, v74, v75
	v_cndmask_b32_e32 v76, 0, v76, vcc
	v_cmp_ge_i32_e32 vcc, v80, v114
	v_add_u32_e32 v80, 26, v98
	s_nop 0
	v_cndmask_b32_e32 v77, 0, v77, vcc
	v_cmp_ge_i32_e32 vcc, v80, v114
	v_add_u32_e32 v80, 27, v98
	v_cvt_pk_bf16_f32 v86, v76, v77
	v_cndmask_b32_e32 v78, 0, v78, vcc
	v_cmp_ge_i32_e32 vcc, v80, v114
	v_cvt_pk_bf16_f32 v80, v64, v65
	v_lshlrev_b32_e32 v64, 3, v115
	v_mul_u32_u24_e32 v65, 0x50, v114
	v_add3_u32 v92, v92, v64, v65
	v_add_u32_e32 v68, 0x3800, v92
	v_add_u32_e32 v89, v89, v64
	ds_read2_b64 v[64:67], v68 offset1:2
	ds_read2_b64 v[104:107], v68 offset0:4 offset1:6
	v_cndmask_b32_e32 v79, 0, v79, vcc
	v_cvt_pk_bf16_f32 v87, v78, v79
	s_waitcnt lgkmcnt(1)
	v_mfma_f32_32x32x16_bf16 v[64:79], v[64:67], v[80:83], 0
	v_add_co_u32_e32 v48, vcc, s2, v102
	s_nop 1
	v_addc_co_u32_e32 v49, vcc, 0, v103, vcc
	s_waitcnt lgkmcnt(0)
	v_mfma_f32_32x32x16_bf16 v[64:79], v[104:107], v[84:87], v[64:79]
	ds_read2_b64 v[104:107], v89 offset1:2
	ds_read2_b64 v[108:111], v89 offset0:4 offset1:6
	s_waitcnt lgkmcnt(1)
	v_mfma_f32_32x32x16_bf16 v[64:79], v[32:35], v[104:107], v[64:79]
	v_cvt_pk_bf16_f32 v32, v40, v41
	v_cvt_pk_bf16_f32 v33, v42, v43
	v_cvt_pk_bf16_f32 v34, v44, v45
	v_cvt_pk_bf16_f32 v35, v46, v47
	s_waitcnt lgkmcnt(0)
	s_nop 0
	v_mfma_f32_32x32x16_bf16 v[64:79], v[32:35], v[108:111], v[64:79]
	ds_read2_b64 v[32:35], v89 offset0:8 offset1:10
	s_waitcnt lgkmcnt(0)
	v_mfma_f32_32x32x16_bf16 v[64:79], v[36:39], v[32:35], v[64:79]
	ds_read2_b64 v[32:35], v89 offset0:12 offset1:14
	v_cvt_pk_bf16_f32 v36, v56, v57
	v_cvt_pk_bf16_f32 v37, v58, v59
	v_cvt_pk_bf16_f32 v38, v60, v61
	v_cvt_pk_bf16_f32 v39, v62, v63
	s_waitcnt lgkmcnt(0)
	s_nop 0
	v_mfma_f32_32x32x16_bf16 v[64:79], v[36:39], v[32:35], v[64:79]
	global_load_dwordx2 v[32:33], v[48:49], off offset:1536
	s_waitcnt vmcnt(0)
	v_lshlrev_b32_e32 v34, 16, v32
	v_and_b32_e32 v35, 0xffff0000, v32
	v_lshlrev_b32_e32 v32, 16, v33
	v_and_b32_e32 v33, 0xffff0000, v33
	s_nop 5
	v_pk_add_f32 v[34:35], v[64:65], v[34:35]
	v_pk_add_f32 v[32:33], v[66:67], v[32:33]
	v_mul_f32_e32 v36, v35, v35
	v_mul_f32_e32 v38, v33, v33
	v_pk_fma_f32 v[36:37], v[34:35], v[34:35], v[36:37] op_sel_hi:[1,1,0]
	v_pk_fma_f32 v[38:39], v[32:33], v[32:33], v[38:39] op_sel_hi:[1,1,0]
	v_cvt_pk_bf16_f32 v34, v34, v35
	v_cvt_pk_bf16_f32 v35, v32, v33
	global_load_dwordx2 v[32:33], v[94:95], off offset:16
	v_pk_add_f32 v[36:37], v[36:37], v[38:39]
	global_store_dwordx2 v[48:49], v[34:35], off offset:1536
	s_waitcnt vmcnt(1)
	v_lshlrev_b32_e32 v34, 16, v32
	v_and_b32_e32 v35, 0xffff0000, v32
	v_lshlrev_b32_e32 v32, 16, v33
	v_and_b32_e32 v33, 0xffff0000, v33
	v_pk_add_f32 v[34:35], v[68:69], v[34:35]
	v_pk_add_f32 v[32:33], v[70:71], v[32:33]
	v_mul_f32_e32 v38, v35, v35
	v_mul_f32_e32 v40, v33, v33
	v_pk_fma_f32 v[38:39], v[34:35], v[34:35], v[38:39] op_sel_hi:[1,1,0]
	v_pk_fma_f32 v[40:41], v[32:33], v[32:33], v[40:41] op_sel_hi:[1,1,0]
	v_cvt_pk_bf16_f32 v34, v34, v35
	v_cvt_pk_bf16_f32 v35, v32, v33
	global_load_dwordx2 v[32:33], v[94:95], off offset:32
	v_pk_add_f32 v[38:39], v[38:39], v[40:41]
	global_store_dwordx2 v[94:95], v[34:35], off offset:16
	v_pk_add_f32 v[36:37], v[36:37], v[38:39]
	s_waitcnt vmcnt(1)
	v_lshlrev_b32_e32 v34, 16, v32
	v_and_b32_e32 v35, 0xffff0000, v32
	v_pk_add_f32 v[34:35], v[72:73], v[34:35]
	v_lshlrev_b32_e32 v32, 16, v33
	v_and_b32_e32 v33, 0xffff0000, v33
	v_pk_add_f32 v[38:39], v[74:75], v[32:33]
	v_mul_f32_e32 v32, v35, v35
	v_pk_fma_f32 v[32:33], v[34:35], v[34:35], v[32:33] op_sel_hi:[1,1,0]
	v_cvt_pk_bf16_f32 v34, v34, v35
	v_cvt_pk_bf16_f32 v35, v38, v39
	global_store_dwordx2 v[94:95], v[34:35], off offset:32
	global_load_dwordx2 v[34:35], v[94:95], off offset:48
	v_mul_f32_e32 v40, v39, v39
	v_pk_fma_f32 v[40:41], v[38:39], v[38:39], v[40:41] op_sel_hi:[1,1,0]
	s_nop 0
	v_pk_add_f32 v[32:33], v[32:33], v[40:41]
	s_nop 0
	v_pk_add_f32 v[32:33], v[36:37], v[32:33]
	s_waitcnt vmcnt(0)
	v_lshlrev_b32_e32 v36, 16, v34
	v_and_b32_e32 v37, 0xffff0000, v34
	v_lshlrev_b32_e32 v34, 16, v35
	v_and_b32_e32 v35, 0xffff0000, v35
	v_pk_add_f32 v[36:37], v[76:77], v[36:37]
	v_pk_add_f32 v[34:35], v[78:79], v[34:35]
	v_mul_f32_e32 v38, v37, v37
	v_mul_f32_e32 v40, v35, v35
	v_pk_fma_f32 v[38:39], v[36:37], v[36:37], v[38:39] op_sel_hi:[1,1,0]
	v_pk_fma_f32 v[40:41], v[34:35], v[34:35], v[40:41] op_sel_hi:[1,1,0]
	s_nop 0
	v_pk_add_f32 v[38:39], v[38:39], v[40:41]
	s_nop 0
	v_pk_add_f32 v[58:59], v[32:33], v[38:39]
	v_cvt_pk_bf16_f32 v32, v36, v37
	v_cvt_pk_bf16_f32 v33, v34, v35
	global_store_dwordx2 v[94:95], v[32:33], off offset:48
	v_add_u32_e32 v36, 0x4000, v92
	ds_read2_b64 v[32:35], v36 offset0:64 offset1:66
	ds_read2_b64 v[50:53], v36 offset0:68 offset1:70
	v_cvt_pk_bf16_f32 v0, v0, v1
	v_cvt_pk_bf16_f32 v1, v2, v3
	v_cvt_pk_bf16_f32 v2, v4, v5
	s_waitcnt lgkmcnt(1)
	v_mfma_f32_32x32x16_bf16 v[32:47], v[32:35], v[80:83], 0
	v_cvt_pk_bf16_f32 v3, v6, v7
	v_cvt_pk_bf16_f32 v4, v16, v17
	v_cvt_pk_bf16_f32 v5, v18, v19
	v_cvt_pk_bf16_f32 v6, v20, v21
	v_cvt_pk_bf16_f32 v7, v22, v23
	s_waitcnt lgkmcnt(0)
	v_mfma_f32_32x32x16_bf16 v[32:47], v[50:53], v[84:87], v[32:47]
	ds_read2_b64 v[50:53], v89 offset1:2
	ds_read2_b64 v[54:57], v89 offset0:4 offset1:6
	s_waitcnt lgkmcnt(1)
	v_mfma_f32_32x32x16_bf16 v[32:47], v[0:3], v[50:53], v[32:47]
	v_cvt_pk_bf16_f32 v0, v8, v9
	v_cvt_pk_bf16_f32 v1, v10, v11
	v_cvt_pk_bf16_f32 v2, v12, v13
	v_cvt_pk_bf16_f32 v3, v14, v15
	s_waitcnt lgkmcnt(0)
	s_nop 0
	v_mfma_f32_32x32x16_bf16 v[32:47], v[0:3], v[54:57], v[32:47]
	ds_read2_b64 v[0:3], v89 offset0:8 offset1:10
	s_waitcnt lgkmcnt(0)
	v_mfma_f32_32x32x16_bf16 v[32:47], v[4:7], v[0:3], v[32:47]
	ds_read2_b64 v[0:3], v89 offset0:12 offset1:14
	v_cvt_pk_bf16_f32 v4, v24, v25
	v_cvt_pk_bf16_f32 v5, v26, v27
	v_cvt_pk_bf16_f32 v6, v28, v29
	v_cvt_pk_bf16_f32 v7, v30, v31
	s_waitcnt lgkmcnt(0)
	s_nop 0
	v_mfma_f32_32x32x16_bf16 v[32:47], v[4:7], v[0:3], v[32:47]
	global_load_dwordx2 v[0:1], v[94:95], off offset:64
	s_waitcnt vmcnt(0)
	v_lshlrev_b32_e32 v2, 16, v0
	v_and_b32_e32 v3, 0xffff0000, v0
	v_lshlrev_b32_e32 v0, 16, v1
	v_and_b32_e32 v1, 0xffff0000, v1
	s_nop 5
	v_pk_add_f32 v[2:3], v[32:33], v[2:3]
	v_pk_add_f32 v[0:1], v[34:35], v[0:1]
	v_mul_f32_e32 v4, v3, v3
	v_mul_f32_e32 v6, v1, v1
	v_pk_fma_f32 v[4:5], v[2:3], v[2:3], v[4:5] op_sel_hi:[1,1,0]
	v_pk_fma_f32 v[6:7], v[0:1], v[0:1], v[6:7] op_sel_hi:[1,1,0]
	v_cvt_pk_bf16_f32 v2, v2, v3
	v_cvt_pk_bf16_f32 v3, v0, v1
	global_load_dwordx2 v[0:1], v[94:95], off offset:80
	v_pk_add_f32 v[4:5], v[4:5], v[6:7]
	global_store_dwordx2 v[94:95], v[2:3], off offset:64
	v_pk_add_f32 v[4:5], v[58:59], v[4:5]
	s_waitcnt vmcnt(1)
	v_lshlrev_b32_e32 v2, 16, v0
	v_and_b32_e32 v3, 0xffff0000, v0
	v_lshlrev_b32_e32 v0, 16, v1
	v_and_b32_e32 v1, 0xffff0000, v1
	v_pk_add_f32 v[2:3], v[36:37], v[2:3]
	v_pk_add_f32 v[0:1], v[38:39], v[0:1]
	v_mul_f32_e32 v6, v3, v3
	v_mul_f32_e32 v8, v1, v1
	v_pk_fma_f32 v[6:7], v[2:3], v[2:3], v[6:7] op_sel_hi:[1,1,0]
	v_pk_fma_f32 v[8:9], v[0:1], v[0:1], v[8:9] op_sel_hi:[1,1,0]
	v_cvt_pk_bf16_f32 v2, v2, v3
	v_cvt_pk_bf16_f32 v3, v0, v1
	global_load_dwordx2 v[0:1], v[94:95], off offset:96
	v_pk_add_f32 v[6:7], v[6:7], v[8:9]
	global_store_dwordx2 v[94:95], v[2:3], off offset:80
	v_pk_add_f32 v[4:5], v[4:5], v[6:7]
	s_waitcnt vmcnt(1)
	v_lshlrev_b32_e32 v2, 16, v0
	v_and_b32_e32 v3, 0xffff0000, v0
	v_lshlrev_b32_e32 v0, 16, v1
	v_and_b32_e32 v1, 0xffff0000, v1
	v_pk_add_f32 v[2:3], v[40:41], v[2:3]
	v_pk_add_f32 v[6:7], v[42:43], v[0:1]
	v_mov_b32_e32 v0, v2
	v_mov_b32_e32 v8, v3
	v_cvt_pk_bf16_f32 v2, v2, v3
	v_cvt_pk_bf16_f32 v3, v6, v7
	global_store_dwordx2 v[94:95], v[2:3], off offset:96
	global_load_dwordx2 v[2:3], v[94:95], off offset:112
	v_mov_b32_e32 v9, v7
	v_mov_b32_e32 v1, v6
	v_pk_mul_f32 v[8:9], v[8:9], v[8:9]
	s_nop 0
	v_pk_fma_f32 v[0:1], v[0:1], v[0:1], v[8:9]
	s_nop 0
	v_pk_add_f32 v[0:1], v[0:1], v[0:1] op_sel:[0,1] op_sel_hi:[1,0]
	s_nop 0
	v_pk_add_f32 v[0:1], v[4:5], v[0:1]
	s_waitcnt vmcnt(0)
	v_lshlrev_b32_e32 v4, 16, v2
	v_and_b32_e32 v5, 0xffff0000, v2
	v_lshlrev_b32_e32 v2, 16, v3
	v_and_b32_e32 v3, 0xffff0000, v3
	v_pk_add_f32 v[4:5], v[44:45], v[4:5]
	v_pk_add_f32 v[2:3], v[46:47], v[2:3]
	v_mov_b32_e32 v8, v5
	v_mov_b32_e32 v9, v3
	v_mov_b32_e32 v6, v4
	v_mov_b32_e32 v7, v2
	v_pk_mul_f32 v[8:9], v[8:9], v[8:9]
	v_cvt_pk_bf16_f32 v4, v4, v5
	v_pk_fma_f32 v[6:7], v[6:7], v[6:7], v[8:9]
	v_cvt_pk_bf16_f32 v5, v2, v3
	v_pk_add_f32 v[6:7], v[6:7], v[6:7] op_sel:[0,1] op_sel_hi:[1,0]
	global_store_dwordx2 v[94:95], v[4:5], off offset:112
	v_pk_add_f32 v[0:1], v[0:1], v[6:7]
	s_waitcnt lgkmcnt(0)
	s_nop 0
	v_mov_b32_e32 v1, v0
	s_nop 1
	v_permlane32_swap_b32_e32 v0, v1
	v_add_f32_e32 v0, v0, v1
	v_fmamk_f32 v0, v0, 0x3c800000, v237
	v_rsq_f32_e32 v4, v0
	v_mad_i64_i32 v[0:1], s[2:3], v88, s6, v[96:97]
	v_lshl_add_u64 v[0:1], v[0:1], 0, v[90:91]
	v_lshl_add_u64 v[0:1], v[0:1], 0, v[100:101]
	v_lshl_add_u64 v[8:9], v[0:1], 0, s[48:49]
	v_add_co_u32_e32 v0, vcc, s5, v0
	global_load_dwordx2 v[10:11], v[48:49], off offset:1536
	s_nop 0
	v_addc_co_u32_e32 v1, vcc, 0, v1, vcc
	global_load_dwordx2 v[12:13], v[0:1], off
	s_add_u32 s2, s12, s0
	s_addc_u32 s3, s13, s1
	v_lshl_add_u64 v[0:1], v[98:99], 2, s[2:3]
	v_lshl_add_u64 v[6:7], v[0:1], 0, s[30:31]
	v_add_co_u32_e32 v0, vcc, s7, v0
	v_readlane_b32 s48, v254, 11
	s_nop 0
	v_addc_co_u32_e32 v1, vcc, 0, v1, vcc
	global_load_dwordx4 v[0:3], v[0:1], off offset:2048
	v_readlane_b32 s49, v254, 12
	s_waitcnt vmcnt(2)
	v_lshlrev_b32_e32 v18, 16, v10
	v_and_b32_e32 v19, 0xffff0000, v10
	v_lshlrev_b32_e32 v10, 16, v11
	s_waitcnt vmcnt(1)
	v_lshlrev_b32_e32 v14, 16, v12
	v_mul_f32_e32 v5, 0xbfb8aa3b, v14
	v_exp_f32_e32 v5, v5
	v_and_b32_e32 v15, 0xffff0000, v12
	v_lshlrev_b32_e32 v12, 16, v13
	v_and_b32_e32 v13, 0xffff0000, v13
	v_add_f32_e32 v5, 1.0, v5
	v_rcp_f32_e32 v16, v5
	v_mul_f32_e32 v5, 0xbfb8aa3b, v15
	v_exp_f32_e32 v5, v5
	v_and_b32_e32 v11, 0xffff0000, v11
	v_add_f32_e32 v5, 1.0, v5
	v_rcp_f32_e32 v17, v5
	v_pk_mul_f32 v[18:19], v[4:5], v[18:19] op_sel_hi:[0,1]
	s_waitcnt vmcnt(0)
	v_pk_mul_f32 v[0:1], v[0:1], v[18:19]
	v_pk_mul_f32 v[10:11], v[4:5], v[10:11] op_sel_hi:[0,1]
	v_pk_mul_f32 v[14:15], v[16:17], v[14:15]
	v_pk_mul_f32 v[2:3], v[2:3], v[10:11]
	v_pk_mul_f32 v[0:1], v[0:1], v[14:15]
	s_nop 0
	v_cvt_pk_bf16_f32 v0, v0, v1
	v_mul_f32_e32 v1, 0xbfb8aa3b, v12
	v_exp_f32_e32 v1, v1
	s_nop 0
	v_add_f32_e32 v1, 1.0, v1
	v_rcp_f32_e32 v14, v1
	v_mul_f32_e32 v1, 0xbfb8aa3b, v13
	v_exp_f32_e32 v1, v1
	s_nop 0
	v_add_f32_e32 v1, 1.0, v1
	v_rcp_f32_e32 v15, v1
	s_nop 0
	v_pk_mul_f32 v[10:11], v[14:15], v[12:13]
	s_nop 0
	v_pk_mul_f32 v[2:3], v[2:3], v[10:11]
	s_nop 0
	v_cvt_pk_bf16_f32 v1, v2, v3
	global_store_dwordx2 v[48:49], v[0:1], off offset:1536
	global_load_dwordx4 v[0:3], v[6:7], off offset:32
	s_nop 0
	global_load_dwordx2 v[10:11], v[8:9], off offset:16
	global_load_dwordx2 v[12:13], v[94:95], off offset:16
	s_waitcnt vmcnt(1)
	v_lshlrev_b32_e32 v14, 16, v10
	v_mul_f32_e32 v5, 0xbfb8aa3b, v14
	v_exp_f32_e32 v5, v5
	v_and_b32_e32 v15, 0xffff0000, v10
	s_waitcnt vmcnt(0)
	v_lshlrev_b32_e32 v18, 16, v12
	v_and_b32_e32 v19, 0xffff0000, v12
	v_add_f32_e32 v5, 1.0, v5
	v_rcp_f32_e32 v16, v5
	v_mul_f32_e32 v5, 0xbfb8aa3b, v15
	v_exp_f32_e32 v5, v5
	v_lshlrev_b32_e32 v10, 16, v11
	v_and_b32_e32 v11, 0xffff0000, v11
	v_lshlrev_b32_e32 v12, 16, v13
	v_add_f32_e32 v5, 1.0, v5
	v_rcp_f32_e32 v17, v5
	v_pk_mul_f32 v[18:19], v[4:5], v[18:19] op_sel_hi:[0,1]
	v_pk_mul_f32 v[0:1], v[0:1], v[18:19]
	v_and_b32_e32 v13, 0xffff0000, v13
	v_pk_mul_f32 v[14:15], v[16:17], v[14:15]
	v_pk_mul_f32 v[12:13], v[4:5], v[12:13] op_sel_hi:[0,1]
	v_pk_mul_f32 v[0:1], v[0:1], v[14:15]
	v_pk_mul_f32 v[2:3], v[2:3], v[12:13]
	v_cvt_pk_bf16_f32 v0, v0, v1
	v_mul_f32_e32 v1, 0xbfb8aa3b, v10
	v_exp_f32_e32 v1, v1
	s_nop 0
	v_add_f32_e32 v1, 1.0, v1
	v_rcp_f32_e32 v14, v1
	v_mul_f32_e32 v1, 0xbfb8aa3b, v11
	v_exp_f32_e32 v1, v1
	s_nop 0
	v_add_f32_e32 v1, 1.0, v1
	v_rcp_f32_e32 v15, v1
	s_nop 0
	v_pk_mul_f32 v[10:11], v[14:15], v[10:11]
	s_nop 0
	v_pk_mul_f32 v[2:3], v[2:3], v[10:11]
	s_nop 0
	v_cvt_pk_bf16_f32 v1, v2, v3
	global_store_dwordx2 v[94:95], v[0:1], off offset:16
	global_load_dwordx4 v[0:3], v[6:7], off offset:64
	s_nop 0
	global_load_dwordx2 v[10:11], v[8:9], off offset:32
	global_load_dwordx2 v[12:13], v[94:95], off offset:32
	s_waitcnt vmcnt(1)
	v_lshlrev_b32_e32 v14, 16, v10
	v_mul_f32_e32 v5, 0xbfb8aa3b, v14
	v_exp_f32_e32 v5, v5
	v_and_b32_e32 v15, 0xffff0000, v10
	s_waitcnt vmcnt(0)
	v_lshlrev_b32_e32 v18, 16, v12
	v_and_b32_e32 v19, 0xffff0000, v12
	v_add_f32_e32 v5, 1.0, v5
	v_rcp_f32_e32 v16, v5
	v_mul_f32_e32 v5, 0xbfb8aa3b, v15
	v_exp_f32_e32 v5, v5
	v_lshlrev_b32_e32 v10, 16, v11
	v_and_b32_e32 v11, 0xffff0000, v11
	v_lshlrev_b32_e32 v12, 16, v13
	v_add_f32_e32 v5, 1.0, v5
	v_rcp_f32_e32 v17, v5
	v_pk_mul_f32 v[18:19], v[4:5], v[18:19] op_sel_hi:[0,1]
	v_pk_mul_f32 v[0:1], v[0:1], v[18:19]
	v_and_b32_e32 v13, 0xffff0000, v13
	v_pk_mul_f32 v[14:15], v[16:17], v[14:15]
	v_pk_mul_f32 v[12:13], v[4:5], v[12:13] op_sel_hi:[0,1]
	v_pk_mul_f32 v[0:1], v[0:1], v[14:15]
	v_pk_mul_f32 v[2:3], v[2:3], v[12:13]
	v_cvt_pk_bf16_f32 v0, v0, v1
	v_mul_f32_e32 v1, 0xbfb8aa3b, v10
	v_exp_f32_e32 v1, v1
	s_nop 0
	v_add_f32_e32 v1, 1.0, v1
	v_rcp_f32_e32 v14, v1
	v_mul_f32_e32 v1, 0xbfb8aa3b, v11
	v_exp_f32_e32 v1, v1
	s_nop 0
	v_add_f32_e32 v1, 1.0, v1
	v_rcp_f32_e32 v15, v1
	s_nop 0
	v_pk_mul_f32 v[10:11], v[14:15], v[10:11]
	s_nop 0
	v_pk_mul_f32 v[2:3], v[2:3], v[10:11]
	s_nop 0
	v_cvt_pk_bf16_f32 v1, v2, v3
	global_store_dwordx2 v[94:95], v[0:1], off offset:32
	global_load_dwordx4 v[0:3], v[6:7], off offset:96
	s_nop 0
	global_load_dwordx2 v[10:11], v[8:9], off offset:48
	global_load_dwordx2 v[12:13], v[94:95], off offset:48
	s_waitcnt vmcnt(1)
	v_lshlrev_b32_e32 v14, 16, v10
	v_mul_f32_e32 v5, 0xbfb8aa3b, v14
	v_exp_f32_e32 v5, v5
	v_and_b32_e32 v15, 0xffff0000, v10
	s_waitcnt vmcnt(0)
	v_lshlrev_b32_e32 v18, 16, v12
	v_and_b32_e32 v19, 0xffff0000, v12
	v_add_f32_e32 v5, 1.0, v5
	v_rcp_f32_e32 v16, v5
	v_mul_f32_e32 v5, 0xbfb8aa3b, v15
	v_exp_f32_e32 v5, v5
	v_lshlrev_b32_e32 v10, 16, v11
	v_and_b32_e32 v11, 0xffff0000, v11
	v_lshlrev_b32_e32 v12, 16, v13
	v_add_f32_e32 v5, 1.0, v5
	v_rcp_f32_e32 v17, v5
	v_pk_mul_f32 v[18:19], v[4:5], v[18:19] op_sel_hi:[0,1]
	v_pk_mul_f32 v[0:1], v[0:1], v[18:19]
	v_and_b32_e32 v13, 0xffff0000, v13
	v_pk_mul_f32 v[14:15], v[16:17], v[14:15]
	v_pk_mul_f32 v[12:13], v[4:5], v[12:13] op_sel_hi:[0,1]
	v_pk_mul_f32 v[0:1], v[0:1], v[14:15]
	v_pk_mul_f32 v[2:3], v[2:3], v[12:13]
	v_cvt_pk_bf16_f32 v0, v0, v1
	v_mul_f32_e32 v1, 0xbfb8aa3b, v10
	v_exp_f32_e32 v1, v1
	s_nop 0
	v_add_f32_e32 v1, 1.0, v1
	v_rcp_f32_e32 v14, v1
	v_mul_f32_e32 v1, 0xbfb8aa3b, v11
	v_exp_f32_e32 v1, v1
	s_nop 0
	v_add_f32_e32 v1, 1.0, v1
	v_rcp_f32_e32 v15, v1
	s_nop 0
	v_pk_mul_f32 v[10:11], v[14:15], v[10:11]
	s_nop 0
	v_pk_mul_f32 v[2:3], v[2:3], v[10:11]
	s_nop 0
	v_cvt_pk_bf16_f32 v1, v2, v3
	global_store_dwordx2 v[94:95], v[0:1], off offset:48
	global_load_dwordx2 v[10:11], v[94:95], off offset:64
	global_load_dwordx2 v[12:13], v[8:9], off offset:64
	global_load_dwordx4 v[0:3], v[6:7], off offset:128
	s_waitcnt vmcnt(2)
	v_lshlrev_b32_e32 v18, 16, v10
	s_waitcnt vmcnt(1)
	v_lshlrev_b32_e32 v14, 16, v12
	v_mul_f32_e32 v5, 0xbfb8aa3b, v14
	v_exp_f32_e32 v5, v5
	v_and_b32_e32 v15, 0xffff0000, v12
	v_and_b32_e32 v19, 0xffff0000, v10
	v_lshlrev_b32_e32 v12, 16, v13
	v_add_f32_e32 v5, 1.0, v5
	v_rcp_f32_e32 v16, v5
	v_mul_f32_e32 v5, 0xbfb8aa3b, v15
	v_exp_f32_e32 v5, v5
	v_and_b32_e32 v13, 0xffff0000, v13
	v_lshlrev_b32_e32 v10, 16, v11
	v_and_b32_e32 v11, 0xffff0000, v11
	v_add_f32_e32 v5, 1.0, v5
	v_rcp_f32_e32 v17, v5
	v_pk_mul_f32 v[18:19], v[4:5], v[18:19] op_sel_hi:[0,1]
	s_waitcnt vmcnt(0)
	v_pk_mul_f32 v[0:1], v[0:1], v[18:19]
	v_pk_mul_f32 v[10:11], v[4:5], v[10:11] op_sel_hi:[0,1]
	v_pk_mul_f32 v[14:15], v[16:17], v[14:15]
	v_pk_mul_f32 v[2:3], v[2:3], v[10:11]
	v_pk_mul_f32 v[0:1], v[0:1], v[14:15]
	s_nop 0
	v_cvt_pk_bf16_f32 v0, v0, v1
	v_mul_f32_e32 v1, 0xbfb8aa3b, v12
	v_exp_f32_e32 v1, v1
	s_nop 0
	v_add_f32_e32 v1, 1.0, v1
	v_rcp_f32_e32 v14, v1
	v_mul_f32_e32 v1, 0xbfb8aa3b, v13
	v_exp_f32_e32 v1, v1
	s_nop 0
	v_add_f32_e32 v1, 1.0, v1
	v_rcp_f32_e32 v15, v1
	s_nop 0
	v_pk_mul_f32 v[10:11], v[14:15], v[12:13]
	s_nop 0
	v_pk_mul_f32 v[2:3], v[2:3], v[10:11]
	s_nop 0
	v_cvt_pk_bf16_f32 v1, v2, v3
	global_store_dwordx2 v[94:95], v[0:1], off offset:64
	global_load_dwordx2 v[10:11], v[94:95], off offset:80
	global_load_dwordx2 v[12:13], v[8:9], off offset:80
	s_nop 0
	global_load_dwordx4 v[0:3], v[6:7], off offset:160
	s_waitcnt vmcnt(2)
	v_lshlrev_b32_e32 v18, 16, v10
	s_waitcnt vmcnt(1)
	v_lshlrev_b32_e32 v14, 16, v12
	v_mul_f32_e32 v5, 0xbfb8aa3b, v14
	v_exp_f32_e32 v5, v5
	v_and_b32_e32 v15, 0xffff0000, v12
	v_and_b32_e32 v19, 0xffff0000, v10
	v_lshlrev_b32_e32 v12, 16, v13
	v_add_f32_e32 v5, 1.0, v5
	v_rcp_f32_e32 v16, v5
	v_mul_f32_e32 v5, 0xbfb8aa3b, v15
	v_exp_f32_e32 v5, v5
	v_and_b32_e32 v13, 0xffff0000, v13
	v_lshlrev_b32_e32 v10, 16, v11
	v_and_b32_e32 v11, 0xffff0000, v11
	v_add_f32_e32 v5, 1.0, v5
	v_rcp_f32_e32 v17, v5
	v_pk_mul_f32 v[18:19], v[4:5], v[18:19] op_sel_hi:[0,1]
	s_waitcnt vmcnt(0)
	v_pk_mul_f32 v[0:1], v[0:1], v[18:19]
	v_pk_mul_f32 v[10:11], v[4:5], v[10:11] op_sel_hi:[0,1]
	v_pk_mul_f32 v[14:15], v[16:17], v[14:15]
	v_pk_mul_f32 v[2:3], v[2:3], v[10:11]
	v_pk_mul_f32 v[0:1], v[0:1], v[14:15]
	s_nop 0
	v_cvt_pk_bf16_f32 v0, v0, v1
	v_mul_f32_e32 v1, 0xbfb8aa3b, v12
	v_exp_f32_e32 v1, v1
	s_nop 0
	v_add_f32_e32 v1, 1.0, v1
	v_rcp_f32_e32 v14, v1
	v_mul_f32_e32 v1, 0xbfb8aa3b, v13
	v_exp_f32_e32 v1, v1
	s_nop 0
	v_add_f32_e32 v1, 1.0, v1
	v_rcp_f32_e32 v15, v1
	s_nop 0
	v_pk_mul_f32 v[10:11], v[14:15], v[12:13]
	s_nop 0
	v_pk_mul_f32 v[2:3], v[2:3], v[10:11]
	s_nop 0
	v_cvt_pk_bf16_f32 v1, v2, v3
	global_store_dwordx2 v[94:95], v[0:1], off offset:80
	global_load_dwordx2 v[10:11], v[94:95], off offset:96
	global_load_dwordx2 v[12:13], v[8:9], off offset:96
	s_nop 0
	global_load_dwordx4 v[0:3], v[6:7], off offset:192
	s_waitcnt vmcnt(2)
	v_lshlrev_b32_e32 v18, 16, v10
	s_waitcnt vmcnt(1)
	v_lshlrev_b32_e32 v14, 16, v12
	v_mul_f32_e32 v5, 0xbfb8aa3b, v14
	v_exp_f32_e32 v5, v5
	v_and_b32_e32 v15, 0xffff0000, v12
	v_and_b32_e32 v19, 0xffff0000, v10
	v_lshlrev_b32_e32 v12, 16, v13
	v_add_f32_e32 v5, 1.0, v5
	v_rcp_f32_e32 v16, v5
	v_mul_f32_e32 v5, 0xbfb8aa3b, v15
	v_exp_f32_e32 v5, v5
	v_and_b32_e32 v13, 0xffff0000, v13
	v_lshlrev_b32_e32 v10, 16, v11
	v_and_b32_e32 v11, 0xffff0000, v11
	v_add_f32_e32 v5, 1.0, v5
	v_rcp_f32_e32 v17, v5
	v_pk_mul_f32 v[18:19], v[4:5], v[18:19] op_sel_hi:[0,1]
	s_waitcnt vmcnt(0)
	v_pk_mul_f32 v[0:1], v[0:1], v[18:19]
	v_pk_mul_f32 v[10:11], v[4:5], v[10:11] op_sel_hi:[0,1]
	v_pk_mul_f32 v[14:15], v[16:17], v[14:15]
	v_pk_mul_f32 v[2:3], v[2:3], v[10:11]
	v_pk_mul_f32 v[0:1], v[0:1], v[14:15]
	s_nop 0
	v_cvt_pk_bf16_f32 v0, v0, v1
	v_mul_f32_e32 v1, 0xbfb8aa3b, v12
	v_exp_f32_e32 v1, v1
	s_nop 0
	v_add_f32_e32 v1, 1.0, v1
	v_rcp_f32_e32 v14, v1
	v_mul_f32_e32 v1, 0xbfb8aa3b, v13
	v_exp_f32_e32 v1, v1
	s_nop 0
	v_add_f32_e32 v1, 1.0, v1
	v_rcp_f32_e32 v15, v1
	s_nop 0
	v_pk_mul_f32 v[10:11], v[14:15], v[12:13]
	s_nop 0
	v_pk_mul_f32 v[2:3], v[2:3], v[10:11]
	s_nop 0
	v_cvt_pk_bf16_f32 v1, v2, v3
	global_store_dwordx2 v[94:95], v[0:1], off offset:96
	global_load_dwordx2 v[0:1], v[94:95], off offset:112
	s_nop 0
	global_load_dwordx2 v[2:3], v[8:9], off offset:112
	s_nop 0
	global_load_dwordx4 v[6:9], v[6:7], off offset:224
	s_waitcnt vmcnt(2)
	v_lshlrev_b32_e32 v14, 16, v0
	s_waitcnt vmcnt(1)
	v_lshlrev_b32_e32 v10, 16, v2
	v_mul_f32_e32 v5, 0xbfb8aa3b, v10
	v_exp_f32_e32 v5, v5
	v_and_b32_e32 v11, 0xffff0000, v2
	v_lshlrev_b32_e32 v2, 16, v3
	v_and_b32_e32 v15, 0xffff0000, v0
	v_add_f32_e32 v5, 1.0, v5
	v_rcp_f32_e32 v12, v5
	v_mul_f32_e32 v5, 0xbfb8aa3b, v11
	v_exp_f32_e32 v5, v5
	v_and_b32_e32 v3, 0xffff0000, v3
	v_add_f32_e32 v5, 1.0, v5
	v_rcp_f32_e32 v13, v5
	v_pk_mul_f32 v[14:15], v[4:5], v[14:15] op_sel_hi:[0,1]
	v_mul_f32_e32 v5, 0xbfb8aa3b, v2
	v_exp_f32_e32 v5, v5
	s_waitcnt vmcnt(0)
	v_pk_mul_f32 v[6:7], v[6:7], v[14:15]
	v_pk_mul_f32 v[10:11], v[12:13], v[10:11]
	v_add_f32_e32 v5, 1.0, v5
	v_pk_mul_f32 v[6:7], v[6:7], v[10:11]
	v_lshlrev_b32_e32 v10, 16, v1
	v_cvt_pk_bf16_f32 v0, v6, v7
	v_rcp_f32_e32 v6, v5
	v_mul_f32_e32 v5, 0xbfb8aa3b, v3
	v_exp_f32_e32 v5, v5
	v_and_b32_e32 v11, 0xffff0000, v1
	v_add_f32_e32 v5, 1.0, v5
	v_rcp_f32_e32 v7, v5
	v_pk_mul_f32 v[4:5], v[4:5], v[10:11] op_sel_hi:[0,1]
	v_pk_mul_f32 v[4:5], v[8:9], v[4:5]
	v_pk_mul_f32 v[2:3], v[6:7], v[2:3]
	s_nop 0
	v_pk_mul_f32 v[2:3], v[4:5], v[2:3]
	s_nop 0
	v_cvt_pk_bf16_f32 v1, v2, v3
	global_store_dwordx2 v[94:95], v[0:1], off offset:112
	s_branch .LBB0_338

	.amdhsa_kernel _Z6mk_fwd4Args
		.amdhsa_group_segment_fixed_size 16
		.amdhsa_private_segment_fixed_size 0
		.amdhsa_kernarg_size 448
		.amdhsa_user_sgpr_count 2
		.amdhsa_user_sgpr_dispatch_ptr 0
		.amdhsa_user_sgpr_queue_ptr 0
		.amdhsa_user_sgpr_kernarg_segment_ptr 1
		.amdhsa_user_sgpr_dispatch_id 0
		.amdhsa_user_sgpr_kernarg_preload_length 0
		.amdhsa_user_sgpr_kernarg_preload_offset 0
		.amdhsa_user_sgpr_private_segment_size 0
		.amdhsa_uses_dynamic_stack 0
		.amdhsa_enable_private_segment 0
		.amdhsa_system_sgpr_workgroup_id_x 1
		.amdhsa_system_sgpr_workgroup_id_y 0
		.amdhsa_system_sgpr_workgroup_id_z 0
		.amdhsa_system_sgpr_workgroup_info 0
		.amdhsa_system_vgpr_workitem_id 2
		.amdhsa_next_free_vgpr 256
		.amdhsa_next_free_sgpr 102
		.amdhsa_accum_offset 256
		.amdhsa_reserve_vcc 1
		.amdhsa_float_round_mode_32 0
		.amdhsa_float_round_mode_16_64 0
		.amdhsa_float_denorm_mode_32 3
		.amdhsa_float_denorm_mode_16_64 3
		.amdhsa_dx10_clamp 1
		.amdhsa_ieee_mode 1
		.amdhsa_fp16_overflow 0
		.amdhsa_tg_split 0
		.amdhsa_exception_fp_ieee_invalid_op 0
		.amdhsa_exception_fp_denorm_src 0
		.amdhsa_exception_fp_ieee_div_zero 0
		.amdhsa_exception_fp_ieee_overflow 0
		.amdhsa_exception_fp_ieee_underflow 0
		.amdhsa_exception_fp_ieee_inexact 0
		.amdhsa_exception_int_div_zero 0
	.end_amdhsa_kernel

amdhsa.kernels:
  - .agpr_count:     0
    .args:
      - .offset:         0
        .size:           192
        .value_kind:     by_value
      - .offset:         192
        .size:           4
        .value_kind:     hidden_block_count_x
      - .offset:         196
        .size:           4
        .value_kind:     hidden_block_count_y
      - .offset:         200
        .size:           4
        .value_kind:     hidden_block_count_z
      - .offset:         204
        .size:           2
        .value_kind:     hidden_group_size_x
      - .offset:         206
        .size:           2
        .value_kind:     hidden_group_size_y
      - .offset:         208
        .size:           2
        .value_kind:     hidden_group_size_z
      - .offset:         210
        .size:           2
        .value_kind:     hidden_remainder_x
      - .offset:         212
        .size:           2
        .value_kind:     hidden_remainder_y
      - .offset:         214
        .size:           2
        .value_kind:     hidden_remainder_z
      - .offset:         232
        .size:           8
        .value_kind:     hidden_global_offset_x
      - .offset:         240
        .size:           8
        .value_kind:     hidden_global_offset_y
      - .offset:         248
        .size:           8
        .value_kind:     hidden_global_offset_z
      - .offset:         256
        .size:           2
        .value_kind:     hidden_grid_dims
      - .offset:         280
        .size:           8
        .value_kind:     hidden_multigrid_sync_arg
      - .offset:         312
        .size:           4
        .value_kind:     hidden_dynamic_lds_size
    .group_segment_fixed_size: 16
    .kernarg_segment_align: 8
    .kernarg_segment_size: 448
    .language:       OpenCL C
    .language_version:
      - 2
      - 0
    .max_flat_workgroup_size: 512
    .name:           _Z6mk_fwd4Args
    .private_segment_fixed_size: 0
    .sgpr_count:     108
    .sgpr_spill_count: 315
    .symbol:         _Z6mk_fwd4Args.kd
    .uniform_work_group_size: 1
    .uses_dynamic_stack: false
    .vgpr_count:     256
    .vgpr_spill_count: 0
    .wavefront_size: 64
